# ssd_sample: all 12 heads' recurrent states loaded up front into per-head register sets (straight-line, head 11 recycles head 0's registers) so state stores never sit in front of state loads in the in-
# baseline (speedup 1.0000x reference)
.LBB0_683:
	s_or_b64 exec, exec, s[8:9]
	v_ashrrev_i32_e32 v16, 3, v74
	s_mul_i32 s8, s89, 12
	s_ashr_i32 s9, s8, 31
	v_ashrrev_i32_e32 v17, 31, v16
	s_lshl_b64 s[0:1], s[8:9], 13
	v_lshlrev_b64 v[0:1], 7, v[16:17]
	v_and_b32_e32 v18, 7, v74
	v_lshl_add_u64 v[0:1], v[0:1], 0, s[0:1]
	v_lshl_or_b32 v0, v18, 4, v0
	v_lshl_add_u64 v[0:1], v[0:1], 2, s[50:51]
	s_mov_b64 s[0:1], 0x8000
	v_lshl_add_u64 v[12:13], v[0:1], 0, s[0:1]
	s_mov_b32 s0, 0x8000
	s_waitcnt lgkmcnt(0)
	s_barrier
	global_load_dwordx4 v[32:35], v[0:1], off offset:48 nt
	global_load_dwordx4 v[36:39], v[0:1], off offset:32 nt
	global_load_dwordx4 v[40:43], v[0:1], off offset:16 nt
	global_load_dwordx4 v[44:47], v[0:1], off nt
	v_add_co_u32_e32 v0, vcc, s0, v0
	v_and_b32_e32 v20, 64, v157
	s_nop 0
	v_addc_co_u32_e32 v1, vcc, 0, v1, vcc
	global_load_dwordx4 v[0:3], v[0:1], off nt
	s_nop 0
	global_load_dwordx4 v[4:7], v[12:13], off offset:48 nt
	global_load_dwordx4 v[8:11], v[12:13], off offset:32 nt
	s_nop 0
	global_load_dwordx4 v[12:15], v[12:13], off offset:16 nt
	v_xor_b32_e32 v19, 1, v157
	v_add_u32_e32 v60, 64, v20
	v_cmp_lt_i32_e32 vcc, v19, v60
	v_lshl_add_u32 v64, v16, 2, 0
	s_lshl_b64 s[2:3], s[8:9], 15
	v_cndmask_b32_e32 v19, v157, v19, vcc
	v_lshlrev_b32_e32 v61, 2, v19
	v_xor_b32_e32 v19, 2, v157
	v_cmp_lt_i32_e32 vcc, v19, v60
	v_lshlrev_b64 v[16:17], 9, v[16:17]
	v_cmp_eq_u32_e64 s[6:7], 0, v18
	v_cndmask_b32_e32 v19, v157, v19, vcc
	v_lshlrev_b32_e32 v62, 2, v19
	v_xor_b32_e32 v19, 4, v157
	v_cmp_lt_i32_e32 vcc, v19, v60
	v_lshlrev_b32_e32 v18, 6, v18
	v_lshl_add_u64 v[16:17], s[2:3], 0, v[16:17]
	v_cndmask_b32_e32 v19, v157, v19, vcc
	v_or_b32_e32 v16, v16, v18
	v_lshlrev_b32_e32 v63, 2, v19
	v_add_u32_e32 v65, 0, v18
	v_lshl_add_u64 v[48:49], s[50:51], 0, v[16:17]
	v_lshl_add_u64 v[50:51], s[56:57], 0, v[16:17]
	s_mov_b32 s0, 0
	s_mov_b64 s[8:9], 0
	s_mov_b64 s[10:11], s[46:47]
	s_mov_b64 s[12:13], s[44:45]
	s_mov_b32 s1, s88
	s_mov_b64 s[2:3], 0x10000
	v_lshl_add_u64 v[90:91], v[48:49], 0, s[2:3]
	global_load_dwordx4 v[16:19], v[90:91], off offset:48 nt
	global_load_dwordx4 v[20:23], v[90:91], off offset:32 nt
	global_load_dwordx4 v[28:31], v[90:91], off offset:16 nt
	global_load_dwordx4 v[24:27], v[90:91], off nt
	s_mov_b64 s[2:3], 0x18000
	v_lshl_add_u64 v[90:91], v[48:49], 0, s[2:3]
	global_load_dwordx4 v[92:95], v[90:91], off offset:48 nt
	global_load_dwordx4 v[96:99], v[90:91], off offset:32 nt
	global_load_dwordx4 v[100:103], v[90:91], off offset:16 nt
	global_load_dwordx4 v[104:107], v[90:91], off nt
	s_mov_b64 s[2:3], 0x20000
	v_lshl_add_u64 v[90:91], v[48:49], 0, s[2:3]
	global_load_dwordx4 v[108:111], v[90:91], off offset:48 nt
	global_load_dwordx4 v[112:115], v[90:91], off offset:32 nt
	global_load_dwordx4 v[116:119], v[90:91], off offset:16 nt
	global_load_dwordx4 v[120:123], v[90:91], off nt
	s_mov_b64 s[2:3], 0x28000
	v_lshl_add_u64 v[90:91], v[48:49], 0, s[2:3]
	global_load_dwordx4 v[124:127], v[90:91], off offset:48 nt
	global_load_dwordx4 v[128:131], v[90:91], off offset:32 nt
	global_load_dwordx4 v[132:135], v[90:91], off offset:16 nt
	global_load_dwordx4 v[136:139], v[90:91], off nt
	s_mov_b64 s[2:3], 0x30000
	v_lshl_add_u64 v[90:91], v[48:49], 0, s[2:3]
	global_load_dwordx4 v[168:171], v[90:91], off offset:48 nt
	global_load_dwordx4 v[172:175], v[90:91], off offset:32 nt
	global_load_dwordx4 v[176:179], v[90:91], off offset:16 nt
	global_load_dwordx4 v[180:183], v[90:91], off nt
	s_mov_b64 s[2:3], 0x38000
	v_lshl_add_u64 v[90:91], v[48:49], 0, s[2:3]
	global_load_dwordx4 v[196:199], v[90:91], off offset:48 nt
	global_load_dwordx4 v[200:203], v[90:91], off offset:32 nt
	global_load_dwordx4 v[204:207], v[90:91], off offset:16 nt
	global_load_dwordx4 v[208:211], v[90:91], off nt
	s_mov_b64 s[2:3], 0x40000
	v_lshl_add_u64 v[90:91], v[48:49], 0, s[2:3]
	global_load_dwordx4 v[212:215], v[90:91], off offset:48 nt
	global_load_dwordx4 v[216:219], v[90:91], off offset:32 nt
	global_load_dwordx4 v[220:223], v[90:91], off offset:16 nt
	global_load_dwordx4 v[224:227], v[90:91], off nt
	s_mov_b64 s[2:3], 0x48000
	v_lshl_add_u64 v[90:91], v[48:49], 0, s[2:3]
	global_load_dwordx4 v[228:231], v[90:91], off offset:48 nt
	global_load_dwordx4 v[232:235], v[90:91], off offset:32 nt
	global_load_dwordx4 v[236:239], v[90:91], off offset:16 nt
	global_load_dwordx4 v[240:243], v[90:91], off nt
	s_mov_b64 s[2:3], 0x50000
	v_lshl_add_u64 v[90:91], v[48:49], 0, s[2:3]
	global_load_dwordx4 v[140:143], v[90:91], off offset:48 nt
	global_load_dwordx4 v[144:147], v[90:91], off offset:32 nt
	global_load_dwordx4 v[148:151], v[90:91], off offset:16 nt
	global_load_dwordx4 v[184:187], v[90:91], off nt
.Lssd12_0:
	s_load_dword s16, s[12:13], 0x0
	s_load_dword s17, s[10:11], 0x0
	s_mul_i32 s2, s0, 0xab
	s_and_b32 s2, s2, 0xfe00
	v_add_u32_e32 v67, s2, v65
	s_waitcnt vmcnt(40)
	s_waitcnt lgkmcnt(0)
	v_mov_b32_e32 v52, s16
	v_mov_b32_e32 v66, s17
	v_mul_f32_e32 v52, 0x3fb8aa3b, v52
	v_exp_f32_e32 v68, v52
	v_mov_b32_e32 v52, s1
	ds_read_b32 v53, v52
	s_waitcnt lgkmcnt(0)
	v_mul_f32_e64 v52, v53, -v68
	v_mul_f32_e32 v52, 0x3fb8aa3b, v52
	v_exp_f32_e32 v58, v52
	ds_read_b32 v52, v64
	ds_read_b128 v[54:57], v67 offset:3072
	ds_read_b128 v[74:77], v67 offset:3088
	ds_read_b128 v[78:81], v67 offset:3104
	ds_read_b128 v[82:85], v67 offset:3120
	v_pk_mul_f32 v[46:47], v[46:47], v[58:59] op_sel_hi:[1,0]
	v_pk_mul_f32 v[86:87], v[44:45], v[58:59] op_sel_hi:[1,0]
	s_waitcnt lgkmcnt(4)
	v_mul_f32_e32 v70, v53, v52
	s_waitcnt lgkmcnt(3)
	v_pk_fma_f32 v[44:45], v[56:57], v[70:71], v[46:47] op_sel_hi:[1,0,1]
	v_pk_fma_f32 v[46:47], v[54:55], v[70:71], v[86:87] op_sel_hi:[1,0,1]
	ds_read_b128 v[54:57], v67 offset:5120
	v_pk_mul_f32 v[42:43], v[42:43], v[58:59] op_sel_hi:[1,0]
	s_waitcnt lgkmcnt(0)
	v_mul_f32_e32 v53, v55, v47
	v_fmac_f32_e32 v53, v54, v46
	v_mul_f32_e32 v54, v57, v45
	v_fmac_f32_e32 v54, v56, v44
	v_add_f32_e32 v53, v53, v54
	v_pk_mul_f32 v[54:55], v[40:41], v[58:59] op_sel_hi:[1,0]
	v_pk_fma_f32 v[40:41], v[70:71], v[76:77], v[42:43] op_sel_hi:[0,1,1]
	v_pk_fma_f32 v[42:43], v[70:71], v[74:75], v[54:55] op_sel_hi:[0,1,1]
	ds_read_b128 v[54:57], v67 offset:5136
	v_add_f32_e32 v53, 0, v53
	s_waitcnt lgkmcnt(0)
	v_mul_f32_e32 v55, v55, v43
	v_fmac_f32_e32 v55, v54, v42
	v_mul_f32_e32 v54, v57, v41
	v_fmac_f32_e32 v54, v56, v40
	v_add_f32_e32 v54, v55, v54
	v_add_f32_e32 v53, v54, v53
	v_pk_mul_f32 v[54:55], v[70:71], v[78:79] op_sel_hi:[0,1]
	v_pk_mul_f32 v[56:57], v[70:71], v[80:81] op_sel_hi:[0,1]
	v_pk_fma_f32 v[38:39], v[38:39], v[58:59], v[56:57] op_sel_hi:[1,0,1]
	v_pk_fma_f32 v[36:37], v[36:37], v[58:59], v[54:55] op_sel_hi:[1,0,1]
	ds_read_b128 v[54:57], v67 offset:5152
	s_waitcnt lgkmcnt(0)
	v_mul_f32_e32 v55, v55, v37
	v_fmac_f32_e32 v55, v54, v36
	v_mul_f32_e32 v54, v57, v39
	v_fmac_f32_e32 v54, v56, v38
	v_add_f32_e32 v54, v55, v54
	v_add_f32_e32 v53, v54, v53
	v_pk_mul_f32 v[54:55], v[70:71], v[82:83] op_sel_hi:[0,1]
	v_pk_mul_f32 v[56:57], v[70:71], v[84:85] op_sel_hi:[0,1]
	v_pk_fma_f32 v[34:35], v[34:35], v[58:59], v[56:57] op_sel_hi:[1,0,1]
	v_pk_fma_f32 v[32:33], v[32:33], v[58:59], v[54:55] op_sel_hi:[1,0,1]
	ds_read_b128 v[54:57], v67 offset:5168
	s_waitcnt lgkmcnt(0)
	v_mul_f32_e32 v55, v55, v33
	v_fmac_f32_e32 v55, v54, v32
	v_mul_f32_e32 v54, v57, v35
	v_fmac_f32_e32 v54, v56, v34
	v_add_f32_e32 v54, v55, v54
	v_add_f32_e32 v53, v53, v54
	ds_bpermute_b32 v54, v61, v53
	s_waitcnt lgkmcnt(0)
	v_add_f32_e32 v53, v53, v54
	ds_bpermute_b32 v54, v62, v53
	s_waitcnt lgkmcnt(0)
	v_add_f32_e32 v53, v53, v54
	ds_bpermute_b32 v54, v63, v53
	s_and_saveexec_b64 s[14:15], s[6:7]
	s_cbranch_execz .Lssd12_0_689
	ds_read_b32 v55, v64 offset:41216
	s_waitcnt lgkmcnt(1)
	v_add_f32_e32 v53, v53, v54
	v_fmac_f32_e32 v53, v66, v52
	s_waitcnt lgkmcnt(0)
	v_mul_f32_e32 v56, 0xbfb8aa3b, v55
	v_exp_f32_e32 v56, v56
	s_nop 0
	v_add_f32_e32 v54, 1.0, v56
	v_div_scale_f32 v56, s[2:3], v54, v54, v55
	v_rcp_f32_e32 v57, v56
	v_div_scale_f32 v52, vcc, v55, v54, v55
	v_fma_f32 v58, -v56, v57, 1.0
	v_fmac_f32_e32 v57, v58, v57
	v_mul_f32_e32 v58, v52, v57
	v_fma_f32 v59, -v56, v58, v52
	v_fmac_f32_e32 v58, v59, v57
	v_fma_f32 v52, -v56, v58, v52
	v_div_fmas_f32 v52, v52, v57, v58
	v_div_fixup_f32 v52, v52, v54, v55
	v_mul_f32_e32 v52, v53, v52
	ds_write_b32 v64, v52 offset:28928

.Lssd12_0_tail:
	s_or_b64 exec, exec, s[14:15]
	s_add_i32 s0, s0, 1
	s_add_i32 s1, s1, 4
	s_waitcnt lgkmcnt(0)
	v_lshl_add_u64 v[52:53], v[50:51], 0, s[8:9]
	s_add_u32 s8, s8, 0x8000
	s_addc_u32 s9, s9, 0
	v_add_co_u32_e32 v52, vcc, 0x2fb35000, v52
	s_add_u32 s12, s12, 4
	s_nop 0
	v_addc_co_u32_e32 v53, vcc, 0, v53, vcc
	s_addc_u32 s13, s13, 0
	global_store_dwordx4 v[52:53], v[32:35], off
	global_store_dwordx4 v[52:53], v[36:39], off offset:16
	global_store_dwordx4 v[52:53], v[40:43], off offset:32
	global_store_dwordx4 v[52:53], v[44:47], off offset:48
	s_add_u32 s10, s10, 4
	s_addc_u32 s11, s11, 0
	v_add_u32_e32 v64, 0x100, v64
	s_mov_b64 s[2:3], 0x58000
	v_lshl_add_u64 v[90:91], v[48:49], 0, s[2:3]
	global_load_dwordx4 v[32:35], v[90:91], off offset:48 nt
	global_load_dwordx4 v[36:39], v[90:91], off offset:32 nt
	global_load_dwordx4 v[40:43], v[90:91], off offset:16 nt
	global_load_dwordx4 v[44:47], v[90:91], off nt
.Lssd12_1:
	s_load_dword s16, s[12:13], 0x0
	s_load_dword s17, s[10:11], 0x0
	s_mul_i32 s2, s0, 0xab
	s_and_b32 s2, s2, 0xfe00
	v_add_u32_e32 v67, s2, v65
	s_waitcnt vmcnt(44)
	s_waitcnt lgkmcnt(0)
	v_mov_b32_e32 v52, s16
	v_mov_b32_e32 v66, s17
	v_mul_f32_e32 v52, 0x3fb8aa3b, v52
	v_exp_f32_e32 v68, v52
	v_mov_b32_e32 v52, s1
	ds_read_b32 v53, v52
	s_waitcnt lgkmcnt(0)
	v_mul_f32_e64 v52, v53, -v68
	v_mul_f32_e32 v52, 0x3fb8aa3b, v52
	v_exp_f32_e32 v58, v52
	ds_read_b32 v52, v64
	ds_read_b128 v[54:57], v67 offset:3072
	ds_read_b128 v[74:77], v67 offset:3088
	ds_read_b128 v[78:81], v67 offset:3104
	ds_read_b128 v[82:85], v67 offset:3120
	v_pk_mul_f32 v[2:3], v[2:3], v[58:59] op_sel_hi:[1,0]
	v_pk_mul_f32 v[86:87], v[0:1], v[58:59] op_sel_hi:[1,0]
	s_waitcnt lgkmcnt(4)
	v_mul_f32_e32 v70, v53, v52
	s_waitcnt lgkmcnt(3)
	v_pk_fma_f32 v[0:1], v[56:57], v[70:71], v[2:3] op_sel_hi:[1,0,1]
	v_pk_fma_f32 v[2:3], v[54:55], v[70:71], v[86:87] op_sel_hi:[1,0,1]
	ds_read_b128 v[54:57], v67 offset:5120
	v_pk_mul_f32 v[14:15], v[14:15], v[58:59] op_sel_hi:[1,0]
	s_waitcnt lgkmcnt(0)
	v_mul_f32_e32 v53, v55, v3
	v_fmac_f32_e32 v53, v54, v2
	v_mul_f32_e32 v54, v57, v1
	v_fmac_f32_e32 v54, v56, v0
	v_add_f32_e32 v53, v53, v54
	v_pk_mul_f32 v[54:55], v[12:13], v[58:59] op_sel_hi:[1,0]
	v_pk_fma_f32 v[12:13], v[70:71], v[76:77], v[14:15] op_sel_hi:[0,1,1]
	v_pk_fma_f32 v[14:15], v[70:71], v[74:75], v[54:55] op_sel_hi:[0,1,1]
	ds_read_b128 v[54:57], v67 offset:5136
	v_add_f32_e32 v53, 0, v53
	s_waitcnt lgkmcnt(0)
	v_mul_f32_e32 v55, v55, v15
	v_fmac_f32_e32 v55, v54, v14
	v_mul_f32_e32 v54, v57, v13
	v_fmac_f32_e32 v54, v56, v12
	v_add_f32_e32 v54, v55, v54
	v_add_f32_e32 v53, v54, v53
	v_pk_mul_f32 v[54:55], v[70:71], v[78:79] op_sel_hi:[0,1]
	v_pk_mul_f32 v[56:57], v[70:71], v[80:81] op_sel_hi:[0,1]
	v_pk_fma_f32 v[10:11], v[10:11], v[58:59], v[56:57] op_sel_hi:[1,0,1]
	v_pk_fma_f32 v[8:9], v[8:9], v[58:59], v[54:55] op_sel_hi:[1,0,1]
	ds_read_b128 v[54:57], v67 offset:5152
	s_waitcnt lgkmcnt(0)
	v_mul_f32_e32 v55, v55, v9
	v_fmac_f32_e32 v55, v54, v8
	v_mul_f32_e32 v54, v57, v11
	v_fmac_f32_e32 v54, v56, v10
	v_add_f32_e32 v54, v55, v54
	v_add_f32_e32 v53, v54, v53
	v_pk_mul_f32 v[54:55], v[70:71], v[82:83] op_sel_hi:[0,1]
	v_pk_mul_f32 v[56:57], v[70:71], v[84:85] op_sel_hi:[0,1]
	v_pk_fma_f32 v[6:7], v[6:7], v[58:59], v[56:57] op_sel_hi:[1,0,1]
	v_pk_fma_f32 v[4:5], v[4:5], v[58:59], v[54:55] op_sel_hi:[1,0,1]
	ds_read_b128 v[54:57], v67 offset:5168
	s_waitcnt lgkmcnt(0)
	v_mul_f32_e32 v55, v55, v5
	v_fmac_f32_e32 v55, v54, v4
	v_mul_f32_e32 v54, v57, v7
	v_fmac_f32_e32 v54, v56, v6
	v_add_f32_e32 v54, v55, v54
	v_add_f32_e32 v53, v53, v54
	ds_bpermute_b32 v54, v61, v53
	s_waitcnt lgkmcnt(0)
	v_add_f32_e32 v53, v53, v54
	ds_bpermute_b32 v54, v62, v53
	s_waitcnt lgkmcnt(0)
	v_add_f32_e32 v53, v53, v54
	ds_bpermute_b32 v54, v63, v53
	s_and_saveexec_b64 s[14:15], s[6:7]
	s_cbranch_execz .Lssd12_1_689
	ds_read_b32 v55, v64 offset:41216
	s_waitcnt lgkmcnt(1)
	v_add_f32_e32 v53, v53, v54
	v_fmac_f32_e32 v53, v66, v52
	s_waitcnt lgkmcnt(0)
	v_mul_f32_e32 v56, 0xbfb8aa3b, v55
	v_exp_f32_e32 v56, v56
	s_nop 0
	v_add_f32_e32 v54, 1.0, v56
	v_div_scale_f32 v56, s[2:3], v54, v54, v55
	v_rcp_f32_e32 v57, v56
	v_div_scale_f32 v52, vcc, v55, v54, v55
	v_fma_f32 v58, -v56, v57, 1.0
	v_fmac_f32_e32 v57, v58, v57
	v_mul_f32_e32 v58, v52, v57
	v_fma_f32 v59, -v56, v58, v52
	v_fmac_f32_e32 v58, v59, v57
	v_fma_f32 v52, -v56, v58, v52
	v_div_fmas_f32 v52, v52, v57, v58
	v_div_fixup_f32 v52, v52, v54, v55
	v_mul_f32_e32 v52, v53, v52
	ds_write_b32 v64, v52 offset:28928

.Lssd12_2:
	s_load_dword s16, s[12:13], 0x0
	s_load_dword s17, s[10:11], 0x0
	s_mul_i32 s2, s0, 0xab
	s_and_b32 s2, s2, 0xfe00
	v_add_u32_e32 v67, s2, v65
	s_waitcnt vmcnt(44)
	s_waitcnt lgkmcnt(0)
	v_mov_b32_e32 v52, s16
	v_mov_b32_e32 v66, s17
	v_mul_f32_e32 v52, 0x3fb8aa3b, v52
	v_exp_f32_e32 v68, v52
	v_mov_b32_e32 v52, s1
	ds_read_b32 v53, v52
	s_waitcnt lgkmcnt(0)
	v_mul_f32_e64 v52, v53, -v68
	v_mul_f32_e32 v52, 0x3fb8aa3b, v52
	v_exp_f32_e32 v58, v52
	ds_read_b32 v52, v64
	ds_read_b128 v[54:57], v67 offset:3072
	ds_read_b128 v[74:77], v67 offset:3088
	ds_read_b128 v[78:81], v67 offset:3104
	ds_read_b128 v[82:85], v67 offset:3120
	v_pk_mul_f32 v[26:27], v[26:27], v[58:59] op_sel_hi:[1,0]
	v_pk_mul_f32 v[86:87], v[24:25], v[58:59] op_sel_hi:[1,0]
	s_waitcnt lgkmcnt(4)
	v_mul_f32_e32 v70, v53, v52
	s_waitcnt lgkmcnt(3)
	v_pk_fma_f32 v[24:25], v[56:57], v[70:71], v[26:27] op_sel_hi:[1,0,1]
	v_pk_fma_f32 v[26:27], v[54:55], v[70:71], v[86:87] op_sel_hi:[1,0,1]
	ds_read_b128 v[54:57], v67 offset:5120
	v_pk_mul_f32 v[30:31], v[30:31], v[58:59] op_sel_hi:[1,0]
	s_waitcnt lgkmcnt(0)
	v_mul_f32_e32 v53, v55, v27
	v_fmac_f32_e32 v53, v54, v26
	v_mul_f32_e32 v54, v57, v25
	v_fmac_f32_e32 v54, v56, v24
	v_add_f32_e32 v53, v53, v54
	v_pk_mul_f32 v[54:55], v[28:29], v[58:59] op_sel_hi:[1,0]
	v_pk_fma_f32 v[28:29], v[70:71], v[76:77], v[30:31] op_sel_hi:[0,1,1]
	v_pk_fma_f32 v[30:31], v[70:71], v[74:75], v[54:55] op_sel_hi:[0,1,1]
	ds_read_b128 v[54:57], v67 offset:5136
	v_add_f32_e32 v53, 0, v53
	s_waitcnt lgkmcnt(0)
	v_mul_f32_e32 v55, v55, v31
	v_fmac_f32_e32 v55, v54, v30
	v_mul_f32_e32 v54, v57, v29
	v_fmac_f32_e32 v54, v56, v28
	v_add_f32_e32 v54, v55, v54
	v_add_f32_e32 v53, v54, v53
	v_pk_mul_f32 v[54:55], v[70:71], v[78:79] op_sel_hi:[0,1]
	v_pk_mul_f32 v[56:57], v[70:71], v[80:81] op_sel_hi:[0,1]
	v_pk_fma_f32 v[22:23], v[22:23], v[58:59], v[56:57] op_sel_hi:[1,0,1]
	v_pk_fma_f32 v[20:21], v[20:21], v[58:59], v[54:55] op_sel_hi:[1,0,1]
	ds_read_b128 v[54:57], v67 offset:5152
	s_waitcnt lgkmcnt(0)
	v_mul_f32_e32 v55, v55, v21
	v_fmac_f32_e32 v55, v54, v20
	v_mul_f32_e32 v54, v57, v23
	v_fmac_f32_e32 v54, v56, v22
	v_add_f32_e32 v54, v55, v54
	v_add_f32_e32 v53, v54, v53
	v_pk_mul_f32 v[54:55], v[70:71], v[82:83] op_sel_hi:[0,1]
	v_pk_mul_f32 v[56:57], v[70:71], v[84:85] op_sel_hi:[0,1]
	v_pk_fma_f32 v[18:19], v[18:19], v[58:59], v[56:57] op_sel_hi:[1,0,1]
	v_pk_fma_f32 v[16:17], v[16:17], v[58:59], v[54:55] op_sel_hi:[1,0,1]
	ds_read_b128 v[54:57], v67 offset:5168
	s_waitcnt lgkmcnt(0)
	v_mul_f32_e32 v55, v55, v17
	v_fmac_f32_e32 v55, v54, v16
	v_mul_f32_e32 v54, v57, v19
	v_fmac_f32_e32 v54, v56, v18
	v_add_f32_e32 v54, v55, v54
	v_add_f32_e32 v53, v53, v54
	ds_bpermute_b32 v54, v61, v53
	s_waitcnt lgkmcnt(0)
	v_add_f32_e32 v53, v53, v54
	ds_bpermute_b32 v54, v62, v53
	s_waitcnt lgkmcnt(0)
	v_add_f32_e32 v53, v53, v54
	ds_bpermute_b32 v54, v63, v53
	s_and_saveexec_b64 s[14:15], s[6:7]
	s_cbranch_execz .Lssd12_2_689
	ds_read_b32 v55, v64 offset:41216
	s_waitcnt lgkmcnt(1)
	v_add_f32_e32 v53, v53, v54
	v_fmac_f32_e32 v53, v66, v52
	s_waitcnt lgkmcnt(0)
	v_mul_f32_e32 v56, 0xbfb8aa3b, v55
	v_exp_f32_e32 v56, v56
	s_nop 0
	v_add_f32_e32 v54, 1.0, v56
	v_div_scale_f32 v56, s[2:3], v54, v54, v55
	v_rcp_f32_e32 v57, v56
	v_div_scale_f32 v52, vcc, v55, v54, v55
	v_fma_f32 v58, -v56, v57, 1.0
	v_fmac_f32_e32 v57, v58, v57
	v_mul_f32_e32 v58, v52, v57
	v_fma_f32 v59, -v56, v58, v52
	v_fmac_f32_e32 v58, v59, v57
	v_fma_f32 v52, -v56, v58, v52
	v_div_fmas_f32 v52, v52, v57, v58
	v_div_fixup_f32 v52, v52, v54, v55
	v_mul_f32_e32 v52, v53, v52
	ds_write_b32 v64, v52 offset:28928

.Lssd12_3:
	s_load_dword s16, s[12:13], 0x0
	s_load_dword s17, s[10:11], 0x0
	s_mul_i32 s2, s0, 0xab
	s_and_b32 s2, s2, 0xfe00
	v_add_u32_e32 v67, s2, v65
	s_waitcnt vmcnt(44)
	s_waitcnt lgkmcnt(0)
	v_mov_b32_e32 v52, s16
	v_mov_b32_e32 v66, s17
	v_mul_f32_e32 v52, 0x3fb8aa3b, v52
	v_exp_f32_e32 v68, v52
	v_mov_b32_e32 v52, s1
	ds_read_b32 v53, v52
	s_waitcnt lgkmcnt(0)
	v_mul_f32_e64 v52, v53, -v68
	v_mul_f32_e32 v52, 0x3fb8aa3b, v52
	v_exp_f32_e32 v58, v52
	ds_read_b32 v52, v64
	ds_read_b128 v[54:57], v67 offset:3072
	ds_read_b128 v[74:77], v67 offset:3088
	ds_read_b128 v[78:81], v67 offset:3104
	ds_read_b128 v[82:85], v67 offset:3120
	v_pk_mul_f32 v[106:107], v[106:107], v[58:59] op_sel_hi:[1,0]
	v_pk_mul_f32 v[86:87], v[104:105], v[58:59] op_sel_hi:[1,0]
	s_waitcnt lgkmcnt(4)
	v_mul_f32_e32 v70, v53, v52
	s_waitcnt lgkmcnt(3)
	v_pk_fma_f32 v[104:105], v[56:57], v[70:71], v[106:107] op_sel_hi:[1,0,1]
	v_pk_fma_f32 v[106:107], v[54:55], v[70:71], v[86:87] op_sel_hi:[1,0,1]
	ds_read_b128 v[54:57], v67 offset:5120
	v_pk_mul_f32 v[102:103], v[102:103], v[58:59] op_sel_hi:[1,0]
	s_waitcnt lgkmcnt(0)
	v_mul_f32_e32 v53, v55, v107
	v_fmac_f32_e32 v53, v54, v106
	v_mul_f32_e32 v54, v57, v105
	v_fmac_f32_e32 v54, v56, v104
	v_add_f32_e32 v53, v53, v54
	v_pk_mul_f32 v[54:55], v[100:101], v[58:59] op_sel_hi:[1,0]
	v_pk_fma_f32 v[100:101], v[70:71], v[76:77], v[102:103] op_sel_hi:[0,1,1]
	v_pk_fma_f32 v[102:103], v[70:71], v[74:75], v[54:55] op_sel_hi:[0,1,1]
	ds_read_b128 v[54:57], v67 offset:5136
	v_add_f32_e32 v53, 0, v53
	s_waitcnt lgkmcnt(0)
	v_mul_f32_e32 v55, v55, v103
	v_fmac_f32_e32 v55, v54, v102
	v_mul_f32_e32 v54, v57, v101
	v_fmac_f32_e32 v54, v56, v100
	v_add_f32_e32 v54, v55, v54
	v_add_f32_e32 v53, v54, v53
	v_pk_mul_f32 v[54:55], v[70:71], v[78:79] op_sel_hi:[0,1]
	v_pk_mul_f32 v[56:57], v[70:71], v[80:81] op_sel_hi:[0,1]
	v_pk_fma_f32 v[98:99], v[98:99], v[58:59], v[56:57] op_sel_hi:[1,0,1]
	v_pk_fma_f32 v[96:97], v[96:97], v[58:59], v[54:55] op_sel_hi:[1,0,1]
	ds_read_b128 v[54:57], v67 offset:5152
	s_waitcnt lgkmcnt(0)
	v_mul_f32_e32 v55, v55, v97
	v_fmac_f32_e32 v55, v54, v96
	v_mul_f32_e32 v54, v57, v99
	v_fmac_f32_e32 v54, v56, v98
	v_add_f32_e32 v54, v55, v54
	v_add_f32_e32 v53, v54, v53
	v_pk_mul_f32 v[54:55], v[70:71], v[82:83] op_sel_hi:[0,1]
	v_pk_mul_f32 v[56:57], v[70:71], v[84:85] op_sel_hi:[0,1]
	v_pk_fma_f32 v[94:95], v[94:95], v[58:59], v[56:57] op_sel_hi:[1,0,1]
	v_pk_fma_f32 v[92:93], v[92:93], v[58:59], v[54:55] op_sel_hi:[1,0,1]
	ds_read_b128 v[54:57], v67 offset:5168
	s_waitcnt lgkmcnt(0)
	v_mul_f32_e32 v55, v55, v93
	v_fmac_f32_e32 v55, v54, v92
	v_mul_f32_e32 v54, v57, v95
	v_fmac_f32_e32 v54, v56, v94
	v_add_f32_e32 v54, v55, v54
	v_add_f32_e32 v53, v53, v54
	ds_bpermute_b32 v54, v61, v53
	s_waitcnt lgkmcnt(0)
	v_add_f32_e32 v53, v53, v54
	ds_bpermute_b32 v54, v62, v53
	s_waitcnt lgkmcnt(0)
	v_add_f32_e32 v53, v53, v54
	ds_bpermute_b32 v54, v63, v53
	s_and_saveexec_b64 s[14:15], s[6:7]
	s_cbranch_execz .Lssd12_3_689
	ds_read_b32 v55, v64 offset:41216
	s_waitcnt lgkmcnt(1)
	v_add_f32_e32 v53, v53, v54
	v_fmac_f32_e32 v53, v66, v52
	s_waitcnt lgkmcnt(0)
	v_mul_f32_e32 v56, 0xbfb8aa3b, v55
	v_exp_f32_e32 v56, v56
	s_nop 0
	v_add_f32_e32 v54, 1.0, v56
	v_div_scale_f32 v56, s[2:3], v54, v54, v55
	v_rcp_f32_e32 v57, v56
	v_div_scale_f32 v52, vcc, v55, v54, v55
	v_fma_f32 v58, -v56, v57, 1.0
	v_fmac_f32_e32 v57, v58, v57
	v_mul_f32_e32 v58, v52, v57
	v_fma_f32 v59, -v56, v58, v52
	v_fmac_f32_e32 v58, v59, v57
	v_fma_f32 v52, -v56, v58, v52
	v_div_fmas_f32 v52, v52, v57, v58
	v_div_fixup_f32 v52, v52, v54, v55
	v_mul_f32_e32 v52, v53, v52
	ds_write_b32 v64, v52 offset:28928
.Lssd12_3_689:
	s_or_b64 exec, exec, s[14:15]
	v_mov_b32_e32 v52, s1
	ds_read_b32 v53, v52 offset:48
	ds_read_b32 v52, v64 offset:7168
	s_waitcnt lgkmcnt(1)
	v_mul_f32_e32 v54, v53, v68
	v_mul_f32_e32 v54, 0xbfb8aa3b, v54
	v_exp_f32_e32 v58, v54
	ds_read_b128 v[54:57], v67 offset:10240
	ds_read_b128 v[74:77], v67 offset:10256
	ds_read_b128 v[78:81], v67 offset:12288
	s_waitcnt lgkmcnt(3)
	v_mul_f32_e32 v70, v53, v52
	ds_read_b128 v[82:85], v67 offset:10272
	ds_read_b128 v[86:89], v67 offset:10288
	v_pk_mul_f32 v[104:105], v[104:105], v[58:59] op_sel_hi:[1,0]
	v_pk_mul_f32 v[106:107], v[106:107], v[58:59] op_sel_hi:[1,0]
	s_waitcnt lgkmcnt(4)
	v_pk_fma_f32 v[104:105], v[56:57], v[70:71], v[104:105] op_sel_hi:[1,0,1]
	v_pk_fma_f32 v[106:107], v[54:55], v[70:71], v[106:107] op_sel_hi:[1,0,1]
	ds_read_b128 v[54:57], v67 offset:12304
	s_waitcnt lgkmcnt(3)
	v_mul_f32_e32 v59, v81, v105
	v_fmac_f32_e32 v59, v80, v104
	v_pk_mul_f32 v[100:101], v[100:101], v[58:59] op_sel_hi:[1,0]
	v_pk_mul_f32 v[102:103], v[102:103], v[58:59] op_sel_hi:[1,0]
	v_pk_fma_f32 v[100:101], v[70:71], v[76:77], v[100:101] op_sel_hi:[0,1,1]
	v_pk_fma_f32 v[102:103], v[70:71], v[74:75], v[102:103] op_sel_hi:[0,1,1]
	s_waitcnt lgkmcnt(2)
	v_pk_mul_f32 v[74:75], v[70:71], v[84:85] op_sel_hi:[0,1]
	v_pk_mul_f32 v[76:77], v[70:71], v[82:83] op_sel_hi:[0,1]
	v_mul_f32_e32 v53, v79, v107
	v_pk_fma_f32 v[98:99], v[98:99], v[58:59], v[74:75] op_sel_hi:[1,0,1]
	v_pk_fma_f32 v[96:97], v[96:97], v[58:59], v[76:77] op_sel_hi:[1,0,1]
	ds_read_b128 v[74:77], v67 offset:12336
	s_waitcnt lgkmcnt(1)
	v_mul_f32_e32 v55, v55, v103
	v_fmac_f32_e32 v53, v78, v106
	v_fmac_f32_e32 v55, v54, v102
	v_mul_f32_e32 v54, v57, v101
	v_add_f32_e32 v53, v53, v59
	v_fmac_f32_e32 v54, v56, v100
	v_add_f32_e32 v53, 0, v53
	v_add_f32_e32 v54, v55, v54
	v_add_f32_e32 v53, v54, v53
	ds_read_b128 v[54:57], v67 offset:12320
	s_waitcnt lgkmcnt(0)
	v_mul_f32_e32 v55, v55, v97
	v_fmac_f32_e32 v55, v54, v96
	v_mul_f32_e32 v54, v57, v99
	v_fmac_f32_e32 v54, v56, v98
	v_add_f32_e32 v54, v55, v54
	v_add_f32_e32 v53, v54, v53
	v_pk_mul_f32 v[54:55], v[70:71], v[88:89] op_sel_hi:[0,1]
	v_pk_mul_f32 v[56:57], v[70:71], v[86:87] op_sel_hi:[0,1]
	v_pk_fma_f32 v[94:95], v[94:95], v[58:59], v[54:55] op_sel_hi:[1,0,1]
	v_pk_fma_f32 v[92:93], v[92:93], v[58:59], v[56:57] op_sel_hi:[1,0,1]
	v_mul_f32_e32 v55, v77, v95
	v_mul_f32_e32 v54, v75, v93
	v_fmac_f32_e32 v54, v74, v92
	v_fmac_f32_e32 v55, v76, v94
	v_add_f32_e32 v54, v54, v55
	v_add_f32_e32 v53, v53, v54
	ds_bpermute_b32 v54, v61, v53
	s_waitcnt lgkmcnt(0)
	v_add_f32_e32 v53, v53, v54
	ds_bpermute_b32 v54, v62, v53
	s_waitcnt lgkmcnt(0)
	v_add_f32_e32 v53, v53, v54
	ds_bpermute_b32 v54, v63, v53
	s_and_saveexec_b64 s[14:15], s[6:7]
	s_cbranch_execz .Lssd12_3_691
	ds_read_b32 v55, v64 offset:44288
	s_waitcnt lgkmcnt(1)
	v_add_f32_e32 v53, v53, v54
	v_fmac_f32_e32 v53, v66, v52
	s_waitcnt lgkmcnt(0)
	v_mul_f32_e32 v56, 0xbfb8aa3b, v55
	v_exp_f32_e32 v56, v56
	s_nop 0
	v_add_f32_e32 v54, 1.0, v56
	v_div_scale_f32 v56, s[2:3], v54, v54, v55
	v_rcp_f32_e32 v57, v56
	v_div_scale_f32 v52, vcc, v55, v54, v55
	v_fma_f32 v58, -v56, v57, 1.0
	v_fmac_f32_e32 v57, v58, v57
	v_mul_f32_e32 v58, v52, v57
	v_fma_f32 v59, -v56, v58, v52
	v_fmac_f32_e32 v58, v59, v57
	v_fma_f32 v52, -v56, v58, v52
	v_div_fmas_f32 v52, v52, v57, v58
	v_div_fixup_f32 v52, v52, v54, v55
	v_mul_f32_e32 v52, v53, v52
	ds_write_b32 v64, v52 offset:32000
.Lssd12_3_691:
	s_or_b64 exec, exec, s[14:15]
	v_mov_b32_e32 v52, s1
	ds_read_b32 v56, v52 offset:96
	ds_read_b32 v69, v64 offset:14336
	s_waitcnt lgkmcnt(1)
	v_mul_f32_e32 v52, v56, v68
	v_mul_f32_e32 v52, 0xbfb8aa3b, v52
	v_exp_f32_e32 v70, v52
	ds_read_b128 v[52:55], v67 offset:17408
	ds_read_b128 v[74:77], v67 offset:17424
	ds_read_b128 v[78:81], v67 offset:19456
	s_waitcnt lgkmcnt(3)
	v_mul_f32_e32 v72, v56, v69
	v_pk_mul_f32 v[56:57], v[104:105], v[70:71] op_sel_hi:[1,0]
	v_pk_mul_f32 v[58:59], v[106:107], v[70:71] op_sel_hi:[1,0]
	s_waitcnt lgkmcnt(2)
	v_pk_fma_f32 v[56:57], v[54:55], v[72:73], v[56:57] op_sel_hi:[1,0,1]
	v_pk_fma_f32 v[58:59], v[52:53], v[72:73], v[58:59] op_sel_hi:[1,0,1]
	s_waitcnt lgkmcnt(0)
	v_mul_f32_e32 v53, v81, v57
	v_mul_f32_e32 v52, v79, v59
	ds_read_b128 v[104:107], v67 offset:17440
	ds_read_b128 v[82:85], v67 offset:17456
	ds_read_b128 v[86:89], v67 offset:19472
	v_fmac_f32_e32 v52, v78, v58
	v_fmac_f32_e32 v53, v80, v56
	v_add_f32_e32 v52, v52, v53
	v_add_f32_e32 v71, 0, v52
	v_pk_mul_f32 v[100:101], v[100:101], v[70:71] op_sel_hi:[1,0]
	v_pk_mul_f32 v[52:53], v[102:103], v[70:71] op_sel_hi:[1,0]
	v_pk_fma_f32 v[102:103], v[72:73], v[76:77], v[100:101] op_sel_hi:[0,1,1]
	v_pk_fma_f32 v[54:55], v[72:73], v[74:75], v[52:53] op_sel_hi:[0,1,1]
	ds_read_b128 v[74:77], v67 offset:19488
	s_waitcnt lgkmcnt(1)
	v_mul_f32_e32 v100, v87, v55
	v_mul_f32_e32 v101, v89, v103
	v_fmac_f32_e32 v100, v86, v54
	v_fmac_f32_e32 v101, v88, v102
	v_add_f32_e32 v100, v100, v101
	v_add_f32_e32 v52, v100, v71
	v_pk_mul_f32 v[100:101], v[72:73], v[106:107] op_sel_hi:[0,1]
	v_pk_mul_f32 v[104:105], v[72:73], v[104:105] op_sel_hi:[0,1]
	v_pk_fma_f32 v[100:101], v[98:99], v[70:71], v[100:101] op_sel_hi:[1,0,1]
	v_pk_fma_f32 v[106:107], v[96:97], v[70:71], v[104:105] op_sel_hi:[1,0,1]
	ds_read_b128 v[96:99], v67 offset:19504
	s_waitcnt lgkmcnt(1)
	v_mul_f32_e32 v104, v75, v107
	v_mul_f32_e32 v105, v77, v101
	v_fmac_f32_e32 v104, v74, v106
	v_fmac_f32_e32 v105, v76, v100
	v_add_f32_e32 v104, v104, v105
	v_add_f32_e32 v71, v104, v52
	v_pk_mul_f32 v[104:105], v[72:73], v[84:85] op_sel_hi:[0,1]
	v_pk_mul_f32 v[52:53], v[72:73], v[82:83] op_sel_hi:[0,1]
	v_pk_fma_f32 v[104:105], v[94:95], v[70:71], v[104:105] op_sel_hi:[1,0,1]
	v_pk_fma_f32 v[52:53], v[92:93], v[70:71], v[52:53] op_sel_hi:[1,0,1]
	s_waitcnt lgkmcnt(0)
	v_mul_f32_e32 v93, v99, v105
	v_mul_f32_e32 v92, v97, v53
	v_fmac_f32_e32 v92, v96, v52
	v_fmac_f32_e32 v93, v98, v104
	v_add_f32_e32 v92, v92, v93
	v_add_f32_e32 v92, v71, v92
	ds_bpermute_b32 v93, v61, v92
	s_waitcnt lgkmcnt(0)
	v_add_f32_e32 v92, v92, v93
	ds_bpermute_b32 v93, v62, v92
	s_waitcnt lgkmcnt(0)
	v_add_f32_e32 v92, v92, v93
	ds_bpermute_b32 v93, v63, v92
	s_and_saveexec_b64 s[14:15], s[6:7]
	s_cbranch_execz .Lssd12_3_693
	ds_read_b32 v94, v64 offset:47360
	s_waitcnt lgkmcnt(1)
	v_add_f32_e32 v92, v92, v93
	v_fmac_f32_e32 v92, v66, v69
	s_waitcnt lgkmcnt(0)
	v_mul_f32_e32 v95, 0xbfb8aa3b, v94
	v_exp_f32_e32 v95, v95
	s_nop 0
	v_add_f32_e32 v93, 1.0, v95
	v_div_scale_f32 v95, s[2:3], v93, v93, v94
	v_rcp_f32_e32 v96, v95
	v_div_scale_f32 v97, vcc, v94, v93, v94
	v_fma_f32 v98, -v95, v96, 1.0
	v_fmac_f32_e32 v96, v98, v96
	v_mul_f32_e32 v98, v97, v96
	v_fma_f32 v99, -v95, v98, v97
	v_fmac_f32_e32 v98, v99, v96
	v_fma_f32 v95, -v95, v98, v97
	v_div_fmas_f32 v95, v95, v96, v98
	v_div_fixup_f32 v93, v95, v93, v94
	v_mul_f32_e32 v92, v92, v93
	ds_write_b32 v64, v92 offset:35072
.Lssd12_3_693:
	s_or_b64 exec, exec, s[14:15]
	v_mov_b32_e32 v92, s1
	ds_read_b32 v70, v92 offset:144
	ds_read_b32 v69, v64 offset:21504
	s_waitcnt lgkmcnt(1)
	v_mul_f32_e32 v92, v70, v68
	v_mul_f32_e32 v92, 0xbfb8aa3b, v92
	v_exp_f32_e32 v68, v92
	ds_read_b128 v[92:95], v67 offset:24576
	ds_read_b128 v[96:99], v67 offset:24592
	ds_read_b128 v[74:77], v67 offset:26624
	s_waitcnt lgkmcnt(3)
	v_mul_f32_e32 v70, v70, v69
	v_pk_mul_f32 v[82:83], v[56:57], v[68:69] op_sel_hi:[1,0]
	v_pk_mul_f32 v[84:85], v[58:59], v[68:69] op_sel_hi:[1,0]
	s_waitcnt lgkmcnt(2)
	v_pk_fma_f32 v[94:95], v[94:95], v[70:71], v[82:83] op_sel_hi:[1,0,1]
	v_pk_fma_f32 v[92:93], v[92:93], v[70:71], v[84:85] op_sel_hi:[1,0,1]
	ds_read_b128 v[56:59], v67 offset:24608
	ds_read_b128 v[78:81], v67 offset:24624
	ds_read_b128 v[82:85], v67 offset:26640
	s_waitcnt lgkmcnt(3)
	v_mul_f32_e32 v71, v75, v93
	v_mul_f32_e32 v72, v77, v95
	v_fmac_f32_e32 v71, v74, v92
	v_fmac_f32_e32 v72, v76, v94
	v_add_f32_e32 v71, v71, v72
	v_add_f32_e32 v71, 0, v71
	v_pk_mul_f32 v[102:103], v[102:103], v[68:69] op_sel_hi:[1,0]
	v_pk_mul_f32 v[54:55], v[54:55], v[68:69] op_sel_hi:[1,0]
	v_pk_fma_f32 v[98:99], v[70:71], v[98:99], v[102:103] op_sel_hi:[0,1,1]
	v_pk_fma_f32 v[96:97], v[70:71], v[96:97], v[54:55] op_sel_hi:[0,1,1]
	ds_read_b128 v[74:77], v67 offset:26656
	s_waitcnt lgkmcnt(1)
	v_mul_f32_e32 v102, v83, v97
	v_mul_f32_e32 v103, v85, v99
	v_fmac_f32_e32 v102, v82, v96
	v_fmac_f32_e32 v103, v84, v98
	v_add_f32_e32 v102, v102, v103
	v_add_f32_e32 v71, v102, v71
	v_pk_mul_f32 v[102:103], v[70:71], v[58:59] op_sel_hi:[0,1]
	v_pk_mul_f32 v[54:55], v[70:71], v[56:57] op_sel_hi:[0,1]
	v_pk_fma_f32 v[102:103], v[100:101], v[68:69], v[102:103] op_sel_hi:[1,0,1]
	v_pk_fma_f32 v[100:101], v[106:107], v[68:69], v[54:55] op_sel_hi:[1,0,1]
	ds_read_b128 v[54:57], v67 offset:26672
	s_waitcnt lgkmcnt(1)
	v_mul_f32_e32 v106, v75, v101
	v_mul_f32_e32 v107, v77, v103
	v_fmac_f32_e32 v106, v74, v100
	v_fmac_f32_e32 v107, v76, v102
	v_add_f32_e32 v106, v106, v107
	v_add_f32_e32 v67, v106, v71
	v_pk_mul_f32 v[106:107], v[70:71], v[80:81] op_sel_hi:[0,1]
	v_pk_mul_f32 v[58:59], v[70:71], v[78:79] op_sel_hi:[0,1]
	v_pk_fma_f32 v[106:107], v[104:105], v[68:69], v[106:107] op_sel_hi:[1,0,1]
	v_pk_fma_f32 v[104:105], v[52:53], v[68:69], v[58:59] op_sel_hi:[1,0,1]
	s_waitcnt lgkmcnt(0)
	v_mul_f32_e32 v53, v57, v107
	v_mul_f32_e32 v52, v55, v105
	v_fmac_f32_e32 v52, v54, v104
	v_fmac_f32_e32 v53, v56, v106
	v_add_f32_e32 v52, v52, v53
	v_add_f32_e32 v52, v67, v52
	ds_bpermute_b32 v53, v61, v52
	s_waitcnt lgkmcnt(0)
	v_add_f32_e32 v52, v52, v53
	ds_bpermute_b32 v53, v62, v52
	s_waitcnt lgkmcnt(0)
	v_add_f32_e32 v52, v52, v53
	ds_bpermute_b32 v53, v63, v52
	s_and_saveexec_b64 s[14:15], s[6:7]
	s_cbranch_execz .Lssd12_3_tail
	ds_read_b32 v54, v64 offset:50432
	s_waitcnt lgkmcnt(1)
	v_add_f32_e32 v52, v52, v53
	v_fmac_f32_e32 v52, v66, v69
	s_waitcnt lgkmcnt(0)
	v_mul_f32_e32 v55, 0xbfb8aa3b, v54
	v_exp_f32_e32 v55, v55
	s_nop 0
	v_add_f32_e32 v53, 1.0, v55
	v_div_scale_f32 v55, s[2:3], v53, v53, v54
	v_rcp_f32_e32 v56, v55
	v_div_scale_f32 v57, vcc, v54, v53, v54
	v_fma_f32 v58, -v55, v56, 1.0
	v_fmac_f32_e32 v56, v58, v56
	v_mul_f32_e32 v58, v57, v56
	v_fma_f32 v59, -v55, v58, v57
	v_fmac_f32_e32 v58, v59, v56
	v_fma_f32 v55, -v55, v58, v57
	v_div_fmas_f32 v55, v55, v56, v58
	v_div_fixup_f32 v53, v55, v53, v54
	v_mul_f32_e32 v52, v52, v53
	ds_write_b32 v64, v52 offset:38144
	s_branch .Lssd12_3_tail
.Lssd12_3_tail:
	s_or_b64 exec, exec, s[14:15]
	s_add_i32 s0, s0, 1
	s_add_i32 s1, s1, 4
	s_waitcnt lgkmcnt(0)
	v_lshl_add_u64 v[52:53], v[50:51], 0, s[8:9]
	s_add_u32 s8, s8, 0x8000
	s_addc_u32 s9, s9, 0
	v_add_co_u32_e32 v52, vcc, 0x2fb35000, v52
	s_add_u32 s12, s12, 4
	s_nop 0
	v_addc_co_u32_e32 v53, vcc, 0, v53, vcc
	s_addc_u32 s13, s13, 0
	global_store_dwordx4 v[52:53], v[92:95], off
	global_store_dwordx4 v[52:53], v[96:99], off offset:16
	global_store_dwordx4 v[52:53], v[100:103], off offset:32
	global_store_dwordx4 v[52:53], v[104:107], off offset:48
	s_add_u32 s10, s10, 4
	s_addc_u32 s11, s11, 0
	v_add_u32_e32 v64, 0x100, v64
.Lssd12_4:
	s_load_dword s16, s[12:13], 0x0
	s_load_dword s17, s[10:11], 0x0
	s_mul_i32 s2, s0, 0xab
	s_and_b32 s2, s2, 0xfe00
	v_add_u32_e32 v67, s2, v65
	s_waitcnt vmcnt(44)
	s_waitcnt lgkmcnt(0)
	v_mov_b32_e32 v52, s16
	v_mov_b32_e32 v66, s17
	v_mul_f32_e32 v52, 0x3fb8aa3b, v52
	v_exp_f32_e32 v68, v52
	v_mov_b32_e32 v52, s1
	ds_read_b32 v53, v52
	s_waitcnt lgkmcnt(0)
	v_mul_f32_e64 v52, v53, -v68
	v_mul_f32_e32 v52, 0x3fb8aa3b, v52
	v_exp_f32_e32 v58, v52
	ds_read_b32 v52, v64
	ds_read_b128 v[54:57], v67 offset:3072
	ds_read_b128 v[74:77], v67 offset:3088
	ds_read_b128 v[78:81], v67 offset:3104
	ds_read_b128 v[82:85], v67 offset:3120
	v_pk_mul_f32 v[122:123], v[122:123], v[58:59] op_sel_hi:[1,0]
	v_pk_mul_f32 v[86:87], v[120:121], v[58:59] op_sel_hi:[1,0]
	s_waitcnt lgkmcnt(4)
	v_mul_f32_e32 v70, v53, v52
	s_waitcnt lgkmcnt(3)
	v_pk_fma_f32 v[120:121], v[56:57], v[70:71], v[122:123] op_sel_hi:[1,0,1]
	v_pk_fma_f32 v[122:123], v[54:55], v[70:71], v[86:87] op_sel_hi:[1,0,1]
	ds_read_b128 v[54:57], v67 offset:5120
	v_pk_mul_f32 v[118:119], v[118:119], v[58:59] op_sel_hi:[1,0]
	s_waitcnt lgkmcnt(0)
	v_mul_f32_e32 v53, v55, v123
	v_fmac_f32_e32 v53, v54, v122
	v_mul_f32_e32 v54, v57, v121
	v_fmac_f32_e32 v54, v56, v120
	v_add_f32_e32 v53, v53, v54
	v_pk_mul_f32 v[54:55], v[116:117], v[58:59] op_sel_hi:[1,0]
	v_pk_fma_f32 v[116:117], v[70:71], v[76:77], v[118:119] op_sel_hi:[0,1,1]
	v_pk_fma_f32 v[118:119], v[70:71], v[74:75], v[54:55] op_sel_hi:[0,1,1]
	ds_read_b128 v[54:57], v67 offset:5136
	v_add_f32_e32 v53, 0, v53
	s_waitcnt lgkmcnt(0)
	v_mul_f32_e32 v55, v55, v119
	v_fmac_f32_e32 v55, v54, v118
	v_mul_f32_e32 v54, v57, v117
	v_fmac_f32_e32 v54, v56, v116
	v_add_f32_e32 v54, v55, v54
	v_add_f32_e32 v53, v54, v53
	v_pk_mul_f32 v[54:55], v[70:71], v[78:79] op_sel_hi:[0,1]
	v_pk_mul_f32 v[56:57], v[70:71], v[80:81] op_sel_hi:[0,1]
	v_pk_fma_f32 v[114:115], v[114:115], v[58:59], v[56:57] op_sel_hi:[1,0,1]
	v_pk_fma_f32 v[112:113], v[112:113], v[58:59], v[54:55] op_sel_hi:[1,0,1]
	ds_read_b128 v[54:57], v67 offset:5152
	s_waitcnt lgkmcnt(0)
	v_mul_f32_e32 v55, v55, v113
	v_fmac_f32_e32 v55, v54, v112
	v_mul_f32_e32 v54, v57, v115
	v_fmac_f32_e32 v54, v56, v114
	v_add_f32_e32 v54, v55, v54
	v_add_f32_e32 v53, v54, v53
	v_pk_mul_f32 v[54:55], v[70:71], v[82:83] op_sel_hi:[0,1]
	v_pk_mul_f32 v[56:57], v[70:71], v[84:85] op_sel_hi:[0,1]
	v_pk_fma_f32 v[110:111], v[110:111], v[58:59], v[56:57] op_sel_hi:[1,0,1]
	v_pk_fma_f32 v[108:109], v[108:109], v[58:59], v[54:55] op_sel_hi:[1,0,1]
	ds_read_b128 v[54:57], v67 offset:5168
	s_waitcnt lgkmcnt(0)
	v_mul_f32_e32 v55, v55, v109
	v_fmac_f32_e32 v55, v54, v108
	v_mul_f32_e32 v54, v57, v111
	v_fmac_f32_e32 v54, v56, v110
	v_add_f32_e32 v54, v55, v54
	v_add_f32_e32 v53, v53, v54
	ds_bpermute_b32 v54, v61, v53
	s_waitcnt lgkmcnt(0)
	v_add_f32_e32 v53, v53, v54
	ds_bpermute_b32 v54, v62, v53
	s_waitcnt lgkmcnt(0)
	v_add_f32_e32 v53, v53, v54
	ds_bpermute_b32 v54, v63, v53
	s_and_saveexec_b64 s[14:15], s[6:7]
	s_cbranch_execz .Lssd12_4_689
	ds_read_b32 v55, v64 offset:41216
	s_waitcnt lgkmcnt(1)
	v_add_f32_e32 v53, v53, v54
	v_fmac_f32_e32 v53, v66, v52
	s_waitcnt lgkmcnt(0)
	v_mul_f32_e32 v56, 0xbfb8aa3b, v55
	v_exp_f32_e32 v56, v56
	s_nop 0
	v_add_f32_e32 v54, 1.0, v56
	v_div_scale_f32 v56, s[2:3], v54, v54, v55
	v_rcp_f32_e32 v57, v56
	v_div_scale_f32 v52, vcc, v55, v54, v55
	v_fma_f32 v58, -v56, v57, 1.0
	v_fmac_f32_e32 v57, v58, v57
	v_mul_f32_e32 v58, v52, v57
	v_fma_f32 v59, -v56, v58, v52
	v_fmac_f32_e32 v58, v59, v57
	v_fma_f32 v52, -v56, v58, v52
	v_div_fmas_f32 v52, v52, v57, v58
	v_div_fixup_f32 v52, v52, v54, v55
	v_mul_f32_e32 v52, v53, v52
	ds_write_b32 v64, v52 offset:28928
.Lssd12_4_689:
	s_or_b64 exec, exec, s[14:15]
	v_mov_b32_e32 v52, s1
	ds_read_b32 v53, v52 offset:48
	ds_read_b32 v52, v64 offset:7168
	s_waitcnt lgkmcnt(1)
	v_mul_f32_e32 v54, v53, v68
	v_mul_f32_e32 v54, 0xbfb8aa3b, v54
	v_exp_f32_e32 v58, v54
	ds_read_b128 v[54:57], v67 offset:10240
	ds_read_b128 v[74:77], v67 offset:10256
	ds_read_b128 v[78:81], v67 offset:12288
	s_waitcnt lgkmcnt(3)
	v_mul_f32_e32 v70, v53, v52
	ds_read_b128 v[82:85], v67 offset:10272
	ds_read_b128 v[86:89], v67 offset:10288
	v_pk_mul_f32 v[120:121], v[120:121], v[58:59] op_sel_hi:[1,0]
	v_pk_mul_f32 v[122:123], v[122:123], v[58:59] op_sel_hi:[1,0]
	s_waitcnt lgkmcnt(4)
	v_pk_fma_f32 v[120:121], v[56:57], v[70:71], v[120:121] op_sel_hi:[1,0,1]
	v_pk_fma_f32 v[122:123], v[54:55], v[70:71], v[122:123] op_sel_hi:[1,0,1]
	ds_read_b128 v[54:57], v67 offset:12304
	s_waitcnt lgkmcnt(3)
	v_mul_f32_e32 v59, v81, v121
	v_fmac_f32_e32 v59, v80, v120
	v_pk_mul_f32 v[116:117], v[116:117], v[58:59] op_sel_hi:[1,0]
	v_pk_mul_f32 v[118:119], v[118:119], v[58:59] op_sel_hi:[1,0]
	v_pk_fma_f32 v[116:117], v[70:71], v[76:77], v[116:117] op_sel_hi:[0,1,1]
	v_pk_fma_f32 v[118:119], v[70:71], v[74:75], v[118:119] op_sel_hi:[0,1,1]
	s_waitcnt lgkmcnt(2)
	v_pk_mul_f32 v[74:75], v[70:71], v[84:85] op_sel_hi:[0,1]
	v_pk_mul_f32 v[76:77], v[70:71], v[82:83] op_sel_hi:[0,1]
	v_mul_f32_e32 v53, v79, v123
	v_pk_fma_f32 v[114:115], v[114:115], v[58:59], v[74:75] op_sel_hi:[1,0,1]
	v_pk_fma_f32 v[112:113], v[112:113], v[58:59], v[76:77] op_sel_hi:[1,0,1]
	ds_read_b128 v[74:77], v67 offset:12336
	s_waitcnt lgkmcnt(1)
	v_mul_f32_e32 v55, v55, v119
	v_fmac_f32_e32 v53, v78, v122
	v_fmac_f32_e32 v55, v54, v118
	v_mul_f32_e32 v54, v57, v117
	v_add_f32_e32 v53, v53, v59
	v_fmac_f32_e32 v54, v56, v116
	v_add_f32_e32 v53, 0, v53
	v_add_f32_e32 v54, v55, v54
	v_add_f32_e32 v53, v54, v53
	ds_read_b128 v[54:57], v67 offset:12320
	s_waitcnt lgkmcnt(0)
	v_mul_f32_e32 v55, v55, v113
	v_fmac_f32_e32 v55, v54, v112
	v_mul_f32_e32 v54, v57, v115
	v_fmac_f32_e32 v54, v56, v114
	v_add_f32_e32 v54, v55, v54
	v_add_f32_e32 v53, v54, v53
	v_pk_mul_f32 v[54:55], v[70:71], v[88:89] op_sel_hi:[0,1]
	v_pk_mul_f32 v[56:57], v[70:71], v[86:87] op_sel_hi:[0,1]
	v_pk_fma_f32 v[110:111], v[110:111], v[58:59], v[54:55] op_sel_hi:[1,0,1]
	v_pk_fma_f32 v[108:109], v[108:109], v[58:59], v[56:57] op_sel_hi:[1,0,1]
	v_mul_f32_e32 v55, v77, v111
	v_mul_f32_e32 v54, v75, v109
	v_fmac_f32_e32 v54, v74, v108
	v_fmac_f32_e32 v55, v76, v110
	v_add_f32_e32 v54, v54, v55
	v_add_f32_e32 v53, v53, v54
	ds_bpermute_b32 v54, v61, v53
	s_waitcnt lgkmcnt(0)
	v_add_f32_e32 v53, v53, v54
	ds_bpermute_b32 v54, v62, v53
	s_waitcnt lgkmcnt(0)
	v_add_f32_e32 v53, v53, v54
	ds_bpermute_b32 v54, v63, v53
	s_and_saveexec_b64 s[14:15], s[6:7]
	s_cbranch_execz .Lssd12_4_691
	ds_read_b32 v55, v64 offset:44288
	s_waitcnt lgkmcnt(1)
	v_add_f32_e32 v53, v53, v54
	v_fmac_f32_e32 v53, v66, v52
	s_waitcnt lgkmcnt(0)
	v_mul_f32_e32 v56, 0xbfb8aa3b, v55
	v_exp_f32_e32 v56, v56
	s_nop 0
	v_add_f32_e32 v54, 1.0, v56
	v_div_scale_f32 v56, s[2:3], v54, v54, v55
	v_rcp_f32_e32 v57, v56
	v_div_scale_f32 v52, vcc, v55, v54, v55
	v_fma_f32 v58, -v56, v57, 1.0
	v_fmac_f32_e32 v57, v58, v57
	v_mul_f32_e32 v58, v52, v57
	v_fma_f32 v59, -v56, v58, v52
	v_fmac_f32_e32 v58, v59, v57
	v_fma_f32 v52, -v56, v58, v52
	v_div_fmas_f32 v52, v52, v57, v58
	v_div_fixup_f32 v52, v52, v54, v55
	v_mul_f32_e32 v52, v53, v52
	ds_write_b32 v64, v52 offset:32000
.Lssd12_4_691:
	s_or_b64 exec, exec, s[14:15]
	v_mov_b32_e32 v52, s1
	ds_read_b32 v56, v52 offset:96
	ds_read_b32 v69, v64 offset:14336
	s_waitcnt lgkmcnt(1)
	v_mul_f32_e32 v52, v56, v68
	v_mul_f32_e32 v52, 0xbfb8aa3b, v52
	v_exp_f32_e32 v70, v52
	ds_read_b128 v[52:55], v67 offset:17408
	ds_read_b128 v[74:77], v67 offset:17424
	ds_read_b128 v[78:81], v67 offset:19456
	s_waitcnt lgkmcnt(3)
	v_mul_f32_e32 v72, v56, v69
	v_pk_mul_f32 v[56:57], v[120:121], v[70:71] op_sel_hi:[1,0]
	v_pk_mul_f32 v[58:59], v[122:123], v[70:71] op_sel_hi:[1,0]
	s_waitcnt lgkmcnt(2)
	v_pk_fma_f32 v[56:57], v[54:55], v[72:73], v[56:57] op_sel_hi:[1,0,1]
	v_pk_fma_f32 v[58:59], v[52:53], v[72:73], v[58:59] op_sel_hi:[1,0,1]
	s_waitcnt lgkmcnt(0)
	v_mul_f32_e32 v53, v81, v57
	v_mul_f32_e32 v52, v79, v59
	ds_read_b128 v[120:123], v67 offset:17440
	ds_read_b128 v[82:85], v67 offset:17456
	ds_read_b128 v[86:89], v67 offset:19472
	v_fmac_f32_e32 v52, v78, v58
	v_fmac_f32_e32 v53, v80, v56
	v_add_f32_e32 v52, v52, v53
	v_add_f32_e32 v71, 0, v52
	v_pk_mul_f32 v[116:117], v[116:117], v[70:71] op_sel_hi:[1,0]
	v_pk_mul_f32 v[52:53], v[118:119], v[70:71] op_sel_hi:[1,0]
	v_pk_fma_f32 v[118:119], v[72:73], v[76:77], v[116:117] op_sel_hi:[0,1,1]
	v_pk_fma_f32 v[54:55], v[72:73], v[74:75], v[52:53] op_sel_hi:[0,1,1]
	ds_read_b128 v[74:77], v67 offset:19488
	s_waitcnt lgkmcnt(1)
	v_mul_f32_e32 v116, v87, v55
	v_mul_f32_e32 v117, v89, v119
	v_fmac_f32_e32 v116, v86, v54
	v_fmac_f32_e32 v117, v88, v118
	v_add_f32_e32 v116, v116, v117
	v_add_f32_e32 v52, v116, v71
	v_pk_mul_f32 v[116:117], v[72:73], v[122:123] op_sel_hi:[0,1]
	v_pk_mul_f32 v[120:121], v[72:73], v[120:121] op_sel_hi:[0,1]
	v_pk_fma_f32 v[116:117], v[114:115], v[70:71], v[116:117] op_sel_hi:[1,0,1]
	v_pk_fma_f32 v[122:123], v[112:113], v[70:71], v[120:121] op_sel_hi:[1,0,1]
	ds_read_b128 v[112:115], v67 offset:19504
	s_waitcnt lgkmcnt(1)
	v_mul_f32_e32 v120, v75, v123
	v_mul_f32_e32 v121, v77, v117
	v_fmac_f32_e32 v120, v74, v122
	v_fmac_f32_e32 v121, v76, v116
	v_add_f32_e32 v120, v120, v121
	v_add_f32_e32 v71, v120, v52
	v_pk_mul_f32 v[120:121], v[72:73], v[84:85] op_sel_hi:[0,1]
	v_pk_mul_f32 v[52:53], v[72:73], v[82:83] op_sel_hi:[0,1]
	v_pk_fma_f32 v[120:121], v[110:111], v[70:71], v[120:121] op_sel_hi:[1,0,1]
	v_pk_fma_f32 v[52:53], v[108:109], v[70:71], v[52:53] op_sel_hi:[1,0,1]
	s_waitcnt lgkmcnt(0)
	v_mul_f32_e32 v109, v115, v121
	v_mul_f32_e32 v108, v113, v53
	v_fmac_f32_e32 v108, v112, v52
	v_fmac_f32_e32 v109, v114, v120
	v_add_f32_e32 v108, v108, v109
	v_add_f32_e32 v108, v71, v108
	ds_bpermute_b32 v109, v61, v108
	s_waitcnt lgkmcnt(0)
	v_add_f32_e32 v108, v108, v109
	ds_bpermute_b32 v109, v62, v108
	s_waitcnt lgkmcnt(0)
	v_add_f32_e32 v108, v108, v109
	ds_bpermute_b32 v109, v63, v108
	s_and_saveexec_b64 s[14:15], s[6:7]
	s_cbranch_execz .Lssd12_4_693
	ds_read_b32 v110, v64 offset:47360
	s_waitcnt lgkmcnt(1)
	v_add_f32_e32 v108, v108, v109
	v_fmac_f32_e32 v108, v66, v69
	s_waitcnt lgkmcnt(0)
	v_mul_f32_e32 v111, 0xbfb8aa3b, v110
	v_exp_f32_e32 v111, v111
	s_nop 0
	v_add_f32_e32 v109, 1.0, v111
	v_div_scale_f32 v111, s[2:3], v109, v109, v110
	v_rcp_f32_e32 v112, v111
	v_div_scale_f32 v113, vcc, v110, v109, v110
	v_fma_f32 v114, -v111, v112, 1.0
	v_fmac_f32_e32 v112, v114, v112
	v_mul_f32_e32 v114, v113, v112
	v_fma_f32 v115, -v111, v114, v113
	v_fmac_f32_e32 v114, v115, v112
	v_fma_f32 v111, -v111, v114, v113
	v_div_fmas_f32 v111, v111, v112, v114
	v_div_fixup_f32 v109, v111, v109, v110
	v_mul_f32_e32 v108, v108, v109
	ds_write_b32 v64, v108 offset:35072
.Lssd12_4_693:
	s_or_b64 exec, exec, s[14:15]
	v_mov_b32_e32 v108, s1
	ds_read_b32 v70, v108 offset:144
	ds_read_b32 v69, v64 offset:21504
	s_waitcnt lgkmcnt(1)
	v_mul_f32_e32 v108, v70, v68
	v_mul_f32_e32 v108, 0xbfb8aa3b, v108
	v_exp_f32_e32 v68, v108
	ds_read_b128 v[108:111], v67 offset:24576
	ds_read_b128 v[112:115], v67 offset:24592
	ds_read_b128 v[74:77], v67 offset:26624
	s_waitcnt lgkmcnt(3)
	v_mul_f32_e32 v70, v70, v69
	v_pk_mul_f32 v[82:83], v[56:57], v[68:69] op_sel_hi:[1,0]
	v_pk_mul_f32 v[84:85], v[58:59], v[68:69] op_sel_hi:[1,0]
	s_waitcnt lgkmcnt(2)
	v_pk_fma_f32 v[110:111], v[110:111], v[70:71], v[82:83] op_sel_hi:[1,0,1]
	v_pk_fma_f32 v[108:109], v[108:109], v[70:71], v[84:85] op_sel_hi:[1,0,1]
	ds_read_b128 v[56:59], v67 offset:24608
	ds_read_b128 v[78:81], v67 offset:24624
	ds_read_b128 v[82:85], v67 offset:26640
	s_waitcnt lgkmcnt(3)
	v_mul_f32_e32 v71, v75, v109
	v_mul_f32_e32 v72, v77, v111
	v_fmac_f32_e32 v71, v74, v108
	v_fmac_f32_e32 v72, v76, v110
	v_add_f32_e32 v71, v71, v72
	v_add_f32_e32 v71, 0, v71
	v_pk_mul_f32 v[118:119], v[118:119], v[68:69] op_sel_hi:[1,0]
	v_pk_mul_f32 v[54:55], v[54:55], v[68:69] op_sel_hi:[1,0]
	v_pk_fma_f32 v[114:115], v[70:71], v[114:115], v[118:119] op_sel_hi:[0,1,1]
	v_pk_fma_f32 v[112:113], v[70:71], v[112:113], v[54:55] op_sel_hi:[0,1,1]
	ds_read_b128 v[74:77], v67 offset:26656
	s_waitcnt lgkmcnt(1)
	v_mul_f32_e32 v118, v83, v113
	v_mul_f32_e32 v119, v85, v115
	v_fmac_f32_e32 v118, v82, v112
	v_fmac_f32_e32 v119, v84, v114
	v_add_f32_e32 v118, v118, v119
	v_add_f32_e32 v71, v118, v71
	v_pk_mul_f32 v[118:119], v[70:71], v[58:59] op_sel_hi:[0,1]
	v_pk_mul_f32 v[54:55], v[70:71], v[56:57] op_sel_hi:[0,1]
	v_pk_fma_f32 v[118:119], v[116:117], v[68:69], v[118:119] op_sel_hi:[1,0,1]
	v_pk_fma_f32 v[116:117], v[122:123], v[68:69], v[54:55] op_sel_hi:[1,0,1]
	ds_read_b128 v[54:57], v67 offset:26672
	s_waitcnt lgkmcnt(1)
	v_mul_f32_e32 v122, v75, v117
	v_mul_f32_e32 v123, v77, v119
	v_fmac_f32_e32 v122, v74, v116
	v_fmac_f32_e32 v123, v76, v118
	v_add_f32_e32 v122, v122, v123
	v_add_f32_e32 v67, v122, v71
	v_pk_mul_f32 v[122:123], v[70:71], v[80:81] op_sel_hi:[0,1]
	v_pk_mul_f32 v[58:59], v[70:71], v[78:79] op_sel_hi:[0,1]
	v_pk_fma_f32 v[122:123], v[120:121], v[68:69], v[122:123] op_sel_hi:[1,0,1]
	v_pk_fma_f32 v[120:121], v[52:53], v[68:69], v[58:59] op_sel_hi:[1,0,1]
	s_waitcnt lgkmcnt(0)
	v_mul_f32_e32 v53, v57, v123
	v_mul_f32_e32 v52, v55, v121
	v_fmac_f32_e32 v52, v54, v120
	v_fmac_f32_e32 v53, v56, v122
	v_add_f32_e32 v52, v52, v53
	v_add_f32_e32 v52, v67, v52
	ds_bpermute_b32 v53, v61, v52
	s_waitcnt lgkmcnt(0)
	v_add_f32_e32 v52, v52, v53
	ds_bpermute_b32 v53, v62, v52
	s_waitcnt lgkmcnt(0)
	v_add_f32_e32 v52, v52, v53
	ds_bpermute_b32 v53, v63, v52
	s_and_saveexec_b64 s[14:15], s[6:7]
	s_cbranch_execz .Lssd12_4_tail
	ds_read_b32 v54, v64 offset:50432
	s_waitcnt lgkmcnt(1)
	v_add_f32_e32 v52, v52, v53
	v_fmac_f32_e32 v52, v66, v69
	s_waitcnt lgkmcnt(0)
	v_mul_f32_e32 v55, 0xbfb8aa3b, v54
	v_exp_f32_e32 v55, v55
	s_nop 0
	v_add_f32_e32 v53, 1.0, v55
	v_div_scale_f32 v55, s[2:3], v53, v53, v54
	v_rcp_f32_e32 v56, v55
	v_div_scale_f32 v57, vcc, v54, v53, v54
	v_fma_f32 v58, -v55, v56, 1.0
	v_fmac_f32_e32 v56, v58, v56
	v_mul_f32_e32 v58, v57, v56
	v_fma_f32 v59, -v55, v58, v57
	v_fmac_f32_e32 v58, v59, v56
	v_fma_f32 v55, -v55, v58, v57
	v_div_fmas_f32 v55, v55, v56, v58
	v_div_fixup_f32 v53, v55, v53, v54
	v_mul_f32_e32 v52, v52, v53
	ds_write_b32 v64, v52 offset:38144
	s_branch .Lssd12_4_tail
.Lssd12_4_tail:
	s_or_b64 exec, exec, s[14:15]
	s_add_i32 s0, s0, 1
	s_add_i32 s1, s1, 4
	s_waitcnt lgkmcnt(0)
	v_lshl_add_u64 v[52:53], v[50:51], 0, s[8:9]
	s_add_u32 s8, s8, 0x8000
	s_addc_u32 s9, s9, 0
	v_add_co_u32_e32 v52, vcc, 0x2fb35000, v52
	s_add_u32 s12, s12, 4
	s_nop 0
	v_addc_co_u32_e32 v53, vcc, 0, v53, vcc
	s_addc_u32 s13, s13, 0
	global_store_dwordx4 v[52:53], v[108:111], off
	global_store_dwordx4 v[52:53], v[112:115], off offset:16
	global_store_dwordx4 v[52:53], v[116:119], off offset:32
	global_store_dwordx4 v[52:53], v[120:123], off offset:48
	s_add_u32 s10, s10, 4
	s_addc_u32 s11, s11, 0
	v_add_u32_e32 v64, 0x100, v64
.Lssd12_5:
	s_load_dword s16, s[12:13], 0x0
	s_load_dword s17, s[10:11], 0x0
	s_mul_i32 s2, s0, 0xab
	s_and_b32 s2, s2, 0xfe00
	v_add_u32_e32 v67, s2, v65
	s_waitcnt vmcnt(44)
	s_waitcnt lgkmcnt(0)
	v_mov_b32_e32 v52, s16
	v_mov_b32_e32 v66, s17
	v_mul_f32_e32 v52, 0x3fb8aa3b, v52
	v_exp_f32_e32 v68, v52
	v_mov_b32_e32 v52, s1
	ds_read_b32 v53, v52
	s_waitcnt lgkmcnt(0)
	v_mul_f32_e64 v52, v53, -v68
	v_mul_f32_e32 v52, 0x3fb8aa3b, v52
	v_exp_f32_e32 v58, v52
	ds_read_b32 v52, v64
	ds_read_b128 v[54:57], v67 offset:3072
	ds_read_b128 v[74:77], v67 offset:3088
	ds_read_b128 v[78:81], v67 offset:3104
	ds_read_b128 v[82:85], v67 offset:3120
	v_pk_mul_f32 v[138:139], v[138:139], v[58:59] op_sel_hi:[1,0]
	v_pk_mul_f32 v[86:87], v[136:137], v[58:59] op_sel_hi:[1,0]
	s_waitcnt lgkmcnt(4)
	v_mul_f32_e32 v70, v53, v52
	s_waitcnt lgkmcnt(3)
	v_pk_fma_f32 v[136:137], v[56:57], v[70:71], v[138:139] op_sel_hi:[1,0,1]
	v_pk_fma_f32 v[138:139], v[54:55], v[70:71], v[86:87] op_sel_hi:[1,0,1]
	ds_read_b128 v[54:57], v67 offset:5120
	v_pk_mul_f32 v[134:135], v[134:135], v[58:59] op_sel_hi:[1,0]
	s_waitcnt lgkmcnt(0)
	v_mul_f32_e32 v53, v55, v139
	v_fmac_f32_e32 v53, v54, v138
	v_mul_f32_e32 v54, v57, v137
	v_fmac_f32_e32 v54, v56, v136
	v_add_f32_e32 v53, v53, v54
	v_pk_mul_f32 v[54:55], v[132:133], v[58:59] op_sel_hi:[1,0]
	v_pk_fma_f32 v[132:133], v[70:71], v[76:77], v[134:135] op_sel_hi:[0,1,1]
	v_pk_fma_f32 v[134:135], v[70:71], v[74:75], v[54:55] op_sel_hi:[0,1,1]
	ds_read_b128 v[54:57], v67 offset:5136
	v_add_f32_e32 v53, 0, v53
	s_waitcnt lgkmcnt(0)
	v_mul_f32_e32 v55, v55, v135
	v_fmac_f32_e32 v55, v54, v134
	v_mul_f32_e32 v54, v57, v133
	v_fmac_f32_e32 v54, v56, v132
	v_add_f32_e32 v54, v55, v54
	v_add_f32_e32 v53, v54, v53
	v_pk_mul_f32 v[54:55], v[70:71], v[78:79] op_sel_hi:[0,1]
	v_pk_mul_f32 v[56:57], v[70:71], v[80:81] op_sel_hi:[0,1]
	v_pk_fma_f32 v[130:131], v[130:131], v[58:59], v[56:57] op_sel_hi:[1,0,1]
	v_pk_fma_f32 v[128:129], v[128:129], v[58:59], v[54:55] op_sel_hi:[1,0,1]
	ds_read_b128 v[54:57], v67 offset:5152
	s_waitcnt lgkmcnt(0)
	v_mul_f32_e32 v55, v55, v129
	v_fmac_f32_e32 v55, v54, v128
	v_mul_f32_e32 v54, v57, v131
	v_fmac_f32_e32 v54, v56, v130
	v_add_f32_e32 v54, v55, v54
	v_add_f32_e32 v53, v54, v53
	v_pk_mul_f32 v[54:55], v[70:71], v[82:83] op_sel_hi:[0,1]
	v_pk_mul_f32 v[56:57], v[70:71], v[84:85] op_sel_hi:[0,1]
	v_pk_fma_f32 v[126:127], v[126:127], v[58:59], v[56:57] op_sel_hi:[1,0,1]
	v_pk_fma_f32 v[124:125], v[124:125], v[58:59], v[54:55] op_sel_hi:[1,0,1]
	ds_read_b128 v[54:57], v67 offset:5168
	s_waitcnt lgkmcnt(0)
	v_mul_f32_e32 v55, v55, v125
	v_fmac_f32_e32 v55, v54, v124
	v_mul_f32_e32 v54, v57, v127
	v_fmac_f32_e32 v54, v56, v126
	v_add_f32_e32 v54, v55, v54
	v_add_f32_e32 v53, v53, v54
	ds_bpermute_b32 v54, v61, v53
	s_waitcnt lgkmcnt(0)
	v_add_f32_e32 v53, v53, v54
	ds_bpermute_b32 v54, v62, v53
	s_waitcnt lgkmcnt(0)
	v_add_f32_e32 v53, v53, v54
	ds_bpermute_b32 v54, v63, v53
	s_and_saveexec_b64 s[14:15], s[6:7]
	s_cbranch_execz .Lssd12_5_689
	ds_read_b32 v55, v64 offset:41216
	s_waitcnt lgkmcnt(1)
	v_add_f32_e32 v53, v53, v54
	v_fmac_f32_e32 v53, v66, v52
	s_waitcnt lgkmcnt(0)
	v_mul_f32_e32 v56, 0xbfb8aa3b, v55
	v_exp_f32_e32 v56, v56
	s_nop 0
	v_add_f32_e32 v54, 1.0, v56
	v_div_scale_f32 v56, s[2:3], v54, v54, v55
	v_rcp_f32_e32 v57, v56
	v_div_scale_f32 v52, vcc, v55, v54, v55
	v_fma_f32 v58, -v56, v57, 1.0
	v_fmac_f32_e32 v57, v58, v57
	v_mul_f32_e32 v58, v52, v57
	v_fma_f32 v59, -v56, v58, v52
	v_fmac_f32_e32 v58, v59, v57
	v_fma_f32 v52, -v56, v58, v52
	v_div_fmas_f32 v52, v52, v57, v58
	v_div_fixup_f32 v52, v52, v54, v55
	v_mul_f32_e32 v52, v53, v52
	ds_write_b32 v64, v52 offset:28928
.Lssd12_5_689:
	s_or_b64 exec, exec, s[14:15]
	v_mov_b32_e32 v52, s1
	ds_read_b32 v53, v52 offset:48
	ds_read_b32 v52, v64 offset:7168
	s_waitcnt lgkmcnt(1)
	v_mul_f32_e32 v54, v53, v68
	v_mul_f32_e32 v54, 0xbfb8aa3b, v54
	v_exp_f32_e32 v58, v54
	ds_read_b128 v[54:57], v67 offset:10240
	ds_read_b128 v[74:77], v67 offset:10256
	ds_read_b128 v[78:81], v67 offset:12288
	s_waitcnt lgkmcnt(3)
	v_mul_f32_e32 v70, v53, v52
	ds_read_b128 v[82:85], v67 offset:10272
	ds_read_b128 v[86:89], v67 offset:10288
	v_pk_mul_f32 v[136:137], v[136:137], v[58:59] op_sel_hi:[1,0]
	v_pk_mul_f32 v[138:139], v[138:139], v[58:59] op_sel_hi:[1,0]
	s_waitcnt lgkmcnt(4)
	v_pk_fma_f32 v[136:137], v[56:57], v[70:71], v[136:137] op_sel_hi:[1,0,1]
	v_pk_fma_f32 v[138:139], v[54:55], v[70:71], v[138:139] op_sel_hi:[1,0,1]
	ds_read_b128 v[54:57], v67 offset:12304
	s_waitcnt lgkmcnt(3)
	v_mul_f32_e32 v59, v81, v137
	v_fmac_f32_e32 v59, v80, v136
	v_pk_mul_f32 v[132:133], v[132:133], v[58:59] op_sel_hi:[1,0]
	v_pk_mul_f32 v[134:135], v[134:135], v[58:59] op_sel_hi:[1,0]
	v_pk_fma_f32 v[132:133], v[70:71], v[76:77], v[132:133] op_sel_hi:[0,1,1]
	v_pk_fma_f32 v[134:135], v[70:71], v[74:75], v[134:135] op_sel_hi:[0,1,1]
	s_waitcnt lgkmcnt(2)
	v_pk_mul_f32 v[74:75], v[70:71], v[84:85] op_sel_hi:[0,1]
	v_pk_mul_f32 v[76:77], v[70:71], v[82:83] op_sel_hi:[0,1]
	v_mul_f32_e32 v53, v79, v139
	v_pk_fma_f32 v[130:131], v[130:131], v[58:59], v[74:75] op_sel_hi:[1,0,1]
	v_pk_fma_f32 v[128:129], v[128:129], v[58:59], v[76:77] op_sel_hi:[1,0,1]
	ds_read_b128 v[74:77], v67 offset:12336
	s_waitcnt lgkmcnt(1)
	v_mul_f32_e32 v55, v55, v135
	v_fmac_f32_e32 v53, v78, v138
	v_fmac_f32_e32 v55, v54, v134
	v_mul_f32_e32 v54, v57, v133
	v_add_f32_e32 v53, v53, v59
	v_fmac_f32_e32 v54, v56, v132
	v_add_f32_e32 v53, 0, v53
	v_add_f32_e32 v54, v55, v54
	v_add_f32_e32 v53, v54, v53
	ds_read_b128 v[54:57], v67 offset:12320
	s_waitcnt lgkmcnt(0)
	v_mul_f32_e32 v55, v55, v129
	v_fmac_f32_e32 v55, v54, v128
	v_mul_f32_e32 v54, v57, v131
	v_fmac_f32_e32 v54, v56, v130
	v_add_f32_e32 v54, v55, v54
	v_add_f32_e32 v53, v54, v53
	v_pk_mul_f32 v[54:55], v[70:71], v[88:89] op_sel_hi:[0,1]
	v_pk_mul_f32 v[56:57], v[70:71], v[86:87] op_sel_hi:[0,1]
	v_pk_fma_f32 v[126:127], v[126:127], v[58:59], v[54:55] op_sel_hi:[1,0,1]
	v_pk_fma_f32 v[124:125], v[124:125], v[58:59], v[56:57] op_sel_hi:[1,0,1]
	v_mul_f32_e32 v55, v77, v127
	v_mul_f32_e32 v54, v75, v125
	v_fmac_f32_e32 v54, v74, v124
	v_fmac_f32_e32 v55, v76, v126
	v_add_f32_e32 v54, v54, v55
	v_add_f32_e32 v53, v53, v54
	ds_bpermute_b32 v54, v61, v53
	s_waitcnt lgkmcnt(0)
	v_add_f32_e32 v53, v53, v54
	ds_bpermute_b32 v54, v62, v53
	s_waitcnt lgkmcnt(0)
	v_add_f32_e32 v53, v53, v54
	ds_bpermute_b32 v54, v63, v53
	s_and_saveexec_b64 s[14:15], s[6:7]
	s_cbranch_execz .Lssd12_5_691
	ds_read_b32 v55, v64 offset:44288
	s_waitcnt lgkmcnt(1)
	v_add_f32_e32 v53, v53, v54
	v_fmac_f32_e32 v53, v66, v52
	s_waitcnt lgkmcnt(0)
	v_mul_f32_e32 v56, 0xbfb8aa3b, v55
	v_exp_f32_e32 v56, v56
	s_nop 0
	v_add_f32_e32 v54, 1.0, v56
	v_div_scale_f32 v56, s[2:3], v54, v54, v55
	v_rcp_f32_e32 v57, v56
	v_div_scale_f32 v52, vcc, v55, v54, v55
	v_fma_f32 v58, -v56, v57, 1.0
	v_fmac_f32_e32 v57, v58, v57
	v_mul_f32_e32 v58, v52, v57
	v_fma_f32 v59, -v56, v58, v52
	v_fmac_f32_e32 v58, v59, v57
	v_fma_f32 v52, -v56, v58, v52
	v_div_fmas_f32 v52, v52, v57, v58
	v_div_fixup_f32 v52, v52, v54, v55
	v_mul_f32_e32 v52, v53, v52
	ds_write_b32 v64, v52 offset:32000
.Lssd12_5_691:
	s_or_b64 exec, exec, s[14:15]
	v_mov_b32_e32 v52, s1
	ds_read_b32 v56, v52 offset:96
	ds_read_b32 v69, v64 offset:14336
	s_waitcnt lgkmcnt(1)
	v_mul_f32_e32 v52, v56, v68
	v_mul_f32_e32 v52, 0xbfb8aa3b, v52
	v_exp_f32_e32 v70, v52
	ds_read_b128 v[52:55], v67 offset:17408
	ds_read_b128 v[74:77], v67 offset:17424
	ds_read_b128 v[78:81], v67 offset:19456
	s_waitcnt lgkmcnt(3)
	v_mul_f32_e32 v72, v56, v69
	v_pk_mul_f32 v[56:57], v[136:137], v[70:71] op_sel_hi:[1,0]
	v_pk_mul_f32 v[58:59], v[138:139], v[70:71] op_sel_hi:[1,0]
	s_waitcnt lgkmcnt(2)
	v_pk_fma_f32 v[56:57], v[54:55], v[72:73], v[56:57] op_sel_hi:[1,0,1]
	v_pk_fma_f32 v[58:59], v[52:53], v[72:73], v[58:59] op_sel_hi:[1,0,1]
	s_waitcnt lgkmcnt(0)
	v_mul_f32_e32 v53, v81, v57
	v_mul_f32_e32 v52, v79, v59
	ds_read_b128 v[136:139], v67 offset:17440
	ds_read_b128 v[82:85], v67 offset:17456
	ds_read_b128 v[86:89], v67 offset:19472
	v_fmac_f32_e32 v52, v78, v58
	v_fmac_f32_e32 v53, v80, v56
	v_add_f32_e32 v52, v52, v53
	v_add_f32_e32 v71, 0, v52
	v_pk_mul_f32 v[132:133], v[132:133], v[70:71] op_sel_hi:[1,0]
	v_pk_mul_f32 v[52:53], v[134:135], v[70:71] op_sel_hi:[1,0]
	v_pk_fma_f32 v[134:135], v[72:73], v[76:77], v[132:133] op_sel_hi:[0,1,1]
	v_pk_fma_f32 v[54:55], v[72:73], v[74:75], v[52:53] op_sel_hi:[0,1,1]
	ds_read_b128 v[74:77], v67 offset:19488
	s_waitcnt lgkmcnt(1)
	v_mul_f32_e32 v132, v87, v55
	v_mul_f32_e32 v133, v89, v135
	v_fmac_f32_e32 v132, v86, v54
	v_fmac_f32_e32 v133, v88, v134
	v_add_f32_e32 v132, v132, v133
	v_add_f32_e32 v52, v132, v71
	v_pk_mul_f32 v[132:133], v[72:73], v[138:139] op_sel_hi:[0,1]
	v_pk_mul_f32 v[136:137], v[72:73], v[136:137] op_sel_hi:[0,1]
	v_pk_fma_f32 v[132:133], v[130:131], v[70:71], v[132:133] op_sel_hi:[1,0,1]
	v_pk_fma_f32 v[138:139], v[128:129], v[70:71], v[136:137] op_sel_hi:[1,0,1]
	ds_read_b128 v[128:131], v67 offset:19504
	s_waitcnt lgkmcnt(1)
	v_mul_f32_e32 v136, v75, v139
	v_mul_f32_e32 v137, v77, v133
	v_fmac_f32_e32 v136, v74, v138
	v_fmac_f32_e32 v137, v76, v132
	v_add_f32_e32 v136, v136, v137
	v_add_f32_e32 v71, v136, v52
	v_pk_mul_f32 v[136:137], v[72:73], v[84:85] op_sel_hi:[0,1]
	v_pk_mul_f32 v[52:53], v[72:73], v[82:83] op_sel_hi:[0,1]
	v_pk_fma_f32 v[136:137], v[126:127], v[70:71], v[136:137] op_sel_hi:[1,0,1]
	v_pk_fma_f32 v[52:53], v[124:125], v[70:71], v[52:53] op_sel_hi:[1,0,1]
	s_waitcnt lgkmcnt(0)
	v_mul_f32_e32 v125, v131, v137
	v_mul_f32_e32 v124, v129, v53
	v_fmac_f32_e32 v124, v128, v52
	v_fmac_f32_e32 v125, v130, v136
	v_add_f32_e32 v124, v124, v125
	v_add_f32_e32 v124, v71, v124
	ds_bpermute_b32 v125, v61, v124
	s_waitcnt lgkmcnt(0)
	v_add_f32_e32 v124, v124, v125
	ds_bpermute_b32 v125, v62, v124
	s_waitcnt lgkmcnt(0)
	v_add_f32_e32 v124, v124, v125
	ds_bpermute_b32 v125, v63, v124
	s_and_saveexec_b64 s[14:15], s[6:7]
	s_cbranch_execz .Lssd12_5_693
	ds_read_b32 v126, v64 offset:47360
	s_waitcnt lgkmcnt(1)
	v_add_f32_e32 v124, v124, v125
	v_fmac_f32_e32 v124, v66, v69
	s_waitcnt lgkmcnt(0)
	v_mul_f32_e32 v127, 0xbfb8aa3b, v126
	v_exp_f32_e32 v127, v127
	s_nop 0
	v_add_f32_e32 v125, 1.0, v127
	v_div_scale_f32 v127, s[2:3], v125, v125, v126
	v_rcp_f32_e32 v128, v127
	v_div_scale_f32 v129, vcc, v126, v125, v126
	v_fma_f32 v130, -v127, v128, 1.0
	v_fmac_f32_e32 v128, v130, v128
	v_mul_f32_e32 v130, v129, v128
	v_fma_f32 v131, -v127, v130, v129
	v_fmac_f32_e32 v130, v131, v128
	v_fma_f32 v127, -v127, v130, v129
	v_div_fmas_f32 v127, v127, v128, v130
	v_div_fixup_f32 v125, v127, v125, v126
	v_mul_f32_e32 v124, v124, v125
	ds_write_b32 v64, v124 offset:35072
.Lssd12_5_693:
	s_or_b64 exec, exec, s[14:15]
	v_mov_b32_e32 v124, s1
	ds_read_b32 v70, v124 offset:144
	ds_read_b32 v69, v64 offset:21504
	s_waitcnt lgkmcnt(1)
	v_mul_f32_e32 v124, v70, v68
	v_mul_f32_e32 v124, 0xbfb8aa3b, v124
	v_exp_f32_e32 v68, v124
	ds_read_b128 v[124:127], v67 offset:24576
	ds_read_b128 v[128:131], v67 offset:24592
	ds_read_b128 v[74:77], v67 offset:26624
	s_waitcnt lgkmcnt(3)
	v_mul_f32_e32 v70, v70, v69
	v_pk_mul_f32 v[82:83], v[56:57], v[68:69] op_sel_hi:[1,0]
	v_pk_mul_f32 v[84:85], v[58:59], v[68:69] op_sel_hi:[1,0]
	s_waitcnt lgkmcnt(2)
	v_pk_fma_f32 v[126:127], v[126:127], v[70:71], v[82:83] op_sel_hi:[1,0,1]
	v_pk_fma_f32 v[124:125], v[124:125], v[70:71], v[84:85] op_sel_hi:[1,0,1]
	ds_read_b128 v[56:59], v67 offset:24608
	ds_read_b128 v[78:81], v67 offset:24624
	ds_read_b128 v[82:85], v67 offset:26640
	s_waitcnt lgkmcnt(3)
	v_mul_f32_e32 v71, v75, v125
	v_mul_f32_e32 v72, v77, v127
	v_fmac_f32_e32 v71, v74, v124
	v_fmac_f32_e32 v72, v76, v126
	v_add_f32_e32 v71, v71, v72
	v_add_f32_e32 v71, 0, v71
	v_pk_mul_f32 v[134:135], v[134:135], v[68:69] op_sel_hi:[1,0]
	v_pk_mul_f32 v[54:55], v[54:55], v[68:69] op_sel_hi:[1,0]
	v_pk_fma_f32 v[130:131], v[70:71], v[130:131], v[134:135] op_sel_hi:[0,1,1]
	v_pk_fma_f32 v[128:129], v[70:71], v[128:129], v[54:55] op_sel_hi:[0,1,1]
	ds_read_b128 v[74:77], v67 offset:26656
	s_waitcnt lgkmcnt(1)
	v_mul_f32_e32 v134, v83, v129
	v_mul_f32_e32 v135, v85, v131
	v_fmac_f32_e32 v134, v82, v128
	v_fmac_f32_e32 v135, v84, v130
	v_add_f32_e32 v134, v134, v135
	v_add_f32_e32 v71, v134, v71
	v_pk_mul_f32 v[134:135], v[70:71], v[58:59] op_sel_hi:[0,1]
	v_pk_mul_f32 v[54:55], v[70:71], v[56:57] op_sel_hi:[0,1]
	v_pk_fma_f32 v[134:135], v[132:133], v[68:69], v[134:135] op_sel_hi:[1,0,1]
	v_pk_fma_f32 v[132:133], v[138:139], v[68:69], v[54:55] op_sel_hi:[1,0,1]
	ds_read_b128 v[54:57], v67 offset:26672
	s_waitcnt lgkmcnt(1)
	v_mul_f32_e32 v138, v75, v133
	v_mul_f32_e32 v139, v77, v135
	v_fmac_f32_e32 v138, v74, v132
	v_fmac_f32_e32 v139, v76, v134
	v_add_f32_e32 v138, v138, v139
	v_add_f32_e32 v67, v138, v71
	v_pk_mul_f32 v[138:139], v[70:71], v[80:81] op_sel_hi:[0,1]
	v_pk_mul_f32 v[58:59], v[70:71], v[78:79] op_sel_hi:[0,1]
	v_pk_fma_f32 v[138:139], v[136:137], v[68:69], v[138:139] op_sel_hi:[1,0,1]
	v_pk_fma_f32 v[136:137], v[52:53], v[68:69], v[58:59] op_sel_hi:[1,0,1]
	s_waitcnt lgkmcnt(0)
	v_mul_f32_e32 v53, v57, v139
	v_mul_f32_e32 v52, v55, v137
	v_fmac_f32_e32 v52, v54, v136
	v_fmac_f32_e32 v53, v56, v138
	v_add_f32_e32 v52, v52, v53
	v_add_f32_e32 v52, v67, v52
	ds_bpermute_b32 v53, v61, v52
	s_waitcnt lgkmcnt(0)
	v_add_f32_e32 v52, v52, v53
	ds_bpermute_b32 v53, v62, v52
	s_waitcnt lgkmcnt(0)
	v_add_f32_e32 v52, v52, v53
	ds_bpermute_b32 v53, v63, v52
	s_and_saveexec_b64 s[14:15], s[6:7]
	s_cbranch_execz .Lssd12_5_tail
	ds_read_b32 v54, v64 offset:50432
	s_waitcnt lgkmcnt(1)
	v_add_f32_e32 v52, v52, v53
	v_fmac_f32_e32 v52, v66, v69
	s_waitcnt lgkmcnt(0)
	v_mul_f32_e32 v55, 0xbfb8aa3b, v54
	v_exp_f32_e32 v55, v55
	s_nop 0
	v_add_f32_e32 v53, 1.0, v55
	v_div_scale_f32 v55, s[2:3], v53, v53, v54
	v_rcp_f32_e32 v56, v55
	v_div_scale_f32 v57, vcc, v54, v53, v54
	v_fma_f32 v58, -v55, v56, 1.0
	v_fmac_f32_e32 v56, v58, v56
	v_mul_f32_e32 v58, v57, v56
	v_fma_f32 v59, -v55, v58, v57
	v_fmac_f32_e32 v58, v59, v56
	v_fma_f32 v55, -v55, v58, v57
	v_div_fmas_f32 v55, v55, v56, v58
	v_div_fixup_f32 v53, v55, v53, v54
	v_mul_f32_e32 v52, v52, v53
	ds_write_b32 v64, v52 offset:38144
	s_branch .Lssd12_5_tail
.Lssd12_5_tail:
	s_or_b64 exec, exec, s[14:15]
	s_add_i32 s0, s0, 1
	s_add_i32 s1, s1, 4
	s_waitcnt lgkmcnt(0)
	v_lshl_add_u64 v[52:53], v[50:51], 0, s[8:9]
	s_add_u32 s8, s8, 0x8000
	s_addc_u32 s9, s9, 0
	v_add_co_u32_e32 v52, vcc, 0x2fb35000, v52
	s_add_u32 s12, s12, 4
	s_nop 0
	v_addc_co_u32_e32 v53, vcc, 0, v53, vcc
	s_addc_u32 s13, s13, 0
	global_store_dwordx4 v[52:53], v[124:127], off
	global_store_dwordx4 v[52:53], v[128:131], off offset:16
	global_store_dwordx4 v[52:53], v[132:135], off offset:32
	global_store_dwordx4 v[52:53], v[136:139], off offset:48
	s_add_u32 s10, s10, 4
	s_addc_u32 s11, s11, 0
	v_add_u32_e32 v64, 0x100, v64
.Lssd12_6:
	s_load_dword s16, s[12:13], 0x0
	s_load_dword s17, s[10:11], 0x0
	s_mul_i32 s2, s0, 0xab
	s_and_b32 s2, s2, 0xfe00
	v_add_u32_e32 v67, s2, v65
	s_waitcnt vmcnt(44)
	s_waitcnt lgkmcnt(0)
	v_mov_b32_e32 v52, s16
	v_mov_b32_e32 v66, s17
	v_mul_f32_e32 v52, 0x3fb8aa3b, v52
	v_exp_f32_e32 v68, v52
	v_mov_b32_e32 v52, s1
	ds_read_b32 v53, v52
	s_waitcnt lgkmcnt(0)
	v_mul_f32_e64 v52, v53, -v68
	v_mul_f32_e32 v52, 0x3fb8aa3b, v52
	v_exp_f32_e32 v58, v52
	ds_read_b32 v52, v64
	ds_read_b128 v[54:57], v67 offset:3072
	ds_read_b128 v[74:77], v67 offset:3088
	ds_read_b128 v[78:81], v67 offset:3104
	ds_read_b128 v[82:85], v67 offset:3120
	v_pk_mul_f32 v[182:183], v[182:183], v[58:59] op_sel_hi:[1,0]
	v_pk_mul_f32 v[86:87], v[180:181], v[58:59] op_sel_hi:[1,0]
	s_waitcnt lgkmcnt(4)
	v_mul_f32_e32 v70, v53, v52
	s_waitcnt lgkmcnt(3)
	v_pk_fma_f32 v[180:181], v[56:57], v[70:71], v[182:183] op_sel_hi:[1,0,1]
	v_pk_fma_f32 v[182:183], v[54:55], v[70:71], v[86:87] op_sel_hi:[1,0,1]
	ds_read_b128 v[54:57], v67 offset:5120
	v_pk_mul_f32 v[178:179], v[178:179], v[58:59] op_sel_hi:[1,0]
	s_waitcnt lgkmcnt(0)
	v_mul_f32_e32 v53, v55, v183
	v_fmac_f32_e32 v53, v54, v182
	v_mul_f32_e32 v54, v57, v181
	v_fmac_f32_e32 v54, v56, v180
	v_add_f32_e32 v53, v53, v54
	v_pk_mul_f32 v[54:55], v[176:177], v[58:59] op_sel_hi:[1,0]
	v_pk_fma_f32 v[176:177], v[70:71], v[76:77], v[178:179] op_sel_hi:[0,1,1]
	v_pk_fma_f32 v[178:179], v[70:71], v[74:75], v[54:55] op_sel_hi:[0,1,1]
	ds_read_b128 v[54:57], v67 offset:5136
	v_add_f32_e32 v53, 0, v53
	s_waitcnt lgkmcnt(0)
	v_mul_f32_e32 v55, v55, v179
	v_fmac_f32_e32 v55, v54, v178
	v_mul_f32_e32 v54, v57, v177
	v_fmac_f32_e32 v54, v56, v176
	v_add_f32_e32 v54, v55, v54
	v_add_f32_e32 v53, v54, v53
	v_pk_mul_f32 v[54:55], v[70:71], v[78:79] op_sel_hi:[0,1]
	v_pk_mul_f32 v[56:57], v[70:71], v[80:81] op_sel_hi:[0,1]
	v_pk_fma_f32 v[174:175], v[174:175], v[58:59], v[56:57] op_sel_hi:[1,0,1]
	v_pk_fma_f32 v[172:173], v[172:173], v[58:59], v[54:55] op_sel_hi:[1,0,1]
	ds_read_b128 v[54:57], v67 offset:5152
	s_waitcnt lgkmcnt(0)
	v_mul_f32_e32 v55, v55, v173
	v_fmac_f32_e32 v55, v54, v172
	v_mul_f32_e32 v54, v57, v175
	v_fmac_f32_e32 v54, v56, v174
	v_add_f32_e32 v54, v55, v54
	v_add_f32_e32 v53, v54, v53
	v_pk_mul_f32 v[54:55], v[70:71], v[82:83] op_sel_hi:[0,1]
	v_pk_mul_f32 v[56:57], v[70:71], v[84:85] op_sel_hi:[0,1]
	v_pk_fma_f32 v[170:171], v[170:171], v[58:59], v[56:57] op_sel_hi:[1,0,1]
	v_pk_fma_f32 v[168:169], v[168:169], v[58:59], v[54:55] op_sel_hi:[1,0,1]
	ds_read_b128 v[54:57], v67 offset:5168
	s_waitcnt lgkmcnt(0)
	v_mul_f32_e32 v55, v55, v169
	v_fmac_f32_e32 v55, v54, v168
	v_mul_f32_e32 v54, v57, v171
	v_fmac_f32_e32 v54, v56, v170
	v_add_f32_e32 v54, v55, v54
	v_add_f32_e32 v53, v53, v54
	ds_bpermute_b32 v54, v61, v53
	s_waitcnt lgkmcnt(0)
	v_add_f32_e32 v53, v53, v54
	ds_bpermute_b32 v54, v62, v53
	s_waitcnt lgkmcnt(0)
	v_add_f32_e32 v53, v53, v54
	ds_bpermute_b32 v54, v63, v53
	s_and_saveexec_b64 s[14:15], s[6:7]
	s_cbranch_execz .Lssd12_6_689
	ds_read_b32 v55, v64 offset:41216
	s_waitcnt lgkmcnt(1)
	v_add_f32_e32 v53, v53, v54
	v_fmac_f32_e32 v53, v66, v52
	s_waitcnt lgkmcnt(0)
	v_mul_f32_e32 v56, 0xbfb8aa3b, v55
	v_exp_f32_e32 v56, v56
	s_nop 0
	v_add_f32_e32 v54, 1.0, v56
	v_div_scale_f32 v56, s[2:3], v54, v54, v55
	v_rcp_f32_e32 v57, v56
	v_div_scale_f32 v52, vcc, v55, v54, v55
	v_fma_f32 v58, -v56, v57, 1.0
	v_fmac_f32_e32 v57, v58, v57
	v_mul_f32_e32 v58, v52, v57
	v_fma_f32 v59, -v56, v58, v52
	v_fmac_f32_e32 v58, v59, v57
	v_fma_f32 v52, -v56, v58, v52
	v_div_fmas_f32 v52, v52, v57, v58
	v_div_fixup_f32 v52, v52, v54, v55
	v_mul_f32_e32 v52, v53, v52
	ds_write_b32 v64, v52 offset:28928
.Lssd12_6_689:
	s_or_b64 exec, exec, s[14:15]
	v_mov_b32_e32 v52, s1
	ds_read_b32 v53, v52 offset:48
	ds_read_b32 v52, v64 offset:7168
	s_waitcnt lgkmcnt(1)
	v_mul_f32_e32 v54, v53, v68
	v_mul_f32_e32 v54, 0xbfb8aa3b, v54
	v_exp_f32_e32 v58, v54
	ds_read_b128 v[54:57], v67 offset:10240
	ds_read_b128 v[74:77], v67 offset:10256
	ds_read_b128 v[78:81], v67 offset:12288
	s_waitcnt lgkmcnt(3)
	v_mul_f32_e32 v70, v53, v52
	ds_read_b128 v[82:85], v67 offset:10272
	ds_read_b128 v[86:89], v67 offset:10288
	v_pk_mul_f32 v[180:181], v[180:181], v[58:59] op_sel_hi:[1,0]
	v_pk_mul_f32 v[182:183], v[182:183], v[58:59] op_sel_hi:[1,0]
	s_waitcnt lgkmcnt(4)
	v_pk_fma_f32 v[180:181], v[56:57], v[70:71], v[180:181] op_sel_hi:[1,0,1]
	v_pk_fma_f32 v[182:183], v[54:55], v[70:71], v[182:183] op_sel_hi:[1,0,1]
	ds_read_b128 v[54:57], v67 offset:12304
	s_waitcnt lgkmcnt(3)
	v_mul_f32_e32 v59, v81, v181
	v_fmac_f32_e32 v59, v80, v180
	v_pk_mul_f32 v[176:177], v[176:177], v[58:59] op_sel_hi:[1,0]
	v_pk_mul_f32 v[178:179], v[178:179], v[58:59] op_sel_hi:[1,0]
	v_pk_fma_f32 v[176:177], v[70:71], v[76:77], v[176:177] op_sel_hi:[0,1,1]
	v_pk_fma_f32 v[178:179], v[70:71], v[74:75], v[178:179] op_sel_hi:[0,1,1]
	s_waitcnt lgkmcnt(2)
	v_pk_mul_f32 v[74:75], v[70:71], v[84:85] op_sel_hi:[0,1]
	v_pk_mul_f32 v[76:77], v[70:71], v[82:83] op_sel_hi:[0,1]
	v_mul_f32_e32 v53, v79, v183
	v_pk_fma_f32 v[174:175], v[174:175], v[58:59], v[74:75] op_sel_hi:[1,0,1]
	v_pk_fma_f32 v[172:173], v[172:173], v[58:59], v[76:77] op_sel_hi:[1,0,1]
	ds_read_b128 v[74:77], v67 offset:12336
	s_waitcnt lgkmcnt(1)
	v_mul_f32_e32 v55, v55, v179
	v_fmac_f32_e32 v53, v78, v182
	v_fmac_f32_e32 v55, v54, v178
	v_mul_f32_e32 v54, v57, v177
	v_add_f32_e32 v53, v53, v59
	v_fmac_f32_e32 v54, v56, v176
	v_add_f32_e32 v53, 0, v53
	v_add_f32_e32 v54, v55, v54
	v_add_f32_e32 v53, v54, v53
	ds_read_b128 v[54:57], v67 offset:12320
	s_waitcnt lgkmcnt(0)
	v_mul_f32_e32 v55, v55, v173
	v_fmac_f32_e32 v55, v54, v172
	v_mul_f32_e32 v54, v57, v175
	v_fmac_f32_e32 v54, v56, v174
	v_add_f32_e32 v54, v55, v54
	v_add_f32_e32 v53, v54, v53
	v_pk_mul_f32 v[54:55], v[70:71], v[88:89] op_sel_hi:[0,1]
	v_pk_mul_f32 v[56:57], v[70:71], v[86:87] op_sel_hi:[0,1]
	v_pk_fma_f32 v[170:171], v[170:171], v[58:59], v[54:55] op_sel_hi:[1,0,1]
	v_pk_fma_f32 v[168:169], v[168:169], v[58:59], v[56:57] op_sel_hi:[1,0,1]
	v_mul_f32_e32 v55, v77, v171
	v_mul_f32_e32 v54, v75, v169
	v_fmac_f32_e32 v54, v74, v168
	v_fmac_f32_e32 v55, v76, v170
	v_add_f32_e32 v54, v54, v55
	v_add_f32_e32 v53, v53, v54
	ds_bpermute_b32 v54, v61, v53
	s_waitcnt lgkmcnt(0)
	v_add_f32_e32 v53, v53, v54
	ds_bpermute_b32 v54, v62, v53
	s_waitcnt lgkmcnt(0)
	v_add_f32_e32 v53, v53, v54
	ds_bpermute_b32 v54, v63, v53
	s_and_saveexec_b64 s[14:15], s[6:7]
	s_cbranch_execz .Lssd12_6_691
	ds_read_b32 v55, v64 offset:44288
	s_waitcnt lgkmcnt(1)
	v_add_f32_e32 v53, v53, v54
	v_fmac_f32_e32 v53, v66, v52
	s_waitcnt lgkmcnt(0)
	v_mul_f32_e32 v56, 0xbfb8aa3b, v55
	v_exp_f32_e32 v56, v56
	s_nop 0
	v_add_f32_e32 v54, 1.0, v56
	v_div_scale_f32 v56, s[2:3], v54, v54, v55
	v_rcp_f32_e32 v57, v56
	v_div_scale_f32 v52, vcc, v55, v54, v55
	v_fma_f32 v58, -v56, v57, 1.0
	v_fmac_f32_e32 v57, v58, v57
	v_mul_f32_e32 v58, v52, v57
	v_fma_f32 v59, -v56, v58, v52
	v_fmac_f32_e32 v58, v59, v57
	v_fma_f32 v52, -v56, v58, v52
	v_div_fmas_f32 v52, v52, v57, v58
	v_div_fixup_f32 v52, v52, v54, v55
	v_mul_f32_e32 v52, v53, v52
	ds_write_b32 v64, v52 offset:32000
.Lssd12_6_691:
	s_or_b64 exec, exec, s[14:15]
	v_mov_b32_e32 v52, s1
	ds_read_b32 v56, v52 offset:96
	ds_read_b32 v69, v64 offset:14336
	s_waitcnt lgkmcnt(1)
	v_mul_f32_e32 v52, v56, v68
	v_mul_f32_e32 v52, 0xbfb8aa3b, v52
	v_exp_f32_e32 v70, v52
	ds_read_b128 v[52:55], v67 offset:17408
	ds_read_b128 v[74:77], v67 offset:17424
	ds_read_b128 v[78:81], v67 offset:19456
	s_waitcnt lgkmcnt(3)
	v_mul_f32_e32 v72, v56, v69
	v_pk_mul_f32 v[56:57], v[180:181], v[70:71] op_sel_hi:[1,0]
	v_pk_mul_f32 v[58:59], v[182:183], v[70:71] op_sel_hi:[1,0]
	s_waitcnt lgkmcnt(2)
	v_pk_fma_f32 v[56:57], v[54:55], v[72:73], v[56:57] op_sel_hi:[1,0,1]
	v_pk_fma_f32 v[58:59], v[52:53], v[72:73], v[58:59] op_sel_hi:[1,0,1]
	s_waitcnt lgkmcnt(0)
	v_mul_f32_e32 v53, v81, v57
	v_mul_f32_e32 v52, v79, v59
	ds_read_b128 v[180:183], v67 offset:17440
	ds_read_b128 v[82:85], v67 offset:17456
	ds_read_b128 v[86:89], v67 offset:19472
	v_fmac_f32_e32 v52, v78, v58
	v_fmac_f32_e32 v53, v80, v56
	v_add_f32_e32 v52, v52, v53
	v_add_f32_e32 v71, 0, v52
	v_pk_mul_f32 v[176:177], v[176:177], v[70:71] op_sel_hi:[1,0]
	v_pk_mul_f32 v[52:53], v[178:179], v[70:71] op_sel_hi:[1,0]
	v_pk_fma_f32 v[178:179], v[72:73], v[76:77], v[176:177] op_sel_hi:[0,1,1]
	v_pk_fma_f32 v[54:55], v[72:73], v[74:75], v[52:53] op_sel_hi:[0,1,1]
	ds_read_b128 v[74:77], v67 offset:19488
	s_waitcnt lgkmcnt(1)
	v_mul_f32_e32 v176, v87, v55
	v_mul_f32_e32 v177, v89, v179
	v_fmac_f32_e32 v176, v86, v54
	v_fmac_f32_e32 v177, v88, v178
	v_add_f32_e32 v176, v176, v177
	v_add_f32_e32 v52, v176, v71
	v_pk_mul_f32 v[176:177], v[72:73], v[182:183] op_sel_hi:[0,1]
	v_pk_mul_f32 v[180:181], v[72:73], v[180:181] op_sel_hi:[0,1]
	v_pk_fma_f32 v[176:177], v[174:175], v[70:71], v[176:177] op_sel_hi:[1,0,1]
	v_pk_fma_f32 v[182:183], v[172:173], v[70:71], v[180:181] op_sel_hi:[1,0,1]
	ds_read_b128 v[172:175], v67 offset:19504
	s_waitcnt lgkmcnt(1)
	v_mul_f32_e32 v180, v75, v183
	v_mul_f32_e32 v181, v77, v177
	v_fmac_f32_e32 v180, v74, v182
	v_fmac_f32_e32 v181, v76, v176
	v_add_f32_e32 v180, v180, v181
	v_add_f32_e32 v71, v180, v52
	v_pk_mul_f32 v[180:181], v[72:73], v[84:85] op_sel_hi:[0,1]
	v_pk_mul_f32 v[52:53], v[72:73], v[82:83] op_sel_hi:[0,1]
	v_pk_fma_f32 v[180:181], v[170:171], v[70:71], v[180:181] op_sel_hi:[1,0,1]
	v_pk_fma_f32 v[52:53], v[168:169], v[70:71], v[52:53] op_sel_hi:[1,0,1]
	s_waitcnt lgkmcnt(0)
	v_mul_f32_e32 v169, v175, v181
	v_mul_f32_e32 v168, v173, v53
	v_fmac_f32_e32 v168, v172, v52
	v_fmac_f32_e32 v169, v174, v180
	v_add_f32_e32 v168, v168, v169
	v_add_f32_e32 v168, v71, v168
	ds_bpermute_b32 v169, v61, v168
	s_waitcnt lgkmcnt(0)
	v_add_f32_e32 v168, v168, v169
	ds_bpermute_b32 v169, v62, v168
	s_waitcnt lgkmcnt(0)
	v_add_f32_e32 v168, v168, v169
	ds_bpermute_b32 v169, v63, v168
	s_and_saveexec_b64 s[14:15], s[6:7]
	s_cbranch_execz .Lssd12_6_693
	ds_read_b32 v170, v64 offset:47360
	s_waitcnt lgkmcnt(1)
	v_add_f32_e32 v168, v168, v169
	v_fmac_f32_e32 v168, v66, v69
	s_waitcnt lgkmcnt(0)
	v_mul_f32_e32 v171, 0xbfb8aa3b, v170
	v_exp_f32_e32 v171, v171
	s_nop 0
	v_add_f32_e32 v169, 1.0, v171
	v_div_scale_f32 v171, s[2:3], v169, v169, v170
	v_rcp_f32_e32 v172, v171
	v_div_scale_f32 v173, vcc, v170, v169, v170
	v_fma_f32 v174, -v171, v172, 1.0
	v_fmac_f32_e32 v172, v174, v172
	v_mul_f32_e32 v174, v173, v172
	v_fma_f32 v175, -v171, v174, v173
	v_fmac_f32_e32 v174, v175, v172
	v_fma_f32 v171, -v171, v174, v173
	v_div_fmas_f32 v171, v171, v172, v174
	v_div_fixup_f32 v169, v171, v169, v170
	v_mul_f32_e32 v168, v168, v169
	ds_write_b32 v64, v168 offset:35072
.Lssd12_6_693:
	s_or_b64 exec, exec, s[14:15]
	v_mov_b32_e32 v168, s1
	ds_read_b32 v70, v168 offset:144
	ds_read_b32 v69, v64 offset:21504
	s_waitcnt lgkmcnt(1)
	v_mul_f32_e32 v168, v70, v68
	v_mul_f32_e32 v168, 0xbfb8aa3b, v168
	v_exp_f32_e32 v68, v168
	ds_read_b128 v[168:171], v67 offset:24576
	ds_read_b128 v[172:175], v67 offset:24592
	ds_read_b128 v[74:77], v67 offset:26624
	s_waitcnt lgkmcnt(3)
	v_mul_f32_e32 v70, v70, v69
	v_pk_mul_f32 v[82:83], v[56:57], v[68:69] op_sel_hi:[1,0]
	v_pk_mul_f32 v[84:85], v[58:59], v[68:69] op_sel_hi:[1,0]
	s_waitcnt lgkmcnt(2)
	v_pk_fma_f32 v[170:171], v[170:171], v[70:71], v[82:83] op_sel_hi:[1,0,1]
	v_pk_fma_f32 v[168:169], v[168:169], v[70:71], v[84:85] op_sel_hi:[1,0,1]
	ds_read_b128 v[56:59], v67 offset:24608
	ds_read_b128 v[78:81], v67 offset:24624
	ds_read_b128 v[82:85], v67 offset:26640
	s_waitcnt lgkmcnt(3)
	v_mul_f32_e32 v71, v75, v169
	v_mul_f32_e32 v72, v77, v171
	v_fmac_f32_e32 v71, v74, v168
	v_fmac_f32_e32 v72, v76, v170
	v_add_f32_e32 v71, v71, v72
	v_add_f32_e32 v71, 0, v71
	v_pk_mul_f32 v[178:179], v[178:179], v[68:69] op_sel_hi:[1,0]
	v_pk_mul_f32 v[54:55], v[54:55], v[68:69] op_sel_hi:[1,0]
	v_pk_fma_f32 v[174:175], v[70:71], v[174:175], v[178:179] op_sel_hi:[0,1,1]
	v_pk_fma_f32 v[172:173], v[70:71], v[172:173], v[54:55] op_sel_hi:[0,1,1]
	ds_read_b128 v[74:77], v67 offset:26656
	s_waitcnt lgkmcnt(1)
	v_mul_f32_e32 v178, v83, v173
	v_mul_f32_e32 v179, v85, v175
	v_fmac_f32_e32 v178, v82, v172
	v_fmac_f32_e32 v179, v84, v174
	v_add_f32_e32 v178, v178, v179
	v_add_f32_e32 v71, v178, v71
	v_pk_mul_f32 v[178:179], v[70:71], v[58:59] op_sel_hi:[0,1]
	v_pk_mul_f32 v[54:55], v[70:71], v[56:57] op_sel_hi:[0,1]
	v_pk_fma_f32 v[178:179], v[176:177], v[68:69], v[178:179] op_sel_hi:[1,0,1]
	v_pk_fma_f32 v[176:177], v[182:183], v[68:69], v[54:55] op_sel_hi:[1,0,1]
	ds_read_b128 v[54:57], v67 offset:26672
	s_waitcnt lgkmcnt(1)
	v_mul_f32_e32 v182, v75, v177
	v_mul_f32_e32 v183, v77, v179
	v_fmac_f32_e32 v182, v74, v176
	v_fmac_f32_e32 v183, v76, v178
	v_add_f32_e32 v182, v182, v183
	v_add_f32_e32 v67, v182, v71
	v_pk_mul_f32 v[182:183], v[70:71], v[80:81] op_sel_hi:[0,1]
	v_pk_mul_f32 v[58:59], v[70:71], v[78:79] op_sel_hi:[0,1]
	v_pk_fma_f32 v[182:183], v[180:181], v[68:69], v[182:183] op_sel_hi:[1,0,1]
	v_pk_fma_f32 v[180:181], v[52:53], v[68:69], v[58:59] op_sel_hi:[1,0,1]
	s_waitcnt lgkmcnt(0)
	v_mul_f32_e32 v53, v57, v183
	v_mul_f32_e32 v52, v55, v181
	v_fmac_f32_e32 v52, v54, v180
	v_fmac_f32_e32 v53, v56, v182
	v_add_f32_e32 v52, v52, v53
	v_add_f32_e32 v52, v67, v52
	ds_bpermute_b32 v53, v61, v52
	s_waitcnt lgkmcnt(0)
	v_add_f32_e32 v52, v52, v53
	ds_bpermute_b32 v53, v62, v52
	s_waitcnt lgkmcnt(0)
	v_add_f32_e32 v52, v52, v53
	ds_bpermute_b32 v53, v63, v52
	s_and_saveexec_b64 s[14:15], s[6:7]
	s_cbranch_execz .Lssd12_6_tail
	ds_read_b32 v54, v64 offset:50432
	s_waitcnt lgkmcnt(1)
	v_add_f32_e32 v52, v52, v53
	v_fmac_f32_e32 v52, v66, v69
	s_waitcnt lgkmcnt(0)
	v_mul_f32_e32 v55, 0xbfb8aa3b, v54
	v_exp_f32_e32 v55, v55
	s_nop 0
	v_add_f32_e32 v53, 1.0, v55
	v_div_scale_f32 v55, s[2:3], v53, v53, v54
	v_rcp_f32_e32 v56, v55
	v_div_scale_f32 v57, vcc, v54, v53, v54
	v_fma_f32 v58, -v55, v56, 1.0
	v_fmac_f32_e32 v56, v58, v56
	v_mul_f32_e32 v58, v57, v56
	v_fma_f32 v59, -v55, v58, v57
	v_fmac_f32_e32 v58, v59, v56
	v_fma_f32 v55, -v55, v58, v57
	v_div_fmas_f32 v55, v55, v56, v58
	v_div_fixup_f32 v53, v55, v53, v54
	v_mul_f32_e32 v52, v52, v53
	ds_write_b32 v64, v52 offset:38144
	s_branch .Lssd12_6_tail
.Lssd12_6_tail:
	s_or_b64 exec, exec, s[14:15]
	s_add_i32 s0, s0, 1
	s_add_i32 s1, s1, 4
	s_waitcnt lgkmcnt(0)
	v_lshl_add_u64 v[52:53], v[50:51], 0, s[8:9]
	s_add_u32 s8, s8, 0x8000
	s_addc_u32 s9, s9, 0
	v_add_co_u32_e32 v52, vcc, 0x2fb35000, v52
	s_add_u32 s12, s12, 4
	s_nop 0
	v_addc_co_u32_e32 v53, vcc, 0, v53, vcc
	s_addc_u32 s13, s13, 0
	global_store_dwordx4 v[52:53], v[168:171], off
	global_store_dwordx4 v[52:53], v[172:175], off offset:16
	global_store_dwordx4 v[52:53], v[176:179], off offset:32
	global_store_dwordx4 v[52:53], v[180:183], off offset:48
	s_add_u32 s10, s10, 4
	s_addc_u32 s11, s11, 0
	v_add_u32_e32 v64, 0x100, v64
.Lssd12_7:
	s_load_dword s16, s[12:13], 0x0
	s_load_dword s17, s[10:11], 0x0
	s_mul_i32 s2, s0, 0xab
	s_and_b32 s2, s2, 0xfe00
	v_add_u32_e32 v67, s2, v65
	s_waitcnt vmcnt(44)
	s_waitcnt lgkmcnt(0)
	v_mov_b32_e32 v52, s16
	v_mov_b32_e32 v66, s17
	v_mul_f32_e32 v52, 0x3fb8aa3b, v52
	v_exp_f32_e32 v68, v52
	v_mov_b32_e32 v52, s1
	ds_read_b32 v53, v52
	s_waitcnt lgkmcnt(0)
	v_mul_f32_e64 v52, v53, -v68
	v_mul_f32_e32 v52, 0x3fb8aa3b, v52
	v_exp_f32_e32 v58, v52
	ds_read_b32 v52, v64
	ds_read_b128 v[54:57], v67 offset:3072
	ds_read_b128 v[74:77], v67 offset:3088
	ds_read_b128 v[78:81], v67 offset:3104
	ds_read_b128 v[82:85], v67 offset:3120
	v_pk_mul_f32 v[210:211], v[210:211], v[58:59] op_sel_hi:[1,0]
	v_pk_mul_f32 v[86:87], v[208:209], v[58:59] op_sel_hi:[1,0]
	s_waitcnt lgkmcnt(4)
	v_mul_f32_e32 v70, v53, v52
	s_waitcnt lgkmcnt(3)
	v_pk_fma_f32 v[208:209], v[56:57], v[70:71], v[210:211] op_sel_hi:[1,0,1]
	v_pk_fma_f32 v[210:211], v[54:55], v[70:71], v[86:87] op_sel_hi:[1,0,1]
	ds_read_b128 v[54:57], v67 offset:5120
	v_pk_mul_f32 v[206:207], v[206:207], v[58:59] op_sel_hi:[1,0]
	s_waitcnt lgkmcnt(0)
	v_mul_f32_e32 v53, v55, v211
	v_fmac_f32_e32 v53, v54, v210
	v_mul_f32_e32 v54, v57, v209
	v_fmac_f32_e32 v54, v56, v208
	v_add_f32_e32 v53, v53, v54
	v_pk_mul_f32 v[54:55], v[204:205], v[58:59] op_sel_hi:[1,0]
	v_pk_fma_f32 v[204:205], v[70:71], v[76:77], v[206:207] op_sel_hi:[0,1,1]
	v_pk_fma_f32 v[206:207], v[70:71], v[74:75], v[54:55] op_sel_hi:[0,1,1]
	ds_read_b128 v[54:57], v67 offset:5136
	v_add_f32_e32 v53, 0, v53
	s_waitcnt lgkmcnt(0)
	v_mul_f32_e32 v55, v55, v207
	v_fmac_f32_e32 v55, v54, v206
	v_mul_f32_e32 v54, v57, v205
	v_fmac_f32_e32 v54, v56, v204
	v_add_f32_e32 v54, v55, v54
	v_add_f32_e32 v53, v54, v53
	v_pk_mul_f32 v[54:55], v[70:71], v[78:79] op_sel_hi:[0,1]
	v_pk_mul_f32 v[56:57], v[70:71], v[80:81] op_sel_hi:[0,1]
	v_pk_fma_f32 v[202:203], v[202:203], v[58:59], v[56:57] op_sel_hi:[1,0,1]
	v_pk_fma_f32 v[200:201], v[200:201], v[58:59], v[54:55] op_sel_hi:[1,0,1]
	ds_read_b128 v[54:57], v67 offset:5152
	s_waitcnt lgkmcnt(0)
	v_mul_f32_e32 v55, v55, v201
	v_fmac_f32_e32 v55, v54, v200
	v_mul_f32_e32 v54, v57, v203
	v_fmac_f32_e32 v54, v56, v202
	v_add_f32_e32 v54, v55, v54
	v_add_f32_e32 v53, v54, v53
	v_pk_mul_f32 v[54:55], v[70:71], v[82:83] op_sel_hi:[0,1]
	v_pk_mul_f32 v[56:57], v[70:71], v[84:85] op_sel_hi:[0,1]
	v_pk_fma_f32 v[198:199], v[198:199], v[58:59], v[56:57] op_sel_hi:[1,0,1]
	v_pk_fma_f32 v[196:197], v[196:197], v[58:59], v[54:55] op_sel_hi:[1,0,1]
	ds_read_b128 v[54:57], v67 offset:5168
	s_waitcnt lgkmcnt(0)
	v_mul_f32_e32 v55, v55, v197
	v_fmac_f32_e32 v55, v54, v196
	v_mul_f32_e32 v54, v57, v199
	v_fmac_f32_e32 v54, v56, v198
	v_add_f32_e32 v54, v55, v54
	v_add_f32_e32 v53, v53, v54
	ds_bpermute_b32 v54, v61, v53
	s_waitcnt lgkmcnt(0)
	v_add_f32_e32 v53, v53, v54
	ds_bpermute_b32 v54, v62, v53
	s_waitcnt lgkmcnt(0)
	v_add_f32_e32 v53, v53, v54
	ds_bpermute_b32 v54, v63, v53
	s_and_saveexec_b64 s[14:15], s[6:7]
	s_cbranch_execz .Lssd12_7_689
	ds_read_b32 v55, v64 offset:41216
	s_waitcnt lgkmcnt(1)
	v_add_f32_e32 v53, v53, v54
	v_fmac_f32_e32 v53, v66, v52
	s_waitcnt lgkmcnt(0)
	v_mul_f32_e32 v56, 0xbfb8aa3b, v55
	v_exp_f32_e32 v56, v56
	s_nop 0
	v_add_f32_e32 v54, 1.0, v56
	v_div_scale_f32 v56, s[2:3], v54, v54, v55
	v_rcp_f32_e32 v57, v56
	v_div_scale_f32 v52, vcc, v55, v54, v55
	v_fma_f32 v58, -v56, v57, 1.0
	v_fmac_f32_e32 v57, v58, v57
	v_mul_f32_e32 v58, v52, v57
	v_fma_f32 v59, -v56, v58, v52
	v_fmac_f32_e32 v58, v59, v57
	v_fma_f32 v52, -v56, v58, v52
	v_div_fmas_f32 v52, v52, v57, v58
	v_div_fixup_f32 v52, v52, v54, v55
	v_mul_f32_e32 v52, v53, v52
	ds_write_b32 v64, v52 offset:28928
.Lssd12_7_689:
	s_or_b64 exec, exec, s[14:15]
	v_mov_b32_e32 v52, s1
	ds_read_b32 v53, v52 offset:48
	ds_read_b32 v52, v64 offset:7168
	s_waitcnt lgkmcnt(1)
	v_mul_f32_e32 v54, v53, v68
	v_mul_f32_e32 v54, 0xbfb8aa3b, v54
	v_exp_f32_e32 v58, v54
	ds_read_b128 v[54:57], v67 offset:10240
	ds_read_b128 v[74:77], v67 offset:10256
	ds_read_b128 v[78:81], v67 offset:12288
	s_waitcnt lgkmcnt(3)
	v_mul_f32_e32 v70, v53, v52
	ds_read_b128 v[82:85], v67 offset:10272
	ds_read_b128 v[86:89], v67 offset:10288
	v_pk_mul_f32 v[208:209], v[208:209], v[58:59] op_sel_hi:[1,0]
	v_pk_mul_f32 v[210:211], v[210:211], v[58:59] op_sel_hi:[1,0]
	s_waitcnt lgkmcnt(4)
	v_pk_fma_f32 v[208:209], v[56:57], v[70:71], v[208:209] op_sel_hi:[1,0,1]
	v_pk_fma_f32 v[210:211], v[54:55], v[70:71], v[210:211] op_sel_hi:[1,0,1]
	ds_read_b128 v[54:57], v67 offset:12304
	s_waitcnt lgkmcnt(3)
	v_mul_f32_e32 v59, v81, v209
	v_fmac_f32_e32 v59, v80, v208
	v_pk_mul_f32 v[204:205], v[204:205], v[58:59] op_sel_hi:[1,0]
	v_pk_mul_f32 v[206:207], v[206:207], v[58:59] op_sel_hi:[1,0]
	v_pk_fma_f32 v[204:205], v[70:71], v[76:77], v[204:205] op_sel_hi:[0,1,1]
	v_pk_fma_f32 v[206:207], v[70:71], v[74:75], v[206:207] op_sel_hi:[0,1,1]
	s_waitcnt lgkmcnt(2)
	v_pk_mul_f32 v[74:75], v[70:71], v[84:85] op_sel_hi:[0,1]
	v_pk_mul_f32 v[76:77], v[70:71], v[82:83] op_sel_hi:[0,1]
	v_mul_f32_e32 v53, v79, v211
	v_pk_fma_f32 v[202:203], v[202:203], v[58:59], v[74:75] op_sel_hi:[1,0,1]
	v_pk_fma_f32 v[200:201], v[200:201], v[58:59], v[76:77] op_sel_hi:[1,0,1]
	ds_read_b128 v[74:77], v67 offset:12336
	s_waitcnt lgkmcnt(1)
	v_mul_f32_e32 v55, v55, v207
	v_fmac_f32_e32 v53, v78, v210
	v_fmac_f32_e32 v55, v54, v206
	v_mul_f32_e32 v54, v57, v205
	v_add_f32_e32 v53, v53, v59
	v_fmac_f32_e32 v54, v56, v204
	v_add_f32_e32 v53, 0, v53
	v_add_f32_e32 v54, v55, v54
	v_add_f32_e32 v53, v54, v53
	ds_read_b128 v[54:57], v67 offset:12320
	s_waitcnt lgkmcnt(0)
	v_mul_f32_e32 v55, v55, v201
	v_fmac_f32_e32 v55, v54, v200
	v_mul_f32_e32 v54, v57, v203
	v_fmac_f32_e32 v54, v56, v202
	v_add_f32_e32 v54, v55, v54
	v_add_f32_e32 v53, v54, v53
	v_pk_mul_f32 v[54:55], v[70:71], v[88:89] op_sel_hi:[0,1]
	v_pk_mul_f32 v[56:57], v[70:71], v[86:87] op_sel_hi:[0,1]
	v_pk_fma_f32 v[198:199], v[198:199], v[58:59], v[54:55] op_sel_hi:[1,0,1]
	v_pk_fma_f32 v[196:197], v[196:197], v[58:59], v[56:57] op_sel_hi:[1,0,1]
	v_mul_f32_e32 v55, v77, v199
	v_mul_f32_e32 v54, v75, v197
	v_fmac_f32_e32 v54, v74, v196
	v_fmac_f32_e32 v55, v76, v198
	v_add_f32_e32 v54, v54, v55
	v_add_f32_e32 v53, v53, v54
	ds_bpermute_b32 v54, v61, v53
	s_waitcnt lgkmcnt(0)
	v_add_f32_e32 v53, v53, v54
	ds_bpermute_b32 v54, v62, v53
	s_waitcnt lgkmcnt(0)
	v_add_f32_e32 v53, v53, v54
	ds_bpermute_b32 v54, v63, v53
	s_and_saveexec_b64 s[14:15], s[6:7]
	s_cbranch_execz .Lssd12_7_691
	ds_read_b32 v55, v64 offset:44288
	s_waitcnt lgkmcnt(1)
	v_add_f32_e32 v53, v53, v54
	v_fmac_f32_e32 v53, v66, v52
	s_waitcnt lgkmcnt(0)
	v_mul_f32_e32 v56, 0xbfb8aa3b, v55
	v_exp_f32_e32 v56, v56
	s_nop 0
	v_add_f32_e32 v54, 1.0, v56
	v_div_scale_f32 v56, s[2:3], v54, v54, v55
	v_rcp_f32_e32 v57, v56
	v_div_scale_f32 v52, vcc, v55, v54, v55
	v_fma_f32 v58, -v56, v57, 1.0
	v_fmac_f32_e32 v57, v58, v57
	v_mul_f32_e32 v58, v52, v57
	v_fma_f32 v59, -v56, v58, v52
	v_fmac_f32_e32 v58, v59, v57
	v_fma_f32 v52, -v56, v58, v52
	v_div_fmas_f32 v52, v52, v57, v58
	v_div_fixup_f32 v52, v52, v54, v55
	v_mul_f32_e32 v52, v53, v52
	ds_write_b32 v64, v52 offset:32000
.Lssd12_7_691:
	s_or_b64 exec, exec, s[14:15]
	v_mov_b32_e32 v52, s1
	ds_read_b32 v56, v52 offset:96
	ds_read_b32 v69, v64 offset:14336
	s_waitcnt lgkmcnt(1)
	v_mul_f32_e32 v52, v56, v68
	v_mul_f32_e32 v52, 0xbfb8aa3b, v52
	v_exp_f32_e32 v70, v52
	ds_read_b128 v[52:55], v67 offset:17408
	ds_read_b128 v[74:77], v67 offset:17424
	ds_read_b128 v[78:81], v67 offset:19456
	s_waitcnt lgkmcnt(3)
	v_mul_f32_e32 v72, v56, v69
	v_pk_mul_f32 v[56:57], v[208:209], v[70:71] op_sel_hi:[1,0]
	v_pk_mul_f32 v[58:59], v[210:211], v[70:71] op_sel_hi:[1,0]
	s_waitcnt lgkmcnt(2)
	v_pk_fma_f32 v[56:57], v[54:55], v[72:73], v[56:57] op_sel_hi:[1,0,1]
	v_pk_fma_f32 v[58:59], v[52:53], v[72:73], v[58:59] op_sel_hi:[1,0,1]
	s_waitcnt lgkmcnt(0)
	v_mul_f32_e32 v53, v81, v57
	v_mul_f32_e32 v52, v79, v59
	ds_read_b128 v[208:211], v67 offset:17440
	ds_read_b128 v[82:85], v67 offset:17456
	ds_read_b128 v[86:89], v67 offset:19472
	v_fmac_f32_e32 v52, v78, v58
	v_fmac_f32_e32 v53, v80, v56
	v_add_f32_e32 v52, v52, v53
	v_add_f32_e32 v71, 0, v52
	v_pk_mul_f32 v[204:205], v[204:205], v[70:71] op_sel_hi:[1,0]
	v_pk_mul_f32 v[52:53], v[206:207], v[70:71] op_sel_hi:[1,0]
	v_pk_fma_f32 v[206:207], v[72:73], v[76:77], v[204:205] op_sel_hi:[0,1,1]
	v_pk_fma_f32 v[54:55], v[72:73], v[74:75], v[52:53] op_sel_hi:[0,1,1]
	ds_read_b128 v[74:77], v67 offset:19488
	s_waitcnt lgkmcnt(1)
	v_mul_f32_e32 v204, v87, v55
	v_mul_f32_e32 v205, v89, v207
	v_fmac_f32_e32 v204, v86, v54
	v_fmac_f32_e32 v205, v88, v206
	v_add_f32_e32 v204, v204, v205
	v_add_f32_e32 v52, v204, v71
	v_pk_mul_f32 v[204:205], v[72:73], v[210:211] op_sel_hi:[0,1]
	v_pk_mul_f32 v[208:209], v[72:73], v[208:209] op_sel_hi:[0,1]
	v_pk_fma_f32 v[204:205], v[202:203], v[70:71], v[204:205] op_sel_hi:[1,0,1]
	v_pk_fma_f32 v[210:211], v[200:201], v[70:71], v[208:209] op_sel_hi:[1,0,1]
	ds_read_b128 v[200:203], v67 offset:19504
	s_waitcnt lgkmcnt(1)
	v_mul_f32_e32 v208, v75, v211
	v_mul_f32_e32 v209, v77, v205
	v_fmac_f32_e32 v208, v74, v210
	v_fmac_f32_e32 v209, v76, v204
	v_add_f32_e32 v208, v208, v209
	v_add_f32_e32 v71, v208, v52
	v_pk_mul_f32 v[208:209], v[72:73], v[84:85] op_sel_hi:[0,1]
	v_pk_mul_f32 v[52:53], v[72:73], v[82:83] op_sel_hi:[0,1]
	v_pk_fma_f32 v[208:209], v[198:199], v[70:71], v[208:209] op_sel_hi:[1,0,1]
	v_pk_fma_f32 v[52:53], v[196:197], v[70:71], v[52:53] op_sel_hi:[1,0,1]
	s_waitcnt lgkmcnt(0)
	v_mul_f32_e32 v197, v203, v209
	v_mul_f32_e32 v196, v201, v53
	v_fmac_f32_e32 v196, v200, v52
	v_fmac_f32_e32 v197, v202, v208
	v_add_f32_e32 v196, v196, v197
	v_add_f32_e32 v196, v71, v196
	ds_bpermute_b32 v197, v61, v196
	s_waitcnt lgkmcnt(0)
	v_add_f32_e32 v196, v196, v197
	ds_bpermute_b32 v197, v62, v196
	s_waitcnt lgkmcnt(0)
	v_add_f32_e32 v196, v196, v197
	ds_bpermute_b32 v197, v63, v196
	s_and_saveexec_b64 s[14:15], s[6:7]
	s_cbranch_execz .Lssd12_7_693
	ds_read_b32 v198, v64 offset:47360
	s_waitcnt lgkmcnt(1)
	v_add_f32_e32 v196, v196, v197
	v_fmac_f32_e32 v196, v66, v69
	s_waitcnt lgkmcnt(0)
	v_mul_f32_e32 v199, 0xbfb8aa3b, v198
	v_exp_f32_e32 v199, v199
	s_nop 0
	v_add_f32_e32 v197, 1.0, v199
	v_div_scale_f32 v199, s[2:3], v197, v197, v198
	v_rcp_f32_e32 v200, v199
	v_div_scale_f32 v201, vcc, v198, v197, v198
	v_fma_f32 v202, -v199, v200, 1.0
	v_fmac_f32_e32 v200, v202, v200
	v_mul_f32_e32 v202, v201, v200
	v_fma_f32 v203, -v199, v202, v201
	v_fmac_f32_e32 v202, v203, v200
	v_fma_f32 v199, -v199, v202, v201
	v_div_fmas_f32 v199, v199, v200, v202
	v_div_fixup_f32 v197, v199, v197, v198
	v_mul_f32_e32 v196, v196, v197
	ds_write_b32 v64, v196 offset:35072
.Lssd12_7_693:
	s_or_b64 exec, exec, s[14:15]
	v_mov_b32_e32 v196, s1
	ds_read_b32 v70, v196 offset:144
	ds_read_b32 v69, v64 offset:21504
	s_waitcnt lgkmcnt(1)
	v_mul_f32_e32 v196, v70, v68
	v_mul_f32_e32 v196, 0xbfb8aa3b, v196
	v_exp_f32_e32 v68, v196
	ds_read_b128 v[196:199], v67 offset:24576
	ds_read_b128 v[200:203], v67 offset:24592
	ds_read_b128 v[74:77], v67 offset:26624
	s_waitcnt lgkmcnt(3)
	v_mul_f32_e32 v70, v70, v69
	v_pk_mul_f32 v[82:83], v[56:57], v[68:69] op_sel_hi:[1,0]
	v_pk_mul_f32 v[84:85], v[58:59], v[68:69] op_sel_hi:[1,0]
	s_waitcnt lgkmcnt(2)
	v_pk_fma_f32 v[198:199], v[198:199], v[70:71], v[82:83] op_sel_hi:[1,0,1]
	v_pk_fma_f32 v[196:197], v[196:197], v[70:71], v[84:85] op_sel_hi:[1,0,1]
	ds_read_b128 v[56:59], v67 offset:24608
	ds_read_b128 v[78:81], v67 offset:24624
	ds_read_b128 v[82:85], v67 offset:26640
	s_waitcnt lgkmcnt(3)
	v_mul_f32_e32 v71, v75, v197
	v_mul_f32_e32 v72, v77, v199
	v_fmac_f32_e32 v71, v74, v196
	v_fmac_f32_e32 v72, v76, v198
	v_add_f32_e32 v71, v71, v72
	v_add_f32_e32 v71, 0, v71
	v_pk_mul_f32 v[206:207], v[206:207], v[68:69] op_sel_hi:[1,0]
	v_pk_mul_f32 v[54:55], v[54:55], v[68:69] op_sel_hi:[1,0]
	v_pk_fma_f32 v[202:203], v[70:71], v[202:203], v[206:207] op_sel_hi:[0,1,1]
	v_pk_fma_f32 v[200:201], v[70:71], v[200:201], v[54:55] op_sel_hi:[0,1,1]
	ds_read_b128 v[74:77], v67 offset:26656
	s_waitcnt lgkmcnt(1)
	v_mul_f32_e32 v206, v83, v201
	v_mul_f32_e32 v207, v85, v203
	v_fmac_f32_e32 v206, v82, v200
	v_fmac_f32_e32 v207, v84, v202
	v_add_f32_e32 v206, v206, v207
	v_add_f32_e32 v71, v206, v71
	v_pk_mul_f32 v[206:207], v[70:71], v[58:59] op_sel_hi:[0,1]
	v_pk_mul_f32 v[54:55], v[70:71], v[56:57] op_sel_hi:[0,1]
	v_pk_fma_f32 v[206:207], v[204:205], v[68:69], v[206:207] op_sel_hi:[1,0,1]
	v_pk_fma_f32 v[204:205], v[210:211], v[68:69], v[54:55] op_sel_hi:[1,0,1]
	ds_read_b128 v[54:57], v67 offset:26672
	s_waitcnt lgkmcnt(1)
	v_mul_f32_e32 v210, v75, v205
	v_mul_f32_e32 v211, v77, v207
	v_fmac_f32_e32 v210, v74, v204
	v_fmac_f32_e32 v211, v76, v206
	v_add_f32_e32 v210, v210, v211
	v_add_f32_e32 v67, v210, v71
	v_pk_mul_f32 v[210:211], v[70:71], v[80:81] op_sel_hi:[0,1]
	v_pk_mul_f32 v[58:59], v[70:71], v[78:79] op_sel_hi:[0,1]
	v_pk_fma_f32 v[210:211], v[208:209], v[68:69], v[210:211] op_sel_hi:[1,0,1]
	v_pk_fma_f32 v[208:209], v[52:53], v[68:69], v[58:59] op_sel_hi:[1,0,1]
	s_waitcnt lgkmcnt(0)
	v_mul_f32_e32 v53, v57, v211
	v_mul_f32_e32 v52, v55, v209
	v_fmac_f32_e32 v52, v54, v208
	v_fmac_f32_e32 v53, v56, v210
	v_add_f32_e32 v52, v52, v53
	v_add_f32_e32 v52, v67, v52
	ds_bpermute_b32 v53, v61, v52
	s_waitcnt lgkmcnt(0)
	v_add_f32_e32 v52, v52, v53
	ds_bpermute_b32 v53, v62, v52
	s_waitcnt lgkmcnt(0)
	v_add_f32_e32 v52, v52, v53
	ds_bpermute_b32 v53, v63, v52
	s_and_saveexec_b64 s[14:15], s[6:7]
	s_cbranch_execz .Lssd12_7_tail
	ds_read_b32 v54, v64 offset:50432
	s_waitcnt lgkmcnt(1)
	v_add_f32_e32 v52, v52, v53
	v_fmac_f32_e32 v52, v66, v69
	s_waitcnt lgkmcnt(0)
	v_mul_f32_e32 v55, 0xbfb8aa3b, v54
	v_exp_f32_e32 v55, v55
	s_nop 0
	v_add_f32_e32 v53, 1.0, v55
	v_div_scale_f32 v55, s[2:3], v53, v53, v54
	v_rcp_f32_e32 v56, v55
	v_div_scale_f32 v57, vcc, v54, v53, v54
	v_fma_f32 v58, -v55, v56, 1.0
	v_fmac_f32_e32 v56, v58, v56
	v_mul_f32_e32 v58, v57, v56
	v_fma_f32 v59, -v55, v58, v57
	v_fmac_f32_e32 v58, v59, v56
	v_fma_f32 v55, -v55, v58, v57
	v_div_fmas_f32 v55, v55, v56, v58
	v_div_fixup_f32 v53, v55, v53, v54
	v_mul_f32_e32 v52, v52, v53
	ds_write_b32 v64, v52 offset:38144
	s_branch .Lssd12_7_tail
.Lssd12_7_tail:
	s_or_b64 exec, exec, s[14:15]
	s_add_i32 s0, s0, 1
	s_add_i32 s1, s1, 4
	s_waitcnt lgkmcnt(0)
	v_lshl_add_u64 v[52:53], v[50:51], 0, s[8:9]
	s_add_u32 s8, s8, 0x8000
	s_addc_u32 s9, s9, 0
	v_add_co_u32_e32 v52, vcc, 0x2fb35000, v52
	s_add_u32 s12, s12, 4
	s_nop 0
	v_addc_co_u32_e32 v53, vcc, 0, v53, vcc
	s_addc_u32 s13, s13, 0
	global_store_dwordx4 v[52:53], v[196:199], off
	global_store_dwordx4 v[52:53], v[200:203], off offset:16
	global_store_dwordx4 v[52:53], v[204:207], off offset:32
	global_store_dwordx4 v[52:53], v[208:211], off offset:48
	s_add_u32 s10, s10, 4
	s_addc_u32 s11, s11, 0
	v_add_u32_e32 v64, 0x100, v64
.Lssd12_8:
	s_load_dword s16, s[12:13], 0x0
	s_load_dword s17, s[10:11], 0x0
	s_mul_i32 s2, s0, 0xab
	s_and_b32 s2, s2, 0xfe00
	v_add_u32_e32 v67, s2, v65
	s_waitcnt vmcnt(44)
	s_waitcnt lgkmcnt(0)
	v_mov_b32_e32 v52, s16
	v_mov_b32_e32 v66, s17
	v_mul_f32_e32 v52, 0x3fb8aa3b, v52
	v_exp_f32_e32 v68, v52
	v_mov_b32_e32 v52, s1
	ds_read_b32 v53, v52
	s_waitcnt lgkmcnt(0)
	v_mul_f32_e64 v52, v53, -v68
	v_mul_f32_e32 v52, 0x3fb8aa3b, v52
	v_exp_f32_e32 v58, v52
	ds_read_b32 v52, v64
	ds_read_b128 v[54:57], v67 offset:3072
	ds_read_b128 v[74:77], v67 offset:3088
	ds_read_b128 v[78:81], v67 offset:3104
	ds_read_b128 v[82:85], v67 offset:3120
	v_pk_mul_f32 v[226:227], v[226:227], v[58:59] op_sel_hi:[1,0]
	v_pk_mul_f32 v[86:87], v[224:225], v[58:59] op_sel_hi:[1,0]
	s_waitcnt lgkmcnt(4)
	v_mul_f32_e32 v70, v53, v52
	s_waitcnt lgkmcnt(3)
	v_pk_fma_f32 v[224:225], v[56:57], v[70:71], v[226:227] op_sel_hi:[1,0,1]
	v_pk_fma_f32 v[226:227], v[54:55], v[70:71], v[86:87] op_sel_hi:[1,0,1]
	ds_read_b128 v[54:57], v67 offset:5120
	v_pk_mul_f32 v[222:223], v[222:223], v[58:59] op_sel_hi:[1,0]
	s_waitcnt lgkmcnt(0)
	v_mul_f32_e32 v53, v55, v227
	v_fmac_f32_e32 v53, v54, v226
	v_mul_f32_e32 v54, v57, v225
	v_fmac_f32_e32 v54, v56, v224
	v_add_f32_e32 v53, v53, v54
	v_pk_mul_f32 v[54:55], v[220:221], v[58:59] op_sel_hi:[1,0]
	v_pk_fma_f32 v[220:221], v[70:71], v[76:77], v[222:223] op_sel_hi:[0,1,1]
	v_pk_fma_f32 v[222:223], v[70:71], v[74:75], v[54:55] op_sel_hi:[0,1,1]
	ds_read_b128 v[54:57], v67 offset:5136
	v_add_f32_e32 v53, 0, v53
	s_waitcnt lgkmcnt(0)
	v_mul_f32_e32 v55, v55, v223
	v_fmac_f32_e32 v55, v54, v222
	v_mul_f32_e32 v54, v57, v221
	v_fmac_f32_e32 v54, v56, v220
	v_add_f32_e32 v54, v55, v54
	v_add_f32_e32 v53, v54, v53
	v_pk_mul_f32 v[54:55], v[70:71], v[78:79] op_sel_hi:[0,1]
	v_pk_mul_f32 v[56:57], v[70:71], v[80:81] op_sel_hi:[0,1]
	v_pk_fma_f32 v[218:219], v[218:219], v[58:59], v[56:57] op_sel_hi:[1,0,1]
	v_pk_fma_f32 v[216:217], v[216:217], v[58:59], v[54:55] op_sel_hi:[1,0,1]
	ds_read_b128 v[54:57], v67 offset:5152
	s_waitcnt lgkmcnt(0)
	v_mul_f32_e32 v55, v55, v217
	v_fmac_f32_e32 v55, v54, v216
	v_mul_f32_e32 v54, v57, v219
	v_fmac_f32_e32 v54, v56, v218
	v_add_f32_e32 v54, v55, v54
	v_add_f32_e32 v53, v54, v53
	v_pk_mul_f32 v[54:55], v[70:71], v[82:83] op_sel_hi:[0,1]
	v_pk_mul_f32 v[56:57], v[70:71], v[84:85] op_sel_hi:[0,1]
	v_pk_fma_f32 v[214:215], v[214:215], v[58:59], v[56:57] op_sel_hi:[1,0,1]
	v_pk_fma_f32 v[212:213], v[212:213], v[58:59], v[54:55] op_sel_hi:[1,0,1]
	ds_read_b128 v[54:57], v67 offset:5168
	s_waitcnt lgkmcnt(0)
	v_mul_f32_e32 v55, v55, v213
	v_fmac_f32_e32 v55, v54, v212
	v_mul_f32_e32 v54, v57, v215
	v_fmac_f32_e32 v54, v56, v214
	v_add_f32_e32 v54, v55, v54
	v_add_f32_e32 v53, v53, v54
	ds_bpermute_b32 v54, v61, v53
	s_waitcnt lgkmcnt(0)
	v_add_f32_e32 v53, v53, v54
	ds_bpermute_b32 v54, v62, v53
	s_waitcnt lgkmcnt(0)
	v_add_f32_e32 v53, v53, v54
	ds_bpermute_b32 v54, v63, v53
	s_and_saveexec_b64 s[14:15], s[6:7]
	s_cbranch_execz .Lssd12_8_689
	ds_read_b32 v55, v64 offset:41216
	s_waitcnt lgkmcnt(1)
	v_add_f32_e32 v53, v53, v54
	v_fmac_f32_e32 v53, v66, v52
	s_waitcnt lgkmcnt(0)
	v_mul_f32_e32 v56, 0xbfb8aa3b, v55
	v_exp_f32_e32 v56, v56
	s_nop 0
	v_add_f32_e32 v54, 1.0, v56
	v_div_scale_f32 v56, s[2:3], v54, v54, v55
	v_rcp_f32_e32 v57, v56
	v_div_scale_f32 v52, vcc, v55, v54, v55
	v_fma_f32 v58, -v56, v57, 1.0
	v_fmac_f32_e32 v57, v58, v57
	v_mul_f32_e32 v58, v52, v57
	v_fma_f32 v59, -v56, v58, v52
	v_fmac_f32_e32 v58, v59, v57
	v_fma_f32 v52, -v56, v58, v52
	v_div_fmas_f32 v52, v52, v57, v58
	v_div_fixup_f32 v52, v52, v54, v55
	v_mul_f32_e32 v52, v53, v52
	ds_write_b32 v64, v52 offset:28928
.Lssd12_8_689:
	s_or_b64 exec, exec, s[14:15]
	v_mov_b32_e32 v52, s1
	ds_read_b32 v53, v52 offset:48
	ds_read_b32 v52, v64 offset:7168
	s_waitcnt lgkmcnt(1)
	v_mul_f32_e32 v54, v53, v68
	v_mul_f32_e32 v54, 0xbfb8aa3b, v54
	v_exp_f32_e32 v58, v54
	ds_read_b128 v[54:57], v67 offset:10240
	ds_read_b128 v[74:77], v67 offset:10256
	ds_read_b128 v[78:81], v67 offset:12288
	s_waitcnt lgkmcnt(3)
	v_mul_f32_e32 v70, v53, v52
	ds_read_b128 v[82:85], v67 offset:10272
	ds_read_b128 v[86:89], v67 offset:10288
	v_pk_mul_f32 v[224:225], v[224:225], v[58:59] op_sel_hi:[1,0]
	v_pk_mul_f32 v[226:227], v[226:227], v[58:59] op_sel_hi:[1,0]
	s_waitcnt lgkmcnt(4)
	v_pk_fma_f32 v[224:225], v[56:57], v[70:71], v[224:225] op_sel_hi:[1,0,1]
	v_pk_fma_f32 v[226:227], v[54:55], v[70:71], v[226:227] op_sel_hi:[1,0,1]
	ds_read_b128 v[54:57], v67 offset:12304
	s_waitcnt lgkmcnt(3)
	v_mul_f32_e32 v59, v81, v225
	v_fmac_f32_e32 v59, v80, v224
	v_pk_mul_f32 v[220:221], v[220:221], v[58:59] op_sel_hi:[1,0]
	v_pk_mul_f32 v[222:223], v[222:223], v[58:59] op_sel_hi:[1,0]
	v_pk_fma_f32 v[220:221], v[70:71], v[76:77], v[220:221] op_sel_hi:[0,1,1]
	v_pk_fma_f32 v[222:223], v[70:71], v[74:75], v[222:223] op_sel_hi:[0,1,1]
	s_waitcnt lgkmcnt(2)
	v_pk_mul_f32 v[74:75], v[70:71], v[84:85] op_sel_hi:[0,1]
	v_pk_mul_f32 v[76:77], v[70:71], v[82:83] op_sel_hi:[0,1]
	v_mul_f32_e32 v53, v79, v227
	v_pk_fma_f32 v[218:219], v[218:219], v[58:59], v[74:75] op_sel_hi:[1,0,1]
	v_pk_fma_f32 v[216:217], v[216:217], v[58:59], v[76:77] op_sel_hi:[1,0,1]
	ds_read_b128 v[74:77], v67 offset:12336
	s_waitcnt lgkmcnt(1)
	v_mul_f32_e32 v55, v55, v223
	v_fmac_f32_e32 v53, v78, v226
	v_fmac_f32_e32 v55, v54, v222
	v_mul_f32_e32 v54, v57, v221
	v_add_f32_e32 v53, v53, v59
	v_fmac_f32_e32 v54, v56, v220
	v_add_f32_e32 v53, 0, v53
	v_add_f32_e32 v54, v55, v54
	v_add_f32_e32 v53, v54, v53
	ds_read_b128 v[54:57], v67 offset:12320
	s_waitcnt lgkmcnt(0)
	v_mul_f32_e32 v55, v55, v217
	v_fmac_f32_e32 v55, v54, v216
	v_mul_f32_e32 v54, v57, v219
	v_fmac_f32_e32 v54, v56, v218
	v_add_f32_e32 v54, v55, v54
	v_add_f32_e32 v53, v54, v53
	v_pk_mul_f32 v[54:55], v[70:71], v[88:89] op_sel_hi:[0,1]
	v_pk_mul_f32 v[56:57], v[70:71], v[86:87] op_sel_hi:[0,1]
	v_pk_fma_f32 v[214:215], v[214:215], v[58:59], v[54:55] op_sel_hi:[1,0,1]
	v_pk_fma_f32 v[212:213], v[212:213], v[58:59], v[56:57] op_sel_hi:[1,0,1]
	v_mul_f32_e32 v55, v77, v215
	v_mul_f32_e32 v54, v75, v213
	v_fmac_f32_e32 v54, v74, v212
	v_fmac_f32_e32 v55, v76, v214
	v_add_f32_e32 v54, v54, v55
	v_add_f32_e32 v53, v53, v54
	ds_bpermute_b32 v54, v61, v53
	s_waitcnt lgkmcnt(0)
	v_add_f32_e32 v53, v53, v54
	ds_bpermute_b32 v54, v62, v53
	s_waitcnt lgkmcnt(0)
	v_add_f32_e32 v53, v53, v54
	ds_bpermute_b32 v54, v63, v53
	s_and_saveexec_b64 s[14:15], s[6:7]
	s_cbranch_execz .Lssd12_8_691
	ds_read_b32 v55, v64 offset:44288
	s_waitcnt lgkmcnt(1)
	v_add_f32_e32 v53, v53, v54
	v_fmac_f32_e32 v53, v66, v52
	s_waitcnt lgkmcnt(0)
	v_mul_f32_e32 v56, 0xbfb8aa3b, v55
	v_exp_f32_e32 v56, v56
	s_nop 0
	v_add_f32_e32 v54, 1.0, v56
	v_div_scale_f32 v56, s[2:3], v54, v54, v55
	v_rcp_f32_e32 v57, v56
	v_div_scale_f32 v52, vcc, v55, v54, v55
	v_fma_f32 v58, -v56, v57, 1.0
	v_fmac_f32_e32 v57, v58, v57
	v_mul_f32_e32 v58, v52, v57
	v_fma_f32 v59, -v56, v58, v52
	v_fmac_f32_e32 v58, v59, v57
	v_fma_f32 v52, -v56, v58, v52
	v_div_fmas_f32 v52, v52, v57, v58
	v_div_fixup_f32 v52, v52, v54, v55
	v_mul_f32_e32 v52, v53, v52
	ds_write_b32 v64, v52 offset:32000
.Lssd12_8_691:
	s_or_b64 exec, exec, s[14:15]
	v_mov_b32_e32 v52, s1
	ds_read_b32 v56, v52 offset:96
	ds_read_b32 v69, v64 offset:14336
	s_waitcnt lgkmcnt(1)
	v_mul_f32_e32 v52, v56, v68
	v_mul_f32_e32 v52, 0xbfb8aa3b, v52
	v_exp_f32_e32 v70, v52
	ds_read_b128 v[52:55], v67 offset:17408
	ds_read_b128 v[74:77], v67 offset:17424
	ds_read_b128 v[78:81], v67 offset:19456
	s_waitcnt lgkmcnt(3)
	v_mul_f32_e32 v72, v56, v69
	v_pk_mul_f32 v[56:57], v[224:225], v[70:71] op_sel_hi:[1,0]
	v_pk_mul_f32 v[58:59], v[226:227], v[70:71] op_sel_hi:[1,0]
	s_waitcnt lgkmcnt(2)
	v_pk_fma_f32 v[56:57], v[54:55], v[72:73], v[56:57] op_sel_hi:[1,0,1]
	v_pk_fma_f32 v[58:59], v[52:53], v[72:73], v[58:59] op_sel_hi:[1,0,1]
	s_waitcnt lgkmcnt(0)
	v_mul_f32_e32 v53, v81, v57
	v_mul_f32_e32 v52, v79, v59
	ds_read_b128 v[224:227], v67 offset:17440
	ds_read_b128 v[82:85], v67 offset:17456
	ds_read_b128 v[86:89], v67 offset:19472
	v_fmac_f32_e32 v52, v78, v58
	v_fmac_f32_e32 v53, v80, v56
	v_add_f32_e32 v52, v52, v53
	v_add_f32_e32 v71, 0, v52
	v_pk_mul_f32 v[220:221], v[220:221], v[70:71] op_sel_hi:[1,0]
	v_pk_mul_f32 v[52:53], v[222:223], v[70:71] op_sel_hi:[1,0]
	v_pk_fma_f32 v[222:223], v[72:73], v[76:77], v[220:221] op_sel_hi:[0,1,1]
	v_pk_fma_f32 v[54:55], v[72:73], v[74:75], v[52:53] op_sel_hi:[0,1,1]
	ds_read_b128 v[74:77], v67 offset:19488
	s_waitcnt lgkmcnt(1)
	v_mul_f32_e32 v220, v87, v55
	v_mul_f32_e32 v221, v89, v223
	v_fmac_f32_e32 v220, v86, v54
	v_fmac_f32_e32 v221, v88, v222
	v_add_f32_e32 v220, v220, v221
	v_add_f32_e32 v52, v220, v71
	v_pk_mul_f32 v[220:221], v[72:73], v[226:227] op_sel_hi:[0,1]
	v_pk_mul_f32 v[224:225], v[72:73], v[224:225] op_sel_hi:[0,1]
	v_pk_fma_f32 v[220:221], v[218:219], v[70:71], v[220:221] op_sel_hi:[1,0,1]
	v_pk_fma_f32 v[226:227], v[216:217], v[70:71], v[224:225] op_sel_hi:[1,0,1]
	ds_read_b128 v[216:219], v67 offset:19504
	s_waitcnt lgkmcnt(1)
	v_mul_f32_e32 v224, v75, v227
	v_mul_f32_e32 v225, v77, v221
	v_fmac_f32_e32 v224, v74, v226
	v_fmac_f32_e32 v225, v76, v220
	v_add_f32_e32 v224, v224, v225
	v_add_f32_e32 v71, v224, v52
	v_pk_mul_f32 v[224:225], v[72:73], v[84:85] op_sel_hi:[0,1]
	v_pk_mul_f32 v[52:53], v[72:73], v[82:83] op_sel_hi:[0,1]
	v_pk_fma_f32 v[224:225], v[214:215], v[70:71], v[224:225] op_sel_hi:[1,0,1]
	v_pk_fma_f32 v[52:53], v[212:213], v[70:71], v[52:53] op_sel_hi:[1,0,1]
	s_waitcnt lgkmcnt(0)
	v_mul_f32_e32 v213, v219, v225
	v_mul_f32_e32 v212, v217, v53
	v_fmac_f32_e32 v212, v216, v52
	v_fmac_f32_e32 v213, v218, v224
	v_add_f32_e32 v212, v212, v213
	v_add_f32_e32 v212, v71, v212
	ds_bpermute_b32 v213, v61, v212
	s_waitcnt lgkmcnt(0)
	v_add_f32_e32 v212, v212, v213
	ds_bpermute_b32 v213, v62, v212
	s_waitcnt lgkmcnt(0)
	v_add_f32_e32 v212, v212, v213
	ds_bpermute_b32 v213, v63, v212
	s_and_saveexec_b64 s[14:15], s[6:7]
	s_cbranch_execz .Lssd12_8_693
	ds_read_b32 v214, v64 offset:47360
	s_waitcnt lgkmcnt(1)
	v_add_f32_e32 v212, v212, v213
	v_fmac_f32_e32 v212, v66, v69
	s_waitcnt lgkmcnt(0)
	v_mul_f32_e32 v215, 0xbfb8aa3b, v214
	v_exp_f32_e32 v215, v215
	s_nop 0
	v_add_f32_e32 v213, 1.0, v215
	v_div_scale_f32 v215, s[2:3], v213, v213, v214
	v_rcp_f32_e32 v216, v215
	v_div_scale_f32 v217, vcc, v214, v213, v214
	v_fma_f32 v218, -v215, v216, 1.0
	v_fmac_f32_e32 v216, v218, v216
	v_mul_f32_e32 v218, v217, v216
	v_fma_f32 v219, -v215, v218, v217
	v_fmac_f32_e32 v218, v219, v216
	v_fma_f32 v215, -v215, v218, v217
	v_div_fmas_f32 v215, v215, v216, v218
	v_div_fixup_f32 v213, v215, v213, v214
	v_mul_f32_e32 v212, v212, v213
	ds_write_b32 v64, v212 offset:35072
.Lssd12_8_693:
	s_or_b64 exec, exec, s[14:15]
	v_mov_b32_e32 v212, s1
	ds_read_b32 v70, v212 offset:144
	ds_read_b32 v69, v64 offset:21504
	s_waitcnt lgkmcnt(1)
	v_mul_f32_e32 v212, v70, v68
	v_mul_f32_e32 v212, 0xbfb8aa3b, v212
	v_exp_f32_e32 v68, v212
	ds_read_b128 v[212:215], v67 offset:24576
	ds_read_b128 v[216:219], v67 offset:24592
	ds_read_b128 v[74:77], v67 offset:26624
	s_waitcnt lgkmcnt(3)
	v_mul_f32_e32 v70, v70, v69
	v_pk_mul_f32 v[82:83], v[56:57], v[68:69] op_sel_hi:[1,0]
	v_pk_mul_f32 v[84:85], v[58:59], v[68:69] op_sel_hi:[1,0]
	s_waitcnt lgkmcnt(2)
	v_pk_fma_f32 v[214:215], v[214:215], v[70:71], v[82:83] op_sel_hi:[1,0,1]
	v_pk_fma_f32 v[212:213], v[212:213], v[70:71], v[84:85] op_sel_hi:[1,0,1]
	ds_read_b128 v[56:59], v67 offset:24608
	ds_read_b128 v[78:81], v67 offset:24624
	ds_read_b128 v[82:85], v67 offset:26640
	s_waitcnt lgkmcnt(3)
	v_mul_f32_e32 v71, v75, v213
	v_mul_f32_e32 v72, v77, v215
	v_fmac_f32_e32 v71, v74, v212
	v_fmac_f32_e32 v72, v76, v214
	v_add_f32_e32 v71, v71, v72
	v_add_f32_e32 v71, 0, v71
	v_pk_mul_f32 v[222:223], v[222:223], v[68:69] op_sel_hi:[1,0]
	v_pk_mul_f32 v[54:55], v[54:55], v[68:69] op_sel_hi:[1,0]
	v_pk_fma_f32 v[218:219], v[70:71], v[218:219], v[222:223] op_sel_hi:[0,1,1]
	v_pk_fma_f32 v[216:217], v[70:71], v[216:217], v[54:55] op_sel_hi:[0,1,1]
	ds_read_b128 v[74:77], v67 offset:26656
	s_waitcnt lgkmcnt(1)
	v_mul_f32_e32 v222, v83, v217
	v_mul_f32_e32 v223, v85, v219
	v_fmac_f32_e32 v222, v82, v216
	v_fmac_f32_e32 v223, v84, v218
	v_add_f32_e32 v222, v222, v223
	v_add_f32_e32 v71, v222, v71
	v_pk_mul_f32 v[222:223], v[70:71], v[58:59] op_sel_hi:[0,1]
	v_pk_mul_f32 v[54:55], v[70:71], v[56:57] op_sel_hi:[0,1]
	v_pk_fma_f32 v[222:223], v[220:221], v[68:69], v[222:223] op_sel_hi:[1,0,1]
	v_pk_fma_f32 v[220:221], v[226:227], v[68:69], v[54:55] op_sel_hi:[1,0,1]
	ds_read_b128 v[54:57], v67 offset:26672
	s_waitcnt lgkmcnt(1)
	v_mul_f32_e32 v226, v75, v221
	v_mul_f32_e32 v227, v77, v223
	v_fmac_f32_e32 v226, v74, v220
	v_fmac_f32_e32 v227, v76, v222
	v_add_f32_e32 v226, v226, v227
	v_add_f32_e32 v67, v226, v71
	v_pk_mul_f32 v[226:227], v[70:71], v[80:81] op_sel_hi:[0,1]
	v_pk_mul_f32 v[58:59], v[70:71], v[78:79] op_sel_hi:[0,1]
	v_pk_fma_f32 v[226:227], v[224:225], v[68:69], v[226:227] op_sel_hi:[1,0,1]
	v_pk_fma_f32 v[224:225], v[52:53], v[68:69], v[58:59] op_sel_hi:[1,0,1]
	s_waitcnt lgkmcnt(0)
	v_mul_f32_e32 v53, v57, v227
	v_mul_f32_e32 v52, v55, v225
	v_fmac_f32_e32 v52, v54, v224
	v_fmac_f32_e32 v53, v56, v226
	v_add_f32_e32 v52, v52, v53
	v_add_f32_e32 v52, v67, v52
	ds_bpermute_b32 v53, v61, v52
	s_waitcnt lgkmcnt(0)
	v_add_f32_e32 v52, v52, v53
	ds_bpermute_b32 v53, v62, v52
	s_waitcnt lgkmcnt(0)
	v_add_f32_e32 v52, v52, v53
	ds_bpermute_b32 v53, v63, v52
	s_and_saveexec_b64 s[14:15], s[6:7]
	s_cbranch_execz .Lssd12_8_tail
	ds_read_b32 v54, v64 offset:50432
	s_waitcnt lgkmcnt(1)
	v_add_f32_e32 v52, v52, v53
	v_fmac_f32_e32 v52, v66, v69
	s_waitcnt lgkmcnt(0)
	v_mul_f32_e32 v55, 0xbfb8aa3b, v54
	v_exp_f32_e32 v55, v55
	s_nop 0
	v_add_f32_e32 v53, 1.0, v55
	v_div_scale_f32 v55, s[2:3], v53, v53, v54
	v_rcp_f32_e32 v56, v55
	v_div_scale_f32 v57, vcc, v54, v53, v54
	v_fma_f32 v58, -v55, v56, 1.0
	v_fmac_f32_e32 v56, v58, v56
	v_mul_f32_e32 v58, v57, v56
	v_fma_f32 v59, -v55, v58, v57
	v_fmac_f32_e32 v58, v59, v56
	v_fma_f32 v55, -v55, v58, v57
	v_div_fmas_f32 v55, v55, v56, v58
	v_div_fixup_f32 v53, v55, v53, v54
	v_mul_f32_e32 v52, v52, v53
	ds_write_b32 v64, v52 offset:38144
	s_branch .Lssd12_8_tail
.Lssd12_8_tail:
	s_or_b64 exec, exec, s[14:15]
	s_add_i32 s0, s0, 1
	s_add_i32 s1, s1, 4
	s_waitcnt lgkmcnt(0)
	v_lshl_add_u64 v[52:53], v[50:51], 0, s[8:9]
	s_add_u32 s8, s8, 0x8000
	s_addc_u32 s9, s9, 0
	v_add_co_u32_e32 v52, vcc, 0x2fb35000, v52
	s_add_u32 s12, s12, 4
	s_nop 0
	v_addc_co_u32_e32 v53, vcc, 0, v53, vcc
	s_addc_u32 s13, s13, 0
	global_store_dwordx4 v[52:53], v[212:215], off
	global_store_dwordx4 v[52:53], v[216:219], off offset:16
	global_store_dwordx4 v[52:53], v[220:223], off offset:32
	global_store_dwordx4 v[52:53], v[224:227], off offset:48
	s_add_u32 s10, s10, 4
	s_addc_u32 s11, s11, 0
	v_add_u32_e32 v64, 0x100, v64
.Lssd12_9:
	s_load_dword s16, s[12:13], 0x0
	s_load_dword s17, s[10:11], 0x0
	s_mul_i32 s2, s0, 0xab
	s_and_b32 s2, s2, 0xfe00
	v_add_u32_e32 v67, s2, v65
	s_waitcnt vmcnt(44)
	s_waitcnt lgkmcnt(0)
	v_mov_b32_e32 v52, s16
	v_mov_b32_e32 v66, s17
	v_mul_f32_e32 v52, 0x3fb8aa3b, v52
	v_exp_f32_e32 v68, v52
	v_mov_b32_e32 v52, s1
	ds_read_b32 v53, v52
	s_waitcnt lgkmcnt(0)
	v_mul_f32_e64 v52, v53, -v68
	v_mul_f32_e32 v52, 0x3fb8aa3b, v52
	v_exp_f32_e32 v58, v52
	ds_read_b32 v52, v64
	ds_read_b128 v[54:57], v67 offset:3072
	ds_read_b128 v[74:77], v67 offset:3088
	ds_read_b128 v[78:81], v67 offset:3104
	ds_read_b128 v[82:85], v67 offset:3120
	v_pk_mul_f32 v[242:243], v[242:243], v[58:59] op_sel_hi:[1,0]
	v_pk_mul_f32 v[86:87], v[240:241], v[58:59] op_sel_hi:[1,0]
	s_waitcnt lgkmcnt(4)
	v_mul_f32_e32 v70, v53, v52
	s_waitcnt lgkmcnt(3)
	v_pk_fma_f32 v[240:241], v[56:57], v[70:71], v[242:243] op_sel_hi:[1,0,1]
	v_pk_fma_f32 v[242:243], v[54:55], v[70:71], v[86:87] op_sel_hi:[1,0,1]
	ds_read_b128 v[54:57], v67 offset:5120
	v_pk_mul_f32 v[238:239], v[238:239], v[58:59] op_sel_hi:[1,0]
	s_waitcnt lgkmcnt(0)
	v_mul_f32_e32 v53, v55, v243
	v_fmac_f32_e32 v53, v54, v242
	v_mul_f32_e32 v54, v57, v241
	v_fmac_f32_e32 v54, v56, v240
	v_add_f32_e32 v53, v53, v54
	v_pk_mul_f32 v[54:55], v[236:237], v[58:59] op_sel_hi:[1,0]
	v_pk_fma_f32 v[236:237], v[70:71], v[76:77], v[238:239] op_sel_hi:[0,1,1]
	v_pk_fma_f32 v[238:239], v[70:71], v[74:75], v[54:55] op_sel_hi:[0,1,1]
	ds_read_b128 v[54:57], v67 offset:5136
	v_add_f32_e32 v53, 0, v53
	s_waitcnt lgkmcnt(0)
	v_mul_f32_e32 v55, v55, v239
	v_fmac_f32_e32 v55, v54, v238
	v_mul_f32_e32 v54, v57, v237
	v_fmac_f32_e32 v54, v56, v236
	v_add_f32_e32 v54, v55, v54
	v_add_f32_e32 v53, v54, v53
	v_pk_mul_f32 v[54:55], v[70:71], v[78:79] op_sel_hi:[0,1]
	v_pk_mul_f32 v[56:57], v[70:71], v[80:81] op_sel_hi:[0,1]
	v_pk_fma_f32 v[234:235], v[234:235], v[58:59], v[56:57] op_sel_hi:[1,0,1]
	v_pk_fma_f32 v[232:233], v[232:233], v[58:59], v[54:55] op_sel_hi:[1,0,1]
	ds_read_b128 v[54:57], v67 offset:5152
	s_waitcnt lgkmcnt(0)
	v_mul_f32_e32 v55, v55, v233
	v_fmac_f32_e32 v55, v54, v232
	v_mul_f32_e32 v54, v57, v235
	v_fmac_f32_e32 v54, v56, v234
	v_add_f32_e32 v54, v55, v54
	v_add_f32_e32 v53, v54, v53
	v_pk_mul_f32 v[54:55], v[70:71], v[82:83] op_sel_hi:[0,1]
	v_pk_mul_f32 v[56:57], v[70:71], v[84:85] op_sel_hi:[0,1]
	v_pk_fma_f32 v[230:231], v[230:231], v[58:59], v[56:57] op_sel_hi:[1,0,1]
	v_pk_fma_f32 v[228:229], v[228:229], v[58:59], v[54:55] op_sel_hi:[1,0,1]
	ds_read_b128 v[54:57], v67 offset:5168
	s_waitcnt lgkmcnt(0)
	v_mul_f32_e32 v55, v55, v229
	v_fmac_f32_e32 v55, v54, v228
	v_mul_f32_e32 v54, v57, v231
	v_fmac_f32_e32 v54, v56, v230
	v_add_f32_e32 v54, v55, v54
	v_add_f32_e32 v53, v53, v54
	ds_bpermute_b32 v54, v61, v53
	s_waitcnt lgkmcnt(0)
	v_add_f32_e32 v53, v53, v54
	ds_bpermute_b32 v54, v62, v53
	s_waitcnt lgkmcnt(0)
	v_add_f32_e32 v53, v53, v54
	ds_bpermute_b32 v54, v63, v53
	s_and_saveexec_b64 s[14:15], s[6:7]
	s_cbranch_execz .Lssd12_9_689
	ds_read_b32 v55, v64 offset:41216
	s_waitcnt lgkmcnt(1)
	v_add_f32_e32 v53, v53, v54
	v_fmac_f32_e32 v53, v66, v52
	s_waitcnt lgkmcnt(0)
	v_mul_f32_e32 v56, 0xbfb8aa3b, v55
	v_exp_f32_e32 v56, v56
	s_nop 0
	v_add_f32_e32 v54, 1.0, v56
	v_div_scale_f32 v56, s[2:3], v54, v54, v55
	v_rcp_f32_e32 v57, v56
	v_div_scale_f32 v52, vcc, v55, v54, v55
	v_fma_f32 v58, -v56, v57, 1.0
	v_fmac_f32_e32 v57, v58, v57
	v_mul_f32_e32 v58, v52, v57
	v_fma_f32 v59, -v56, v58, v52
	v_fmac_f32_e32 v58, v59, v57
	v_fma_f32 v52, -v56, v58, v52
	v_div_fmas_f32 v52, v52, v57, v58
	v_div_fixup_f32 v52, v52, v54, v55
	v_mul_f32_e32 v52, v53, v52
	ds_write_b32 v64, v52 offset:28928
.Lssd12_9_689:
	s_or_b64 exec, exec, s[14:15]
	v_mov_b32_e32 v52, s1
	ds_read_b32 v53, v52 offset:48
	ds_read_b32 v52, v64 offset:7168
	s_waitcnt lgkmcnt(1)
	v_mul_f32_e32 v54, v53, v68
	v_mul_f32_e32 v54, 0xbfb8aa3b, v54
	v_exp_f32_e32 v58, v54
	ds_read_b128 v[54:57], v67 offset:10240
	ds_read_b128 v[74:77], v67 offset:10256
	ds_read_b128 v[78:81], v67 offset:12288
	s_waitcnt lgkmcnt(3)
	v_mul_f32_e32 v70, v53, v52
	ds_read_b128 v[82:85], v67 offset:10272
	ds_read_b128 v[86:89], v67 offset:10288
	v_pk_mul_f32 v[240:241], v[240:241], v[58:59] op_sel_hi:[1,0]
	v_pk_mul_f32 v[242:243], v[242:243], v[58:59] op_sel_hi:[1,0]
	s_waitcnt lgkmcnt(4)
	v_pk_fma_f32 v[240:241], v[56:57], v[70:71], v[240:241] op_sel_hi:[1,0,1]
	v_pk_fma_f32 v[242:243], v[54:55], v[70:71], v[242:243] op_sel_hi:[1,0,1]
	ds_read_b128 v[54:57], v67 offset:12304
	s_waitcnt lgkmcnt(3)
	v_mul_f32_e32 v59, v81, v241
	v_fmac_f32_e32 v59, v80, v240
	v_pk_mul_f32 v[236:237], v[236:237], v[58:59] op_sel_hi:[1,0]
	v_pk_mul_f32 v[238:239], v[238:239], v[58:59] op_sel_hi:[1,0]
	v_pk_fma_f32 v[236:237], v[70:71], v[76:77], v[236:237] op_sel_hi:[0,1,1]
	v_pk_fma_f32 v[238:239], v[70:71], v[74:75], v[238:239] op_sel_hi:[0,1,1]
	s_waitcnt lgkmcnt(2)
	v_pk_mul_f32 v[74:75], v[70:71], v[84:85] op_sel_hi:[0,1]
	v_pk_mul_f32 v[76:77], v[70:71], v[82:83] op_sel_hi:[0,1]
	v_mul_f32_e32 v53, v79, v243
	v_pk_fma_f32 v[234:235], v[234:235], v[58:59], v[74:75] op_sel_hi:[1,0,1]
	v_pk_fma_f32 v[232:233], v[232:233], v[58:59], v[76:77] op_sel_hi:[1,0,1]
	ds_read_b128 v[74:77], v67 offset:12336
	s_waitcnt lgkmcnt(1)
	v_mul_f32_e32 v55, v55, v239
	v_fmac_f32_e32 v53, v78, v242
	v_fmac_f32_e32 v55, v54, v238
	v_mul_f32_e32 v54, v57, v237
	v_add_f32_e32 v53, v53, v59
	v_fmac_f32_e32 v54, v56, v236
	v_add_f32_e32 v53, 0, v53
	v_add_f32_e32 v54, v55, v54
	v_add_f32_e32 v53, v54, v53
	ds_read_b128 v[54:57], v67 offset:12320
	s_waitcnt lgkmcnt(0)
	v_mul_f32_e32 v55, v55, v233
	v_fmac_f32_e32 v55, v54, v232
	v_mul_f32_e32 v54, v57, v235
	v_fmac_f32_e32 v54, v56, v234
	v_add_f32_e32 v54, v55, v54
	v_add_f32_e32 v53, v54, v53
	v_pk_mul_f32 v[54:55], v[70:71], v[88:89] op_sel_hi:[0,1]
	v_pk_mul_f32 v[56:57], v[70:71], v[86:87] op_sel_hi:[0,1]
	v_pk_fma_f32 v[230:231], v[230:231], v[58:59], v[54:55] op_sel_hi:[1,0,1]
	v_pk_fma_f32 v[228:229], v[228:229], v[58:59], v[56:57] op_sel_hi:[1,0,1]
	v_mul_f32_e32 v55, v77, v231
	v_mul_f32_e32 v54, v75, v229
	v_fmac_f32_e32 v54, v74, v228
	v_fmac_f32_e32 v55, v76, v230
	v_add_f32_e32 v54, v54, v55
	v_add_f32_e32 v53, v53, v54
	ds_bpermute_b32 v54, v61, v53
	s_waitcnt lgkmcnt(0)
	v_add_f32_e32 v53, v53, v54
	ds_bpermute_b32 v54, v62, v53
	s_waitcnt lgkmcnt(0)
	v_add_f32_e32 v53, v53, v54
	ds_bpermute_b32 v54, v63, v53
	s_and_saveexec_b64 s[14:15], s[6:7]
	s_cbranch_execz .Lssd12_9_691
	ds_read_b32 v55, v64 offset:44288
	s_waitcnt lgkmcnt(1)
	v_add_f32_e32 v53, v53, v54
	v_fmac_f32_e32 v53, v66, v52
	s_waitcnt lgkmcnt(0)
	v_mul_f32_e32 v56, 0xbfb8aa3b, v55
	v_exp_f32_e32 v56, v56
	s_nop 0
	v_add_f32_e32 v54, 1.0, v56
	v_div_scale_f32 v56, s[2:3], v54, v54, v55
	v_rcp_f32_e32 v57, v56
	v_div_scale_f32 v52, vcc, v55, v54, v55
	v_fma_f32 v58, -v56, v57, 1.0
	v_fmac_f32_e32 v57, v58, v57
	v_mul_f32_e32 v58, v52, v57
	v_fma_f32 v59, -v56, v58, v52
	v_fmac_f32_e32 v58, v59, v57
	v_fma_f32 v52, -v56, v58, v52
	v_div_fmas_f32 v52, v52, v57, v58
	v_div_fixup_f32 v52, v52, v54, v55
	v_mul_f32_e32 v52, v53, v52
	ds_write_b32 v64, v52 offset:32000
.Lssd12_9_691:
	s_or_b64 exec, exec, s[14:15]
	v_mov_b32_e32 v52, s1
	ds_read_b32 v56, v52 offset:96
	ds_read_b32 v69, v64 offset:14336
	s_waitcnt lgkmcnt(1)
	v_mul_f32_e32 v52, v56, v68
	v_mul_f32_e32 v52, 0xbfb8aa3b, v52
	v_exp_f32_e32 v70, v52
	ds_read_b128 v[52:55], v67 offset:17408
	ds_read_b128 v[74:77], v67 offset:17424
	ds_read_b128 v[78:81], v67 offset:19456
	s_waitcnt lgkmcnt(3)
	v_mul_f32_e32 v72, v56, v69
	v_pk_mul_f32 v[56:57], v[240:241], v[70:71] op_sel_hi:[1,0]
	v_pk_mul_f32 v[58:59], v[242:243], v[70:71] op_sel_hi:[1,0]
	s_waitcnt lgkmcnt(2)
	v_pk_fma_f32 v[56:57], v[54:55], v[72:73], v[56:57] op_sel_hi:[1,0,1]
	v_pk_fma_f32 v[58:59], v[52:53], v[72:73], v[58:59] op_sel_hi:[1,0,1]
	s_waitcnt lgkmcnt(0)
	v_mul_f32_e32 v53, v81, v57
	v_mul_f32_e32 v52, v79, v59
	ds_read_b128 v[240:243], v67 offset:17440
	ds_read_b128 v[82:85], v67 offset:17456
	ds_read_b128 v[86:89], v67 offset:19472
	v_fmac_f32_e32 v52, v78, v58
	v_fmac_f32_e32 v53, v80, v56
	v_add_f32_e32 v52, v52, v53
	v_add_f32_e32 v71, 0, v52
	v_pk_mul_f32 v[236:237], v[236:237], v[70:71] op_sel_hi:[1,0]
	v_pk_mul_f32 v[52:53], v[238:239], v[70:71] op_sel_hi:[1,0]
	v_pk_fma_f32 v[238:239], v[72:73], v[76:77], v[236:237] op_sel_hi:[0,1,1]
	v_pk_fma_f32 v[54:55], v[72:73], v[74:75], v[52:53] op_sel_hi:[0,1,1]
	ds_read_b128 v[74:77], v67 offset:19488
	s_waitcnt lgkmcnt(1)
	v_mul_f32_e32 v236, v87, v55
	v_mul_f32_e32 v237, v89, v239
	v_fmac_f32_e32 v236, v86, v54
	v_fmac_f32_e32 v237, v88, v238
	v_add_f32_e32 v236, v236, v237
	v_add_f32_e32 v52, v236, v71
	v_pk_mul_f32 v[236:237], v[72:73], v[242:243] op_sel_hi:[0,1]
	v_pk_mul_f32 v[240:241], v[72:73], v[240:241] op_sel_hi:[0,1]
	v_pk_fma_f32 v[236:237], v[234:235], v[70:71], v[236:237] op_sel_hi:[1,0,1]
	v_pk_fma_f32 v[242:243], v[232:233], v[70:71], v[240:241] op_sel_hi:[1,0,1]
	ds_read_b128 v[232:235], v67 offset:19504
	s_waitcnt lgkmcnt(1)
	v_mul_f32_e32 v240, v75, v243
	v_mul_f32_e32 v241, v77, v237
	v_fmac_f32_e32 v240, v74, v242
	v_fmac_f32_e32 v241, v76, v236
	v_add_f32_e32 v240, v240, v241
	v_add_f32_e32 v71, v240, v52
	v_pk_mul_f32 v[240:241], v[72:73], v[84:85] op_sel_hi:[0,1]
	v_pk_mul_f32 v[52:53], v[72:73], v[82:83] op_sel_hi:[0,1]
	v_pk_fma_f32 v[240:241], v[230:231], v[70:71], v[240:241] op_sel_hi:[1,0,1]
	v_pk_fma_f32 v[52:53], v[228:229], v[70:71], v[52:53] op_sel_hi:[1,0,1]
	s_waitcnt lgkmcnt(0)
	v_mul_f32_e32 v229, v235, v241
	v_mul_f32_e32 v228, v233, v53
	v_fmac_f32_e32 v228, v232, v52
	v_fmac_f32_e32 v229, v234, v240
	v_add_f32_e32 v228, v228, v229
	v_add_f32_e32 v228, v71, v228
	ds_bpermute_b32 v229, v61, v228
	s_waitcnt lgkmcnt(0)
	v_add_f32_e32 v228, v228, v229
	ds_bpermute_b32 v229, v62, v228
	s_waitcnt lgkmcnt(0)
	v_add_f32_e32 v228, v228, v229
	ds_bpermute_b32 v229, v63, v228
	s_and_saveexec_b64 s[14:15], s[6:7]
	s_cbranch_execz .Lssd12_9_693
	ds_read_b32 v230, v64 offset:47360
	s_waitcnt lgkmcnt(1)
	v_add_f32_e32 v228, v228, v229
	v_fmac_f32_e32 v228, v66, v69
	s_waitcnt lgkmcnt(0)
	v_mul_f32_e32 v231, 0xbfb8aa3b, v230
	v_exp_f32_e32 v231, v231
	s_nop 0
	v_add_f32_e32 v229, 1.0, v231
	v_div_scale_f32 v231, s[2:3], v229, v229, v230
	v_rcp_f32_e32 v232, v231
	v_div_scale_f32 v233, vcc, v230, v229, v230
	v_fma_f32 v234, -v231, v232, 1.0
	v_fmac_f32_e32 v232, v234, v232
	v_mul_f32_e32 v234, v233, v232
	v_fma_f32 v235, -v231, v234, v233
	v_fmac_f32_e32 v234, v235, v232
	v_fma_f32 v231, -v231, v234, v233
	v_div_fmas_f32 v231, v231, v232, v234
	v_div_fixup_f32 v229, v231, v229, v230
	v_mul_f32_e32 v228, v228, v229
	ds_write_b32 v64, v228 offset:35072
.Lssd12_9_693:
	s_or_b64 exec, exec, s[14:15]
	v_mov_b32_e32 v228, s1
	ds_read_b32 v70, v228 offset:144
	ds_read_b32 v69, v64 offset:21504
	s_waitcnt lgkmcnt(1)
	v_mul_f32_e32 v228, v70, v68
	v_mul_f32_e32 v228, 0xbfb8aa3b, v228
	v_exp_f32_e32 v68, v228
	ds_read_b128 v[228:231], v67 offset:24576
	ds_read_b128 v[232:235], v67 offset:24592
	ds_read_b128 v[74:77], v67 offset:26624
	s_waitcnt lgkmcnt(3)
	v_mul_f32_e32 v70, v70, v69
	v_pk_mul_f32 v[82:83], v[56:57], v[68:69] op_sel_hi:[1,0]
	v_pk_mul_f32 v[84:85], v[58:59], v[68:69] op_sel_hi:[1,0]
	s_waitcnt lgkmcnt(2)
	v_pk_fma_f32 v[230:231], v[230:231], v[70:71], v[82:83] op_sel_hi:[1,0,1]
	v_pk_fma_f32 v[228:229], v[228:229], v[70:71], v[84:85] op_sel_hi:[1,0,1]
	ds_read_b128 v[56:59], v67 offset:24608
	ds_read_b128 v[78:81], v67 offset:24624
	ds_read_b128 v[82:85], v67 offset:26640
	s_waitcnt lgkmcnt(3)
	v_mul_f32_e32 v71, v75, v229
	v_mul_f32_e32 v72, v77, v231
	v_fmac_f32_e32 v71, v74, v228
	v_fmac_f32_e32 v72, v76, v230
	v_add_f32_e32 v71, v71, v72
	v_add_f32_e32 v71, 0, v71
	v_pk_mul_f32 v[238:239], v[238:239], v[68:69] op_sel_hi:[1,0]
	v_pk_mul_f32 v[54:55], v[54:55], v[68:69] op_sel_hi:[1,0]
	v_pk_fma_f32 v[234:235], v[70:71], v[234:235], v[238:239] op_sel_hi:[0,1,1]
	v_pk_fma_f32 v[232:233], v[70:71], v[232:233], v[54:55] op_sel_hi:[0,1,1]
	ds_read_b128 v[74:77], v67 offset:26656
	s_waitcnt lgkmcnt(1)
	v_mul_f32_e32 v238, v83, v233
	v_mul_f32_e32 v239, v85, v235
	v_fmac_f32_e32 v238, v82, v232
	v_fmac_f32_e32 v239, v84, v234
	v_add_f32_e32 v238, v238, v239
	v_add_f32_e32 v71, v238, v71
	v_pk_mul_f32 v[238:239], v[70:71], v[58:59] op_sel_hi:[0,1]
	v_pk_mul_f32 v[54:55], v[70:71], v[56:57] op_sel_hi:[0,1]
	v_pk_fma_f32 v[238:239], v[236:237], v[68:69], v[238:239] op_sel_hi:[1,0,1]
	v_pk_fma_f32 v[236:237], v[242:243], v[68:69], v[54:55] op_sel_hi:[1,0,1]
	ds_read_b128 v[54:57], v67 offset:26672
	s_waitcnt lgkmcnt(1)
	v_mul_f32_e32 v242, v75, v237
	v_mul_f32_e32 v243, v77, v239
	v_fmac_f32_e32 v242, v74, v236
	v_fmac_f32_e32 v243, v76, v238
	v_add_f32_e32 v242, v242, v243
	v_add_f32_e32 v67, v242, v71
	v_pk_mul_f32 v[242:243], v[70:71], v[80:81] op_sel_hi:[0,1]
	v_pk_mul_f32 v[58:59], v[70:71], v[78:79] op_sel_hi:[0,1]
	v_pk_fma_f32 v[242:243], v[240:241], v[68:69], v[242:243] op_sel_hi:[1,0,1]
	v_pk_fma_f32 v[240:241], v[52:53], v[68:69], v[58:59] op_sel_hi:[1,0,1]
	s_waitcnt lgkmcnt(0)
	v_mul_f32_e32 v53, v57, v243
	v_mul_f32_e32 v52, v55, v241
	v_fmac_f32_e32 v52, v54, v240
	v_fmac_f32_e32 v53, v56, v242
	v_add_f32_e32 v52, v52, v53
	v_add_f32_e32 v52, v67, v52
	ds_bpermute_b32 v53, v61, v52
	s_waitcnt lgkmcnt(0)
	v_add_f32_e32 v52, v52, v53
	ds_bpermute_b32 v53, v62, v52
	s_waitcnt lgkmcnt(0)
	v_add_f32_e32 v52, v52, v53
	ds_bpermute_b32 v53, v63, v52
	s_and_saveexec_b64 s[14:15], s[6:7]
	s_cbranch_execz .Lssd12_9_tail
	ds_read_b32 v54, v64 offset:50432
	s_waitcnt lgkmcnt(1)
	v_add_f32_e32 v52, v52, v53
	v_fmac_f32_e32 v52, v66, v69
	s_waitcnt lgkmcnt(0)
	v_mul_f32_e32 v55, 0xbfb8aa3b, v54
	v_exp_f32_e32 v55, v55
	s_nop 0
	v_add_f32_e32 v53, 1.0, v55
	v_div_scale_f32 v55, s[2:3], v53, v53, v54
	v_rcp_f32_e32 v56, v55
	v_div_scale_f32 v57, vcc, v54, v53, v54
	v_fma_f32 v58, -v55, v56, 1.0
	v_fmac_f32_e32 v56, v58, v56
	v_mul_f32_e32 v58, v57, v56
	v_fma_f32 v59, -v55, v58, v57
	v_fmac_f32_e32 v58, v59, v56
	v_fma_f32 v55, -v55, v58, v57
	v_div_fmas_f32 v55, v55, v56, v58
	v_div_fixup_f32 v53, v55, v53, v54
	v_mul_f32_e32 v52, v52, v53
	ds_write_b32 v64, v52 offset:38144
	s_branch .Lssd12_9_tail
.Lssd12_9_tail:
	s_or_b64 exec, exec, s[14:15]
	s_add_i32 s0, s0, 1
	s_add_i32 s1, s1, 4
	s_waitcnt lgkmcnt(0)
	v_lshl_add_u64 v[52:53], v[50:51], 0, s[8:9]
	s_add_u32 s8, s8, 0x8000
	s_addc_u32 s9, s9, 0
	v_add_co_u32_e32 v52, vcc, 0x2fb35000, v52
	s_add_u32 s12, s12, 4
	s_nop 0
	v_addc_co_u32_e32 v53, vcc, 0, v53, vcc
	s_addc_u32 s13, s13, 0
	global_store_dwordx4 v[52:53], v[228:231], off
	global_store_dwordx4 v[52:53], v[232:235], off offset:16
	global_store_dwordx4 v[52:53], v[236:239], off offset:32
	global_store_dwordx4 v[52:53], v[240:243], off offset:48
	s_add_u32 s10, s10, 4
	s_addc_u32 s11, s11, 0
	v_add_u32_e32 v64, 0x100, v64
.Lssd12_10:
	s_load_dword s16, s[12:13], 0x0
	s_load_dword s17, s[10:11], 0x0
	s_mul_i32 s2, s0, 0xab
	s_and_b32 s2, s2, 0xfe00
	v_add_u32_e32 v67, s2, v65
	s_waitcnt vmcnt(44)
	s_waitcnt lgkmcnt(0)
	v_mov_b32_e32 v52, s16
	v_mov_b32_e32 v66, s17
	v_mul_f32_e32 v52, 0x3fb8aa3b, v52
	v_exp_f32_e32 v68, v52
	v_mov_b32_e32 v52, s1
	ds_read_b32 v53, v52
	s_waitcnt lgkmcnt(0)
	v_mul_f32_e64 v52, v53, -v68
	v_mul_f32_e32 v52, 0x3fb8aa3b, v52
	v_exp_f32_e32 v58, v52
	ds_read_b32 v52, v64
	ds_read_b128 v[54:57], v67 offset:3072
	ds_read_b128 v[74:77], v67 offset:3088
	ds_read_b128 v[78:81], v67 offset:3104
	ds_read_b128 v[82:85], v67 offset:3120
	v_pk_mul_f32 v[186:187], v[186:187], v[58:59] op_sel_hi:[1,0]
	v_pk_mul_f32 v[86:87], v[184:185], v[58:59] op_sel_hi:[1,0]
	s_waitcnt lgkmcnt(4)
	v_mul_f32_e32 v70, v53, v52
	s_waitcnt lgkmcnt(3)
	v_pk_fma_f32 v[184:185], v[56:57], v[70:71], v[186:187] op_sel_hi:[1,0,1]
	v_pk_fma_f32 v[186:187], v[54:55], v[70:71], v[86:87] op_sel_hi:[1,0,1]
	ds_read_b128 v[54:57], v67 offset:5120
	v_pk_mul_f32 v[150:151], v[150:151], v[58:59] op_sel_hi:[1,0]
	s_waitcnt lgkmcnt(0)
	v_mul_f32_e32 v53, v55, v187
	v_fmac_f32_e32 v53, v54, v186
	v_mul_f32_e32 v54, v57, v185
	v_fmac_f32_e32 v54, v56, v184
	v_add_f32_e32 v53, v53, v54
	v_pk_mul_f32 v[54:55], v[148:149], v[58:59] op_sel_hi:[1,0]
	v_pk_fma_f32 v[148:149], v[70:71], v[76:77], v[150:151] op_sel_hi:[0,1,1]
	v_pk_fma_f32 v[150:151], v[70:71], v[74:75], v[54:55] op_sel_hi:[0,1,1]
	ds_read_b128 v[54:57], v67 offset:5136
	v_add_f32_e32 v53, 0, v53
	s_waitcnt lgkmcnt(0)
	v_mul_f32_e32 v55, v55, v151
	v_fmac_f32_e32 v55, v54, v150
	v_mul_f32_e32 v54, v57, v149
	v_fmac_f32_e32 v54, v56, v148
	v_add_f32_e32 v54, v55, v54
	v_add_f32_e32 v53, v54, v53
	v_pk_mul_f32 v[54:55], v[70:71], v[78:79] op_sel_hi:[0,1]
	v_pk_mul_f32 v[56:57], v[70:71], v[80:81] op_sel_hi:[0,1]
	v_pk_fma_f32 v[146:147], v[146:147], v[58:59], v[56:57] op_sel_hi:[1,0,1]
	v_pk_fma_f32 v[144:145], v[144:145], v[58:59], v[54:55] op_sel_hi:[1,0,1]
	ds_read_b128 v[54:57], v67 offset:5152
	s_waitcnt lgkmcnt(0)
	v_mul_f32_e32 v55, v55, v145
	v_fmac_f32_e32 v55, v54, v144
	v_mul_f32_e32 v54, v57, v147
	v_fmac_f32_e32 v54, v56, v146
	v_add_f32_e32 v54, v55, v54
	v_add_f32_e32 v53, v54, v53
	v_pk_mul_f32 v[54:55], v[70:71], v[82:83] op_sel_hi:[0,1]
	v_pk_mul_f32 v[56:57], v[70:71], v[84:85] op_sel_hi:[0,1]
	v_pk_fma_f32 v[142:143], v[142:143], v[58:59], v[56:57] op_sel_hi:[1,0,1]
	v_pk_fma_f32 v[140:141], v[140:141], v[58:59], v[54:55] op_sel_hi:[1,0,1]
	ds_read_b128 v[54:57], v67 offset:5168
	s_waitcnt lgkmcnt(0)
	v_mul_f32_e32 v55, v55, v141
	v_fmac_f32_e32 v55, v54, v140
	v_mul_f32_e32 v54, v57, v143
	v_fmac_f32_e32 v54, v56, v142
	v_add_f32_e32 v54, v55, v54
	v_add_f32_e32 v53, v53, v54
	ds_bpermute_b32 v54, v61, v53
	s_waitcnt lgkmcnt(0)
	v_add_f32_e32 v53, v53, v54
	ds_bpermute_b32 v54, v62, v53
	s_waitcnt lgkmcnt(0)
	v_add_f32_e32 v53, v53, v54
	ds_bpermute_b32 v54, v63, v53
	s_and_saveexec_b64 s[14:15], s[6:7]
	s_cbranch_execz .Lssd12_10_689
	ds_read_b32 v55, v64 offset:41216
	s_waitcnt lgkmcnt(1)
	v_add_f32_e32 v53, v53, v54
	v_fmac_f32_e32 v53, v66, v52
	s_waitcnt lgkmcnt(0)
	v_mul_f32_e32 v56, 0xbfb8aa3b, v55
	v_exp_f32_e32 v56, v56
	s_nop 0
	v_add_f32_e32 v54, 1.0, v56
	v_div_scale_f32 v56, s[2:3], v54, v54, v55
	v_rcp_f32_e32 v57, v56
	v_div_scale_f32 v52, vcc, v55, v54, v55
	v_fma_f32 v58, -v56, v57, 1.0
	v_fmac_f32_e32 v57, v58, v57
	v_mul_f32_e32 v58, v52, v57
	v_fma_f32 v59, -v56, v58, v52
	v_fmac_f32_e32 v58, v59, v57
	v_fma_f32 v52, -v56, v58, v52
	v_div_fmas_f32 v52, v52, v57, v58
	v_div_fixup_f32 v52, v52, v54, v55
	v_mul_f32_e32 v52, v53, v52
	ds_write_b32 v64, v52 offset:28928
.Lssd12_10_689:
	s_or_b64 exec, exec, s[14:15]
	v_mov_b32_e32 v52, s1
	ds_read_b32 v53, v52 offset:48
	ds_read_b32 v52, v64 offset:7168
	s_waitcnt lgkmcnt(1)
	v_mul_f32_e32 v54, v53, v68
	v_mul_f32_e32 v54, 0xbfb8aa3b, v54
	v_exp_f32_e32 v58, v54
	ds_read_b128 v[54:57], v67 offset:10240
	ds_read_b128 v[74:77], v67 offset:10256
	ds_read_b128 v[78:81], v67 offset:12288
	s_waitcnt lgkmcnt(3)
	v_mul_f32_e32 v70, v53, v52
	ds_read_b128 v[82:85], v67 offset:10272
	ds_read_b128 v[86:89], v67 offset:10288
	v_pk_mul_f32 v[184:185], v[184:185], v[58:59] op_sel_hi:[1,0]
	v_pk_mul_f32 v[186:187], v[186:187], v[58:59] op_sel_hi:[1,0]
	s_waitcnt lgkmcnt(4)
	v_pk_fma_f32 v[184:185], v[56:57], v[70:71], v[184:185] op_sel_hi:[1,0,1]
	v_pk_fma_f32 v[186:187], v[54:55], v[70:71], v[186:187] op_sel_hi:[1,0,1]
	ds_read_b128 v[54:57], v67 offset:12304
	s_waitcnt lgkmcnt(3)
	v_mul_f32_e32 v59, v81, v185
	v_fmac_f32_e32 v59, v80, v184
	v_pk_mul_f32 v[148:149], v[148:149], v[58:59] op_sel_hi:[1,0]
	v_pk_mul_f32 v[150:151], v[150:151], v[58:59] op_sel_hi:[1,0]
	v_pk_fma_f32 v[148:149], v[70:71], v[76:77], v[148:149] op_sel_hi:[0,1,1]
	v_pk_fma_f32 v[150:151], v[70:71], v[74:75], v[150:151] op_sel_hi:[0,1,1]
	s_waitcnt lgkmcnt(2)
	v_pk_mul_f32 v[74:75], v[70:71], v[84:85] op_sel_hi:[0,1]
	v_pk_mul_f32 v[76:77], v[70:71], v[82:83] op_sel_hi:[0,1]
	v_mul_f32_e32 v53, v79, v187
	v_pk_fma_f32 v[146:147], v[146:147], v[58:59], v[74:75] op_sel_hi:[1,0,1]
	v_pk_fma_f32 v[144:145], v[144:145], v[58:59], v[76:77] op_sel_hi:[1,0,1]
	ds_read_b128 v[74:77], v67 offset:12336
	s_waitcnt lgkmcnt(1)
	v_mul_f32_e32 v55, v55, v151
	v_fmac_f32_e32 v53, v78, v186
	v_fmac_f32_e32 v55, v54, v150
	v_mul_f32_e32 v54, v57, v149
	v_add_f32_e32 v53, v53, v59
	v_fmac_f32_e32 v54, v56, v148
	v_add_f32_e32 v53, 0, v53
	v_add_f32_e32 v54, v55, v54
	v_add_f32_e32 v53, v54, v53
	ds_read_b128 v[54:57], v67 offset:12320
	s_waitcnt lgkmcnt(0)
	v_mul_f32_e32 v55, v55, v145
	v_fmac_f32_e32 v55, v54, v144
	v_mul_f32_e32 v54, v57, v147
	v_fmac_f32_e32 v54, v56, v146
	v_add_f32_e32 v54, v55, v54
	v_add_f32_e32 v53, v54, v53
	v_pk_mul_f32 v[54:55], v[70:71], v[88:89] op_sel_hi:[0,1]
	v_pk_mul_f32 v[56:57], v[70:71], v[86:87] op_sel_hi:[0,1]
	v_pk_fma_f32 v[142:143], v[142:143], v[58:59], v[54:55] op_sel_hi:[1,0,1]
	v_pk_fma_f32 v[140:141], v[140:141], v[58:59], v[56:57] op_sel_hi:[1,0,1]
	v_mul_f32_e32 v55, v77, v143
	v_mul_f32_e32 v54, v75, v141
	v_fmac_f32_e32 v54, v74, v140
	v_fmac_f32_e32 v55, v76, v142
	v_add_f32_e32 v54, v54, v55
	v_add_f32_e32 v53, v53, v54
	ds_bpermute_b32 v54, v61, v53
	s_waitcnt lgkmcnt(0)
	v_add_f32_e32 v53, v53, v54
	ds_bpermute_b32 v54, v62, v53
	s_waitcnt lgkmcnt(0)
	v_add_f32_e32 v53, v53, v54
	ds_bpermute_b32 v54, v63, v53
	s_and_saveexec_b64 s[14:15], s[6:7]
	s_cbranch_execz .Lssd12_10_691
	ds_read_b32 v55, v64 offset:44288
	s_waitcnt lgkmcnt(1)
	v_add_f32_e32 v53, v53, v54
	v_fmac_f32_e32 v53, v66, v52
	s_waitcnt lgkmcnt(0)
	v_mul_f32_e32 v56, 0xbfb8aa3b, v55
	v_exp_f32_e32 v56, v56
	s_nop 0
	v_add_f32_e32 v54, 1.0, v56
	v_div_scale_f32 v56, s[2:3], v54, v54, v55
	v_rcp_f32_e32 v57, v56
	v_div_scale_f32 v52, vcc, v55, v54, v55
	v_fma_f32 v58, -v56, v57, 1.0
	v_fmac_f32_e32 v57, v58, v57
	v_mul_f32_e32 v58, v52, v57
	v_fma_f32 v59, -v56, v58, v52
	v_fmac_f32_e32 v58, v59, v57
	v_fma_f32 v52, -v56, v58, v52
	v_div_fmas_f32 v52, v52, v57, v58
	v_div_fixup_f32 v52, v52, v54, v55
	v_mul_f32_e32 v52, v53, v52
	ds_write_b32 v64, v52 offset:32000
.Lssd12_10_691:
	s_or_b64 exec, exec, s[14:15]
	v_mov_b32_e32 v52, s1
	ds_read_b32 v56, v52 offset:96
	ds_read_b32 v69, v64 offset:14336
	s_waitcnt lgkmcnt(1)
	v_mul_f32_e32 v52, v56, v68
	v_mul_f32_e32 v52, 0xbfb8aa3b, v52
	v_exp_f32_e32 v70, v52
	ds_read_b128 v[52:55], v67 offset:17408
	ds_read_b128 v[74:77], v67 offset:17424
	ds_read_b128 v[78:81], v67 offset:19456
	s_waitcnt lgkmcnt(3)
	v_mul_f32_e32 v72, v56, v69
	v_pk_mul_f32 v[56:57], v[184:185], v[70:71] op_sel_hi:[1,0]
	v_pk_mul_f32 v[58:59], v[186:187], v[70:71] op_sel_hi:[1,0]
	s_waitcnt lgkmcnt(2)
	v_pk_fma_f32 v[56:57], v[54:55], v[72:73], v[56:57] op_sel_hi:[1,0,1]
	v_pk_fma_f32 v[58:59], v[52:53], v[72:73], v[58:59] op_sel_hi:[1,0,1]
	s_waitcnt lgkmcnt(0)
	v_mul_f32_e32 v53, v81, v57
	v_mul_f32_e32 v52, v79, v59
	ds_read_b128 v[184:187], v67 offset:17440
	ds_read_b128 v[82:85], v67 offset:17456
	ds_read_b128 v[86:89], v67 offset:19472
	v_fmac_f32_e32 v52, v78, v58
	v_fmac_f32_e32 v53, v80, v56
	v_add_f32_e32 v52, v52, v53
	v_add_f32_e32 v71, 0, v52
	v_pk_mul_f32 v[148:149], v[148:149], v[70:71] op_sel_hi:[1,0]
	v_pk_mul_f32 v[52:53], v[150:151], v[70:71] op_sel_hi:[1,0]
	v_pk_fma_f32 v[150:151], v[72:73], v[76:77], v[148:149] op_sel_hi:[0,1,1]
	v_pk_fma_f32 v[54:55], v[72:73], v[74:75], v[52:53] op_sel_hi:[0,1,1]
	ds_read_b128 v[74:77], v67 offset:19488
	s_waitcnt lgkmcnt(1)
	v_mul_f32_e32 v148, v87, v55
	v_mul_f32_e32 v149, v89, v151
	v_fmac_f32_e32 v148, v86, v54
	v_fmac_f32_e32 v149, v88, v150
	v_add_f32_e32 v148, v148, v149
	v_add_f32_e32 v52, v148, v71
	v_pk_mul_f32 v[148:149], v[72:73], v[186:187] op_sel_hi:[0,1]
	v_pk_mul_f32 v[184:185], v[72:73], v[184:185] op_sel_hi:[0,1]
	v_pk_fma_f32 v[148:149], v[146:147], v[70:71], v[148:149] op_sel_hi:[1,0,1]
	v_pk_fma_f32 v[186:187], v[144:145], v[70:71], v[184:185] op_sel_hi:[1,0,1]
	ds_read_b128 v[144:147], v67 offset:19504
	s_waitcnt lgkmcnt(1)
	v_mul_f32_e32 v184, v75, v187
	v_mul_f32_e32 v185, v77, v149
	v_fmac_f32_e32 v184, v74, v186
	v_fmac_f32_e32 v185, v76, v148
	v_add_f32_e32 v184, v184, v185
	v_add_f32_e32 v71, v184, v52
	v_pk_mul_f32 v[184:185], v[72:73], v[84:85] op_sel_hi:[0,1]
	v_pk_mul_f32 v[52:53], v[72:73], v[82:83] op_sel_hi:[0,1]
	v_pk_fma_f32 v[184:185], v[142:143], v[70:71], v[184:185] op_sel_hi:[1,0,1]
	v_pk_fma_f32 v[52:53], v[140:141], v[70:71], v[52:53] op_sel_hi:[1,0,1]
	s_waitcnt lgkmcnt(0)
	v_mul_f32_e32 v141, v147, v185
	v_mul_f32_e32 v140, v145, v53
	v_fmac_f32_e32 v140, v144, v52
	v_fmac_f32_e32 v141, v146, v184
	v_add_f32_e32 v140, v140, v141
	v_add_f32_e32 v140, v71, v140
	ds_bpermute_b32 v141, v61, v140
	s_waitcnt lgkmcnt(0)
	v_add_f32_e32 v140, v140, v141
	ds_bpermute_b32 v141, v62, v140
	s_waitcnt lgkmcnt(0)
	v_add_f32_e32 v140, v140, v141
	ds_bpermute_b32 v141, v63, v140
	s_and_saveexec_b64 s[14:15], s[6:7]
	s_cbranch_execz .Lssd12_10_693
	ds_read_b32 v142, v64 offset:47360
	s_waitcnt lgkmcnt(1)
	v_add_f32_e32 v140, v140, v141
	v_fmac_f32_e32 v140, v66, v69
	s_waitcnt lgkmcnt(0)
	v_mul_f32_e32 v143, 0xbfb8aa3b, v142
	v_exp_f32_e32 v143, v143
	s_nop 0
	v_add_f32_e32 v141, 1.0, v143
	v_div_scale_f32 v143, s[2:3], v141, v141, v142
	v_rcp_f32_e32 v144, v143
	v_div_scale_f32 v145, vcc, v142, v141, v142
	v_fma_f32 v146, -v143, v144, 1.0
	v_fmac_f32_e32 v144, v146, v144
	v_mul_f32_e32 v146, v145, v144
	v_fma_f32 v147, -v143, v146, v145
	v_fmac_f32_e32 v146, v147, v144
	v_fma_f32 v143, -v143, v146, v145
	v_div_fmas_f32 v143, v143, v144, v146
	v_div_fixup_f32 v141, v143, v141, v142
	v_mul_f32_e32 v140, v140, v141
	ds_write_b32 v64, v140 offset:35072
.Lssd12_10_693:
	s_or_b64 exec, exec, s[14:15]
	v_mov_b32_e32 v140, s1
	ds_read_b32 v70, v140 offset:144
	ds_read_b32 v69, v64 offset:21504
	s_waitcnt lgkmcnt(1)
	v_mul_f32_e32 v140, v70, v68
	v_mul_f32_e32 v140, 0xbfb8aa3b, v140
	v_exp_f32_e32 v68, v140
	ds_read_b128 v[140:143], v67 offset:24576
	ds_read_b128 v[144:147], v67 offset:24592
	ds_read_b128 v[74:77], v67 offset:26624
	s_waitcnt lgkmcnt(3)
	v_mul_f32_e32 v70, v70, v69
	v_pk_mul_f32 v[82:83], v[56:57], v[68:69] op_sel_hi:[1,0]
	v_pk_mul_f32 v[84:85], v[58:59], v[68:69] op_sel_hi:[1,0]
	s_waitcnt lgkmcnt(2)
	v_pk_fma_f32 v[142:143], v[142:143], v[70:71], v[82:83] op_sel_hi:[1,0,1]
	v_pk_fma_f32 v[140:141], v[140:141], v[70:71], v[84:85] op_sel_hi:[1,0,1]
	ds_read_b128 v[56:59], v67 offset:24608
	ds_read_b128 v[78:81], v67 offset:24624
	ds_read_b128 v[82:85], v67 offset:26640
	s_waitcnt lgkmcnt(3)
	v_mul_f32_e32 v71, v75, v141
	v_mul_f32_e32 v72, v77, v143
	v_fmac_f32_e32 v71, v74, v140
	v_fmac_f32_e32 v72, v76, v142
	v_add_f32_e32 v71, v71, v72
	v_add_f32_e32 v71, 0, v71
	v_pk_mul_f32 v[150:151], v[150:151], v[68:69] op_sel_hi:[1,0]
	v_pk_mul_f32 v[54:55], v[54:55], v[68:69] op_sel_hi:[1,0]
	v_pk_fma_f32 v[146:147], v[70:71], v[146:147], v[150:151] op_sel_hi:[0,1,1]
	v_pk_fma_f32 v[144:145], v[70:71], v[144:145], v[54:55] op_sel_hi:[0,1,1]
	ds_read_b128 v[74:77], v67 offset:26656
	s_waitcnt lgkmcnt(1)
	v_mul_f32_e32 v150, v83, v145
	v_mul_f32_e32 v151, v85, v147
	v_fmac_f32_e32 v150, v82, v144
	v_fmac_f32_e32 v151, v84, v146
	v_add_f32_e32 v150, v150, v151
	v_add_f32_e32 v71, v150, v71
	v_pk_mul_f32 v[150:151], v[70:71], v[58:59] op_sel_hi:[0,1]
	v_pk_mul_f32 v[54:55], v[70:71], v[56:57] op_sel_hi:[0,1]
	v_pk_fma_f32 v[150:151], v[148:149], v[68:69], v[150:151] op_sel_hi:[1,0,1]
	v_pk_fma_f32 v[148:149], v[186:187], v[68:69], v[54:55] op_sel_hi:[1,0,1]
	ds_read_b128 v[54:57], v67 offset:26672
	s_waitcnt lgkmcnt(1)
	v_mul_f32_e32 v186, v75, v149
	v_mul_f32_e32 v187, v77, v151
	v_fmac_f32_e32 v186, v74, v148
	v_fmac_f32_e32 v187, v76, v150
	v_add_f32_e32 v186, v186, v187
	v_add_f32_e32 v67, v186, v71
	v_pk_mul_f32 v[186:187], v[70:71], v[80:81] op_sel_hi:[0,1]
	v_pk_mul_f32 v[58:59], v[70:71], v[78:79] op_sel_hi:[0,1]
	v_pk_fma_f32 v[186:187], v[184:185], v[68:69], v[186:187] op_sel_hi:[1,0,1]
	v_pk_fma_f32 v[184:185], v[52:53], v[68:69], v[58:59] op_sel_hi:[1,0,1]
	s_waitcnt lgkmcnt(0)
	v_mul_f32_e32 v53, v57, v187
	v_mul_f32_e32 v52, v55, v185
	v_fmac_f32_e32 v52, v54, v184
	v_fmac_f32_e32 v53, v56, v186
	v_add_f32_e32 v52, v52, v53
	v_add_f32_e32 v52, v67, v52
	ds_bpermute_b32 v53, v61, v52
	s_waitcnt lgkmcnt(0)
	v_add_f32_e32 v52, v52, v53
	ds_bpermute_b32 v53, v62, v52
	s_waitcnt lgkmcnt(0)
	v_add_f32_e32 v52, v52, v53
	ds_bpermute_b32 v53, v63, v52
	s_and_saveexec_b64 s[14:15], s[6:7]
	s_cbranch_execz .Lssd12_10_tail
	ds_read_b32 v54, v64 offset:50432
	s_waitcnt lgkmcnt(1)
	v_add_f32_e32 v52, v52, v53
	v_fmac_f32_e32 v52, v66, v69
	s_waitcnt lgkmcnt(0)
	v_mul_f32_e32 v55, 0xbfb8aa3b, v54
	v_exp_f32_e32 v55, v55
	s_nop 0
	v_add_f32_e32 v53, 1.0, v55
	v_div_scale_f32 v55, s[2:3], v53, v53, v54
	v_rcp_f32_e32 v56, v55
	v_div_scale_f32 v57, vcc, v54, v53, v54
	v_fma_f32 v58, -v55, v56, 1.0
	v_fmac_f32_e32 v56, v58, v56
	v_mul_f32_e32 v58, v57, v56
	v_fma_f32 v59, -v55, v58, v57
	v_fmac_f32_e32 v58, v59, v56
	v_fma_f32 v55, -v55, v58, v57
	v_div_fmas_f32 v55, v55, v56, v58
	v_div_fixup_f32 v53, v55, v53, v54
	v_mul_f32_e32 v52, v52, v53
	ds_write_b32 v64, v52 offset:38144
	s_branch .Lssd12_10_tail
.Lssd12_10_tail:
	s_or_b64 exec, exec, s[14:15]
	s_add_i32 s0, s0, 1
	s_add_i32 s1, s1, 4
	s_waitcnt lgkmcnt(0)
	v_lshl_add_u64 v[52:53], v[50:51], 0, s[8:9]
	s_add_u32 s8, s8, 0x8000
	s_addc_u32 s9, s9, 0
	v_add_co_u32_e32 v52, vcc, 0x2fb35000, v52
	s_add_u32 s12, s12, 4
	s_nop 0
	v_addc_co_u32_e32 v53, vcc, 0, v53, vcc
	s_addc_u32 s13, s13, 0
	global_store_dwordx4 v[52:53], v[140:143], off
	global_store_dwordx4 v[52:53], v[144:147], off offset:16
	global_store_dwordx4 v[52:53], v[148:151], off offset:32
	global_store_dwordx4 v[52:53], v[184:187], off offset:48
	s_add_u32 s10, s10, 4
	s_addc_u32 s11, s11, 0
	v_add_u32_e32 v64, 0x100, v64

.Lssd12_11_tail:
	s_or_b64 exec, exec, s[14:15]
	s_add_i32 s0, s0, 1
	s_add_i32 s1, s1, 4
	s_waitcnt lgkmcnt(0)
	v_lshl_add_u64 v[52:53], v[50:51], 0, s[8:9]
	s_add_u32 s8, s8, 0x8000
	s_addc_u32 s9, s9, 0
	v_add_co_u32_e32 v52, vcc, 0x2fb35000, v52
	s_add_u32 s12, s12, 4
	s_nop 0
	v_addc_co_u32_e32 v53, vcc, 0, v53, vcc
	s_addc_u32 s13, s13, 0
	global_store_dwordx4 v[52:53], v[32:35], off
	global_store_dwordx4 v[52:53], v[36:39], off offset:16
	global_store_dwordx4 v[52:53], v[40:43], off offset:32
	global_store_dwordx4 v[52:53], v[44:47], off offset:48
	s_add_u32 s10, s10, 4
	s_addc_u32 s11, s11, 0
	v_add_u32_e32 v64, 0x100, v64
	s_branch .LBB0_695
